# speedup vs baseline: 1.0312x; 1.0081x over previous
.LBB0_96:
	s_lshl_b32 s10, s0, 8
	s_lshl_b32 s8, s23, 8
	s_cmp_gt_i32 s23, 7
	s_mov_b64 s[4:5], -1
	s_cbranch_scc0 .LBB0_113
	v_mov_b64_e32 v[2:3], s[6:7]
	flat_load_dwordx2 v[132:133], v[2:3] offset:160
	s_load_dwordx2 s[100:101], s[78:79], 0xa0
	s_load_dwordx2 s[100:101], s[78:79], 0xa0
	s_cmp_gt_u32 s23, 15
	s_waitcnt vmcnt(0) lgkmcnt(0)
	v_lshl_add_u64 v[134:135], v[132:133], 0, s[94:95]
	s_cbranch_scc0 .LBB0_105
	v_mov_b32_e32 v17, v204
	s_ashr_i32 s9, s8, 31
	v_lshrrev_b32_e32 v18, 4, v17
	v_xor_b32_e32 v0, v17, v18
	v_lshlrev_b32_e32 v0, 3, v0
	v_readfirstlane_b32 s0, v17
	v_and_b32_e32 v14, 56, v0
	v_lshlrev_b32_e32 v0, 8, v17
	s_ashr_i32 s27, s0, 6
	v_and_b32_e32 v15, 0xfffff800, v0
	v_or_b32_e32 v0, v14, v15
	v_add_u32_e32 v16, 0x20000, v15
	s_lshl_b64 s[4:5], s[8:9], 12
	s_lshl_b32 s1, s27, 10
	v_or_b32_e32 v4, v14, v16
	v_lshl_add_u64 v[6:7], v[134:135], 0, s[4:5]
	s_add_i32 s2, s1, 0x10000
	v_lshlrev_b64 v[20:21], 1, v[0:1]
	v_mov_b32_e32 v5, v1
	s_ashr_i32 s11, s10, 31
	v_lshl_add_u64 v[2:3], v[6:7], 0, v[20:21]
	s_mov_b32 m0, s2
	v_lshlrev_b64 v[22:23], 1, v[4:5]
	s_add_i32 s3, s1, 0x12000
	s_lshl_b64 s[12:13], s[10:11], 12
	s_or_b32 s24, s8, 0x80
	global_load_lds_dwordx4 v[2:3], off
	v_lshl_add_u64 v[4:5], v[6:7], 0, v[22:23]
	s_mov_b32 m0, s3
	v_lshl_add_u64 v[6:7], v[132:133], 0, s[12:13]
	s_ashr_i32 s25, s24, 31
	global_load_lds_dwordx4 v[4:5], off
	v_lshl_add_u64 v[8:9], v[6:7], 0, v[20:21]
	s_mov_b32 m0, s1
	s_add_i32 s9, s1, 0x2000
	s_lshl_b64 s[24:25], s[24:25], 12
	s_or_b32 s28, s10, 0x80
	global_load_lds_dwordx4 v[8:9], off
	v_lshl_add_u64 v[6:7], v[6:7], 0, v[22:23]
	s_mov_b32 m0, s9
	v_lshl_add_u64 v[10:11], v[134:135], 0, s[24:25]
	s_add_i32 s11, s1, 0x14000
	s_ashr_i32 s29, s28, 31
	global_load_lds_dwordx4 v[6:7], off
	v_lshl_add_u64 v[12:13], v[10:11], 0, v[20:21]
	s_mov_b32 m0, s11
	s_add_i32 s24, s1, 0x16000
	s_lshl_b64 s[28:29], s[28:29], 12
	global_load_lds_dwordx4 v[12:13], off
	v_lshl_add_u64 v[10:11], v[10:11], 0, v[22:23]
	s_mov_b32 m0, s24
	v_lshl_add_u64 v[24:25], v[132:133], 0, s[28:29]
	s_add_i32 s25, s1, 0x4000
	global_load_lds_dwordx4 v[10:11], off
	v_lshl_add_u64 v[138:139], v[24:25], 0, v[20:21]
	s_mov_b32 m0, s25
	s_add_i32 s26, s1, 0x6000
	global_load_lds_dwordx4 v[138:139], off
	v_lshl_add_u64 v[136:137], v[24:25], 0, v[22:23]
	s_mov_b32 m0, s26
	s_ashr_i32 s28, s0, 8
	global_load_lds_dwordx4 v[136:137], off
	s_cmp_lg_u32 s28, 1
	s_cbranch_scc1 .LBB0_100
	s_barrier
.LBB0_100:
	s_lshl_b32 s27, s27, 5
	v_and_b32_e32 v0, 15, v17
	s_and_b32 s27, s27, 0x60
	v_lshlrev_b32_e32 v19, 7, v0
	v_or_b32_e32 v0, s27, v0
	s_add_i32 s27, s1, 0x18000
	s_mov_b64 s[34:35], 0x80
	v_lshl_or_b32 v19, s28, 13, v19
	v_lshl_add_u64 v[2:3], v[2:3], 0, s[34:35]
	s_mov_b32 m0, s27
	s_add_i32 s28, s1, 0x1a000
	s_waitcnt vmcnt(4)
	s_barrier
	global_load_lds_dwordx4 v[2:3], off
	v_lshl_add_u64 v[2:3], v[4:5], 0, s[34:35]
	s_mov_b32 m0, s28
	s_add_i32 s29, s1, 0x8000
	global_load_lds_dwordx4 v[2:3], off
	v_lshl_add_u64 v[2:3], v[8:9], 0, s[34:35]
	s_mov_b32 m0, s29
	s_add_i32 s30, s1, 0xa000
	global_load_lds_dwordx4 v[2:3], off
	v_lshl_add_u64 v[2:3], v[6:7], 0, s[34:35]
	s_mov_b32 m0, s30
	s_add_i32 s31, s1, 0x1c000
	global_load_lds_dwordx4 v[2:3], off
	v_lshl_add_u64 v[2:3], v[12:13], 0, s[34:35]
	s_mov_b32 m0, s31
	v_and_b32_e32 v20, 3, v18
	global_load_lds_dwordx4 v[2:3], off
	v_lshl_add_u64 v[2:3], v[10:11], 0, s[34:35]
	s_add_i32 s34, s1, 0x1e000
	s_mov_b32 m0, s34
	v_bfe_u32 v17, v17, 1, 3
	global_load_lds_dwordx4 v[2:3], off
	v_bitop3_b32 v18, v18, v17, 3 bitop3:0x6c
	v_bitop3_b32 v17, v20, v17, 4 bitop3:0x36
	v_lshlrev_b32_e32 v18, 4, v18
	v_lshlrev_b32_e32 v17, 4, v17
	v_lshlrev_b32_e32 v0, 7, v0
	v_or_b32_e32 v150, v18, v19
	v_or_b32_e32 v18, v0, v18
	v_or_b32_e32 v151, v17, v19
	v_or_b32_e32 v17, v0, v17
	v_add_u32_e32 v0, v16, v14
	s_waitcnt vmcnt(6)
	v_lshlrev_b64 v[2:3], 1, v[0:1]
	v_add_u32_e32 v0, v15, v14
	v_lshl_add_u64 v[140:141], s[12:13], 0, v[2:3]
	v_lshlrev_b64 v[4:5], 1, v[0:1]
	v_lshl_add_u64 v[144:145], s[4:5], 0, v[2:3]
	v_mov_b32_e32 v2, 0
	v_lshl_add_u64 v[142:143], s[12:13], 0, v[4:5]
	v_lshl_add_u64 v[146:147], s[4:5], 0, v[4:5]
	s_mov_b32 s5, -2
	v_or_b32_e32 v163, 0x10000, v18
	v_or_b32_e32 v164, 0x10000, v17
	v_add_u32_e32 v165, 0x10800, v18
	v_add_u32_e32 v166, 0x10800, v17
	s_add_i32 s12, s1, 0xc000
	s_add_i32 s4, s1, 0xe000
	v_or_b32_e32 v159, 0x14000, v18
	v_or_b32_e32 v160, 0x14000, v17
	v_add_u32_e32 v161, 0x14800, v18
	v_add_u32_e32 v162, 0x14800, v17
	v_or_b32_e32 v155, 0x18000, v18
	v_or_b32_e32 v156, 0x18000, v17
	v_add_u32_e32 v157, 0x18800, v18
	v_add_u32_e32 v158, 0x18800, v17
	v_or_b32_e32 v0, 0x1c000, v18
	v_or_b32_e32 v152, 0x1c000, v17
	v_add_u32_e32 v153, 0x1c800, v18
	v_add_u32_e32 v154, 0x1c800, v17
	v_mov_b64_e32 v[148:149], v[132:133]
	v_mov_b32_e32 v3, v2
	v_mov_b32_e32 v4, v2
	v_mov_b32_e32 v5, v2
	v_mov_b32_e32 v6, v2
	v_mov_b32_e32 v7, v2
	v_mov_b32_e32 v8, v2
	v_mov_b32_e32 v9, v2
	v_mov_b32_e32 v10, v2
	v_mov_b32_e32 v11, v2
	v_mov_b32_e32 v12, v2
	v_mov_b32_e32 v13, v2
	v_mov_b32_e32 v14, v2
	v_mov_b32_e32 v15, v2
	v_mov_b32_e32 v16, v2
	v_mov_b32_e32 v17, v2
	v_mov_b32_e32 v18, v2
	v_mov_b32_e32 v19, v2
	v_mov_b32_e32 v20, v2
	v_mov_b32_e32 v21, v2
	v_mov_b32_e32 v22, v2
	v_mov_b32_e32 v23, v2
	v_mov_b32_e32 v24, v2
	v_mov_b32_e32 v25, v2
	v_mov_b32_e32 v26, v2
	v_mov_b32_e32 v27, v2
	v_mov_b32_e32 v28, v2
	v_mov_b32_e32 v29, v2
	v_mov_b32_e32 v30, v2
	v_mov_b32_e32 v31, v2
	v_mov_b32_e32 v32, v2
	v_mov_b32_e32 v33, v2
	v_mov_b32_e32 v34, v2
	v_mov_b32_e32 v35, v2
	v_mov_b32_e32 v36, v2
	v_mov_b32_e32 v37, v2
	v_mov_b32_e32 v38, v2
	v_mov_b32_e32 v39, v2
	v_mov_b32_e32 v40, v2
	v_mov_b32_e32 v41, v2
	v_mov_b32_e32 v42, v2
	v_mov_b32_e32 v43, v2
	v_mov_b32_e32 v44, v2
	v_mov_b32_e32 v45, v2
	v_mov_b32_e32 v46, v2
	v_mov_b32_e32 v47, v2
	v_mov_b32_e32 v48, v2
	v_mov_b32_e32 v49, v2
	v_mov_b32_e32 v50, v2
	v_mov_b32_e32 v51, v2
	v_mov_b32_e32 v52, v2
	v_mov_b32_e32 v53, v2
	v_mov_b32_e32 v54, v2
	v_mov_b32_e32 v55, v2
	v_mov_b32_e32 v56, v2
	v_mov_b32_e32 v57, v2
	v_mov_b32_e32 v58, v2
	v_mov_b32_e32 v59, v2
	v_mov_b32_e32 v60, v2
	v_mov_b32_e32 v61, v2
	v_mov_b32_e32 v62, v2
	v_mov_b32_e32 v63, v2
	v_mov_b32_e32 v64, v2
	v_mov_b32_e32 v65, v2
	v_mov_b32_e32 v66, v2
	v_mov_b32_e32 v67, v2
	v_mov_b32_e32 v68, v2
	v_mov_b32_e32 v69, v2
	v_mov_b32_e32 v70, v2
	v_mov_b32_e32 v71, v2
	v_mov_b32_e32 v72, v2
	v_mov_b32_e32 v73, v2
	v_mov_b32_e32 v74, v2
	v_mov_b32_e32 v75, v2
	v_mov_b32_e32 v76, v2
	v_mov_b32_e32 v77, v2
	v_mov_b32_e32 v78, v2
	v_mov_b32_e32 v79, v2
	v_mov_b32_e32 v80, v2
	v_mov_b32_e32 v81, v2
	v_mov_b32_e32 v82, v2
	v_mov_b32_e32 v83, v2
	v_mov_b32_e32 v84, v2
	v_mov_b32_e32 v85, v2
	v_mov_b32_e32 v86, v2
	v_mov_b32_e32 v87, v2
	v_mov_b32_e32 v88, v2
	v_mov_b32_e32 v89, v2
	v_mov_b32_e32 v90, v2
	v_mov_b32_e32 v91, v2
	v_mov_b32_e32 v92, v2
	v_mov_b32_e32 v93, v2
	v_mov_b32_e32 v94, v2
	v_mov_b32_e32 v95, v2
	v_mov_b32_e32 v96, v2
	v_mov_b32_e32 v97, v2
	v_mov_b32_e32 v98, v2
	v_mov_b32_e32 v99, v2
	v_mov_b32_e32 v100, v2
	v_mov_b32_e32 v101, v2
	v_mov_b32_e32 v102, v2
	v_mov_b32_e32 v103, v2
	v_mov_b32_e32 v104, v2
	v_mov_b32_e32 v105, v2
	v_mov_b32_e32 v106, v2
	v_mov_b32_e32 v107, v2
	v_mov_b32_e32 v108, v2
	v_mov_b32_e32 v109, v2
	v_mov_b32_e32 v110, v2
	v_mov_b32_e32 v111, v2
	v_mov_b32_e32 v112, v2
	v_mov_b32_e32 v113, v2
	v_mov_b32_e32 v114, v2
	v_mov_b32_e32 v115, v2
	v_mov_b32_e32 v116, v2
	v_mov_b32_e32 v117, v2
	v_mov_b32_e32 v118, v2
	v_mov_b32_e32 v119, v2
	v_mov_b32_e32 v120, v2
	v_mov_b32_e32 v121, v2
	v_mov_b32_e32 v122, v2
	v_mov_b32_e32 v123, v2
	v_mov_b32_e32 v124, v2
	v_mov_b32_e32 v125, v2
	v_mov_b32_e32 v126, v2
	v_mov_b32_e32 v127, v2
	v_mov_b32_e32 v128, v2
	v_mov_b32_e32 v129, v2
	s_mov_b64 s[36:37], 0x82d4900
	s_mov_b64 s[38:39], 0x8254980
	s_mov_b64 s[40:41], 0x82d4980
	s_waitcnt lgkmcnt(0)
	s_sub_u32 s100, s100, 0x40000000
	s_subb_u32 s101, s101, 0
	s_mov_b64 vcc, s[100:101]
	v_lshl_add_u64 v[210:211], v[148:149], 0, v[142:143]
	v_subrev_u32_e32 v210, vcc_lo, v210
	v_lshl_add_u64 v[214:215], v[148:149], 0, v[140:141]
	v_subrev_u32_e32 v214, vcc_lo, v214
	v_lshl_add_u64 v[242:243], v[148:149], 0, v[146:147]
	v_subrev_u32_e32 v242, vcc_lo, v242
	v_lshl_add_u64 v[244:245], v[148:149], 0, v[144:145]
	v_subrev_u32_e32 v244, vcc_lo, v244
	s_barrier
.LBB0_101:
	ds_read_b128 v[168:171], v163
	ds_read_b128 v[172:175], v164
	ds_read_b128 v[176:179], v165
	ds_read_b128 v[180:183], v166
	s_mov_b32 m0, s12
	ds_read_b128 v[184:187], v150
	ds_read_b128 v[188:191], v150 offset:2048
	ds_read_b128 v[192:195], v151
	ds_read_b128 v[196:199], v151 offset:2048
	ds_read_b128 v[200:203], v150 offset:4096
	ds_read_b128 v[206:209], v150 offset:6144
	ds_read_b128 v[218:221], v151 offset:4096
	ds_read_b128 v[222:225], v151 offset:6144
	s_add_u32 s100, vcc_lo, s50
	s_addc_u32 s101, vcc_hi, s51
	global_load_lds_dwordx4 v210, s[100:101]
	s_mov_b32 m0, s4
	s_add_u32 s100, vcc_lo, s50
	s_addc_u32 s101, vcc_hi, s51
	global_load_lds_dwordx4 v214, s[100:101]
	s_waitcnt lgkmcnt(8)
	s_waitcnt vmcnt(10)
	s_barrier
	s_waitcnt lgkmcnt(0)
	s_setprio 1
	s_waitcnt lgkmcnt(0)
	v_mfma_f32_16x16x32_bf16 v[126:129], v[184:187], v[168:171], v[126:129]
	v_mfma_f32_16x16x32_bf16 v[122:125], v[184:187], v[176:179], v[122:125]
	v_mfma_f32_16x16x32_bf16 v[118:121], v[188:191], v[168:171], v[118:121]
	v_mfma_f32_16x16x32_bf16 v[114:117], v[188:191], v[176:179], v[114:117]
	v_mfma_f32_16x16x32_bf16 v[110:113], v[200:203], v[168:171], v[110:113]
	v_mfma_f32_16x16x32_bf16 v[106:109], v[200:203], v[176:179], v[106:109]
	v_mfma_f32_16x16x32_bf16 v[102:105], v[206:209], v[168:171], v[102:105]
	v_mfma_f32_16x16x32_bf16 v[98:101], v[206:209], v[176:179], v[98:101]
	v_mfma_f32_16x16x32_bf16 v[126:129], v[192:195], v[172:175], v[126:129]
	v_mfma_f32_16x16x32_bf16 v[122:125], v[192:195], v[180:183], v[122:125]
	v_mfma_f32_16x16x32_bf16 v[118:121], v[196:199], v[172:175], v[118:121]
	v_mfma_f32_16x16x32_bf16 v[114:117], v[196:199], v[180:183], v[114:117]
	v_mfma_f32_16x16x32_bf16 v[110:113], v[218:221], v[172:175], v[110:113]
	v_mfma_f32_16x16x32_bf16 v[106:109], v[218:221], v[180:183], v[106:109]
	v_mfma_f32_16x16x32_bf16 v[102:105], v[222:225], v[172:175], v[102:105]
	v_mfma_f32_16x16x32_bf16 v[98:101], v[222:225], v[180:183], v[98:101]
	s_setprio 0
	s_barrier
	s_mov_b32 m0, s2
	ds_read_b128 v[226:229], v159
	ds_read_b128 v[230:233], v160
	ds_read_b128 v[234:237], v161
	ds_read_b128 v[238:241], v162
	s_add_u32 s100, vcc_lo, s70
	s_addc_u32 s101, vcc_hi, s71
	global_load_lds_dwordx4 v242, s[100:101]
	s_mov_b32 m0, s3
	s_add_u32 s100, vcc_lo, s70
	s_addc_u32 s101, vcc_hi, s71
	global_load_lds_dwordx4 v244, s[100:101]
	s_waitcnt vmcnt(10)
	s_waitcnt lgkmcnt(0)
	s_barrier
	s_waitcnt lgkmcnt(0)
	s_setprio 1
	s_waitcnt lgkmcnt(0)
	v_mfma_f32_16x16x32_bf16 v[94:97], v[184:187], v[226:229], v[94:97]
	v_mfma_f32_16x16x32_bf16 v[90:93], v[184:187], v[234:237], v[90:93]
	v_mfma_f32_16x16x32_bf16 v[86:89], v[188:191], v[226:229], v[86:89]
	v_mfma_f32_16x16x32_bf16 v[82:85], v[188:191], v[234:237], v[82:85]
	v_mfma_f32_16x16x32_bf16 v[78:81], v[200:203], v[226:229], v[78:81]
	v_mfma_f32_16x16x32_bf16 v[74:77], v[200:203], v[234:237], v[74:77]
	v_mfma_f32_16x16x32_bf16 v[70:73], v[206:209], v[226:229], v[70:73]
	v_mfma_f32_16x16x32_bf16 v[66:69], v[206:209], v[234:237], v[66:69]
	v_mfma_f32_16x16x32_bf16 v[94:97], v[192:195], v[230:233], v[94:97]
	v_mfma_f32_16x16x32_bf16 v[90:93], v[192:195], v[238:241], v[90:93]
	v_mfma_f32_16x16x32_bf16 v[86:89], v[196:199], v[230:233], v[86:89]
	v_mfma_f32_16x16x32_bf16 v[82:85], v[196:199], v[238:241], v[82:85]
	v_mfma_f32_16x16x32_bf16 v[78:81], v[218:221], v[230:233], v[78:81]
	v_mfma_f32_16x16x32_bf16 v[74:77], v[218:221], v[238:241], v[74:77]
	v_mfma_f32_16x16x32_bf16 v[70:73], v[222:225], v[230:233], v[70:73]
	v_mfma_f32_16x16x32_bf16 v[66:69], v[222:225], v[238:241], v[66:69]
	s_setprio 0
	s_mov_b32 m0, s1
	s_barrier
	ds_read_b128 v[184:187], v150 offset:16384
	ds_read_b128 v[188:191], v150 offset:18432
	ds_read_b128 v[192:195], v151 offset:16384
	ds_read_b128 v[196:199], v151 offset:18432
	ds_read_b128 v[200:203], v150 offset:20480
	ds_read_b128 v[206:209], v150 offset:22528
	ds_read_b128 v[218:221], v151 offset:20480
	ds_read_b128 v[222:225], v151 offset:22528
	s_add_u32 s100, vcc_lo, s54
	s_addc_u32 s101, vcc_hi, s55
	global_load_lds_dwordx4 v210, s[100:101]
	s_mov_b32 m0, s9
	s_add_u32 s100, vcc_lo, s54
	s_addc_u32 s101, vcc_hi, s55
	global_load_lds_dwordx4 v214, s[100:101]
	s_mov_b32 m0, s11
	s_add_u32 s100, vcc_lo, s36
	s_addc_u32 s101, vcc_hi, s37
	global_load_lds_dwordx4 v242, s[100:101]
	s_mov_b32 m0, s24
	s_add_u32 s100, vcc_lo, s36
	s_addc_u32 s101, vcc_hi, s37
	global_load_lds_dwordx4 v244, s[100:101]
	s_waitcnt vmcnt(10)
	s_waitcnt lgkmcnt(0)
	s_barrier
	s_waitcnt lgkmcnt(0)
	s_setprio 1
	s_waitcnt lgkmcnt(0)
	v_mfma_f32_16x16x32_bf16 v[62:65], v[184:187], v[168:171], v[62:65]
	v_mfma_f32_16x16x32_bf16 v[58:61], v[184:187], v[176:179], v[58:61]
	v_mfma_f32_16x16x32_bf16 v[54:57], v[188:191], v[168:171], v[54:57]
	v_mfma_f32_16x16x32_bf16 v[50:53], v[188:191], v[176:179], v[50:53]
	v_mfma_f32_16x16x32_bf16 v[46:49], v[200:203], v[168:171], v[46:49]
	v_mfma_f32_16x16x32_bf16 v[42:45], v[200:203], v[176:179], v[42:45]
	v_mfma_f32_16x16x32_bf16 v[38:41], v[206:209], v[168:171], v[38:41]
	v_mfma_f32_16x16x32_bf16 v[34:37], v[206:209], v[176:179], v[34:37]
	v_mfma_f32_16x16x32_bf16 v[62:65], v[192:195], v[172:175], v[62:65]
	v_mfma_f32_16x16x32_bf16 v[58:61], v[192:195], v[180:183], v[58:61]
	v_mfma_f32_16x16x32_bf16 v[54:57], v[196:199], v[172:175], v[54:57]
	v_mfma_f32_16x16x32_bf16 v[50:53], v[196:199], v[180:183], v[50:53]
	v_mfma_f32_16x16x32_bf16 v[46:49], v[218:221], v[172:175], v[46:49]
	v_mfma_f32_16x16x32_bf16 v[42:45], v[218:221], v[180:183], v[42:45]
	v_mfma_f32_16x16x32_bf16 v[38:41], v[222:225], v[172:175], v[38:41]
	v_mfma_f32_16x16x32_bf16 v[34:37], v[222:225], v[180:183], v[34:37]
	v_mfma_f32_16x16x32_bf16 v[30:33], v[184:187], v[226:229], v[30:33]
	v_mfma_f32_16x16x32_bf16 v[26:29], v[184:187], v[234:237], v[26:29]
	v_mfma_f32_16x16x32_bf16 v[22:25], v[188:191], v[226:229], v[22:25]
	v_mfma_f32_16x16x32_bf16 v[18:21], v[188:191], v[234:237], v[18:21]
	v_mfma_f32_16x16x32_bf16 v[14:17], v[200:203], v[226:229], v[14:17]
	v_mfma_f32_16x16x32_bf16 v[10:13], v[200:203], v[234:237], v[10:13]
	v_mfma_f32_16x16x32_bf16 v[6:9], v[206:209], v[226:229], v[6:9]
	v_mfma_f32_16x16x32_bf16 v[2:5], v[206:209], v[234:237], v[2:5]
	v_mfma_f32_16x16x32_bf16 v[30:33], v[192:195], v[230:233], v[30:33]
	v_mfma_f32_16x16x32_bf16 v[26:29], v[192:195], v[238:241], v[26:29]
	v_mfma_f32_16x16x32_bf16 v[22:25], v[196:199], v[230:233], v[22:25]
	v_mfma_f32_16x16x32_bf16 v[18:21], v[196:199], v[238:241], v[18:21]
	v_mfma_f32_16x16x32_bf16 v[14:17], v[218:221], v[230:233], v[14:17]
	v_mfma_f32_16x16x32_bf16 v[10:13], v[218:221], v[238:241], v[10:13]
	v_mfma_f32_16x16x32_bf16 v[6:9], v[222:225], v[230:233], v[6:9]
	v_mfma_f32_16x16x32_bf16 v[2:5], v[222:225], v[238:241], v[2:5]
	s_setprio 0
	s_barrier
	ds_read_b128 v[168:171], v155
	ds_read_b128 v[172:175], v156
	ds_read_b128 v[176:179], v157
	ds_read_b128 v[180:183], v158
	s_mov_b32 m0, s25
	ds_read_b128 v[184:187], v150 offset:32768
	ds_read_b128 v[188:191], v150 offset:34816
	ds_read_b128 v[192:195], v151 offset:32768
	ds_read_b128 v[196:199], v151 offset:34816
	ds_read_b128 v[200:203], v150 offset:36864
	ds_read_b128 v[206:209], v150 offset:38912
	ds_read_b128 v[218:221], v151 offset:36864
	ds_read_b128 v[222:225], v151 offset:38912
	s_add_u32 s100, vcc_lo, s58
	s_addc_u32 s101, vcc_hi, s59
	global_load_lds_dwordx4 v210, s[100:101]
	s_mov_b32 m0, s26
	s_add_u32 s100, vcc_lo, s58
	s_addc_u32 s101, vcc_hi, s59
	global_load_lds_dwordx4 v214, s[100:101]
	s_waitcnt lgkmcnt(8)
	s_waitcnt vmcnt(10)
	s_barrier
	s_waitcnt lgkmcnt(0)
	s_setprio 1
	s_waitcnt lgkmcnt(0)
	v_mfma_f32_16x16x32_bf16 v[126:129], v[184:187], v[168:171], v[126:129]
	v_mfma_f32_16x16x32_bf16 v[122:125], v[184:187], v[176:179], v[122:125]
	v_mfma_f32_16x16x32_bf16 v[118:121], v[188:191], v[168:171], v[118:121]
	v_mfma_f32_16x16x32_bf16 v[114:117], v[188:191], v[176:179], v[114:117]
	v_mfma_f32_16x16x32_bf16 v[110:113], v[200:203], v[168:171], v[110:113]
	v_mfma_f32_16x16x32_bf16 v[106:109], v[200:203], v[176:179], v[106:109]
	v_mfma_f32_16x16x32_bf16 v[102:105], v[206:209], v[168:171], v[102:105]
	v_mfma_f32_16x16x32_bf16 v[98:101], v[206:209], v[176:179], v[98:101]
	v_mfma_f32_16x16x32_bf16 v[126:129], v[192:195], v[172:175], v[126:129]
	v_mfma_f32_16x16x32_bf16 v[122:125], v[192:195], v[180:183], v[122:125]
	v_mfma_f32_16x16x32_bf16 v[118:121], v[196:199], v[172:175], v[118:121]
	v_mfma_f32_16x16x32_bf16 v[114:117], v[196:199], v[180:183], v[114:117]
	v_mfma_f32_16x16x32_bf16 v[110:113], v[218:221], v[172:175], v[110:113]
	v_mfma_f32_16x16x32_bf16 v[106:109], v[218:221], v[180:183], v[106:109]
	v_mfma_f32_16x16x32_bf16 v[102:105], v[222:225], v[172:175], v[102:105]
	v_mfma_f32_16x16x32_bf16 v[98:101], v[222:225], v[180:183], v[98:101]
	s_setprio 0
	s_barrier
	s_mov_b32 m0, s27
	ds_read_b128 v[226:229], v0
	ds_read_b128 v[230:233], v152
	ds_read_b128 v[234:237], v153
	ds_read_b128 v[238:241], v154
	s_add_u32 s100, vcc_lo, s38
	s_addc_u32 s101, vcc_hi, s39
	global_load_lds_dwordx4 v242, s[100:101]
	s_mov_b32 m0, s28
	s_add_u32 s100, vcc_lo, s38
	s_addc_u32 s101, vcc_hi, s39
	global_load_lds_dwordx4 v244, s[100:101]
	s_waitcnt vmcnt(10)
	s_waitcnt lgkmcnt(0)
	s_barrier
	s_waitcnt lgkmcnt(0)
	s_setprio 1
	s_waitcnt lgkmcnt(0)
	v_mfma_f32_16x16x32_bf16 v[94:97], v[184:187], v[226:229], v[94:97]
	v_mfma_f32_16x16x32_bf16 v[90:93], v[184:187], v[234:237], v[90:93]
	v_mfma_f32_16x16x32_bf16 v[86:89], v[188:191], v[226:229], v[86:89]
	v_mfma_f32_16x16x32_bf16 v[82:85], v[188:191], v[234:237], v[82:85]
	v_mfma_f32_16x16x32_bf16 v[78:81], v[200:203], v[226:229], v[78:81]
	v_mfma_f32_16x16x32_bf16 v[74:77], v[200:203], v[234:237], v[74:77]
	v_mfma_f32_16x16x32_bf16 v[70:73], v[206:209], v[226:229], v[70:73]
	v_mfma_f32_16x16x32_bf16 v[66:69], v[206:209], v[234:237], v[66:69]
	v_mfma_f32_16x16x32_bf16 v[94:97], v[192:195], v[230:233], v[94:97]
	v_mfma_f32_16x16x32_bf16 v[90:93], v[192:195], v[238:241], v[90:93]
	v_mfma_f32_16x16x32_bf16 v[86:89], v[196:199], v[230:233], v[86:89]
	v_mfma_f32_16x16x32_bf16 v[82:85], v[196:199], v[238:241], v[82:85]
	v_mfma_f32_16x16x32_bf16 v[78:81], v[218:221], v[230:233], v[78:81]
	v_mfma_f32_16x16x32_bf16 v[74:77], v[218:221], v[238:241], v[74:77]
	v_mfma_f32_16x16x32_bf16 v[70:73], v[222:225], v[230:233], v[70:73]
	v_mfma_f32_16x16x32_bf16 v[66:69], v[222:225], v[238:241], v[66:69]
	s_setprio 0
	s_mov_b32 m0, s29
	s_barrier
	ds_read_b128 v[184:187], v150 offset:49152
	ds_read_b128 v[188:191], v150 offset:51200
	ds_read_b128 v[192:195], v151 offset:49152
	ds_read_b128 v[196:199], v151 offset:51200
	ds_read_b128 v[200:203], v150 offset:53248
	ds_read_b128 v[206:209], v150 offset:55296
	ds_read_b128 v[218:221], v151 offset:53248
	ds_read_b128 v[222:225], v151 offset:55296
	s_add_u32 s100, vcc_lo, s62
	s_addc_u32 s101, vcc_hi, s63
	global_load_lds_dwordx4 v210, s[100:101]
	s_mov_b32 m0, s30
	s_add_u32 s100, vcc_lo, s62
	s_addc_u32 s101, vcc_hi, s63
	global_load_lds_dwordx4 v214, s[100:101]
	s_mov_b32 m0, s31
	s_add_u32 s100, vcc_lo, s40
	s_addc_u32 s101, vcc_hi, s41
	global_load_lds_dwordx4 v242, s[100:101]
	s_mov_b32 m0, s34
	s_add_u32 s100, vcc_lo, s40
	s_addc_u32 s101, vcc_hi, s41
	global_load_lds_dwordx4 v244, s[100:101]
	s_waitcnt vmcnt(10)
	s_waitcnt lgkmcnt(0)
	s_barrier
	s_waitcnt lgkmcnt(0)
	s_setprio 1
	s_waitcnt lgkmcnt(0)
	v_mfma_f32_16x16x32_bf16 v[62:65], v[184:187], v[168:171], v[62:65]
	v_mfma_f32_16x16x32_bf16 v[58:61], v[184:187], v[176:179], v[58:61]
	v_mfma_f32_16x16x32_bf16 v[54:57], v[188:191], v[168:171], v[54:57]
	v_mfma_f32_16x16x32_bf16 v[50:53], v[188:191], v[176:179], v[50:53]
	v_mfma_f32_16x16x32_bf16 v[46:49], v[200:203], v[168:171], v[46:49]
	v_mfma_f32_16x16x32_bf16 v[42:45], v[200:203], v[176:179], v[42:45]
	v_mfma_f32_16x16x32_bf16 v[38:41], v[206:209], v[168:171], v[38:41]
	v_mfma_f32_16x16x32_bf16 v[34:37], v[206:209], v[176:179], v[34:37]
	v_mfma_f32_16x16x32_bf16 v[62:65], v[192:195], v[172:175], v[62:65]
	v_mfma_f32_16x16x32_bf16 v[58:61], v[192:195], v[180:183], v[58:61]
	v_mfma_f32_16x16x32_bf16 v[54:57], v[196:199], v[172:175], v[54:57]
	v_mfma_f32_16x16x32_bf16 v[50:53], v[196:199], v[180:183], v[50:53]
	v_mfma_f32_16x16x32_bf16 v[46:49], v[218:221], v[172:175], v[46:49]
	v_mfma_f32_16x16x32_bf16 v[42:45], v[218:221], v[180:183], v[42:45]
	v_mfma_f32_16x16x32_bf16 v[38:41], v[222:225], v[172:175], v[38:41]
	v_mfma_f32_16x16x32_bf16 v[34:37], v[222:225], v[180:183], v[34:37]
	v_mfma_f32_16x16x32_bf16 v[30:33], v[184:187], v[226:229], v[30:33]
	v_mfma_f32_16x16x32_bf16 v[26:29], v[184:187], v[234:237], v[26:29]
	v_mfma_f32_16x16x32_bf16 v[22:25], v[188:191], v[226:229], v[22:25]
	v_mfma_f32_16x16x32_bf16 v[18:21], v[188:191], v[234:237], v[18:21]
	v_mfma_f32_16x16x32_bf16 v[14:17], v[200:203], v[226:229], v[14:17]
	v_mfma_f32_16x16x32_bf16 v[10:13], v[200:203], v[234:237], v[10:13]
	v_mfma_f32_16x16x32_bf16 v[6:9], v[206:209], v[226:229], v[6:9]
	v_mfma_f32_16x16x32_bf16 v[2:5], v[206:209], v[234:237], v[2:5]
	v_mfma_f32_16x16x32_bf16 v[30:33], v[192:195], v[230:233], v[30:33]
	v_mfma_f32_16x16x32_bf16 v[26:29], v[192:195], v[238:241], v[26:29]
	v_mfma_f32_16x16x32_bf16 v[22:25], v[196:199], v[230:233], v[22:25]
	v_mfma_f32_16x16x32_bf16 v[18:21], v[196:199], v[238:241], v[18:21]
	v_mfma_f32_16x16x32_bf16 v[14:17], v[218:221], v[230:233], v[14:17]
	v_mfma_f32_16x16x32_bf16 v[10:13], v[218:221], v[238:241], v[10:13]
	v_mfma_f32_16x16x32_bf16 v[6:9], v[222:225], v[230:233], v[6:9]
	v_mfma_f32_16x16x32_bf16 v[2:5], v[222:225], v[238:241], v[2:5]
	s_setprio 0
	s_add_u32 vcc_lo, vcc_lo, s54
	s_addc_u32 vcc_hi, vcc_hi, s55
	s_add_i32 s5, s5, 2
	s_cmp_lt_u32 s5, 28
	v_lshl_add_u64 v[148:149], v[148:149], 0, s[54:55]
	s_barrier
	s_cbranch_scc1 .LBB0_101
	s_waitcnt vmcnt(6)
	s_mov_b64 s[2:3], 0xf80
	s_mov_b32 m0, s12
	v_lshl_add_u64 v[138:139], v[138:139], 0, s[2:3]
	ds_read_b128 v[140:143], v163
	ds_read_b128 v[144:147], v164
	ds_read_b128 v[168:171], v165
	ds_read_b128 v[164:167], v166
	ds_read_b128 v[172:175], v150
	ds_read_b128 v[176:179], v150 offset:2048
	ds_read_b128 v[180:183], v151
	ds_read_b128 v[184:187], v151 offset:2048
	ds_read_b128 v[188:191], v150 offset:4096
	ds_read_b128 v[192:195], v150 offset:6144
	ds_read_b128 v[196:199], v151 offset:4096
	ds_read_b128 v[200:203], v151 offset:6144
	global_load_lds_dwordx4 v[138:139], off
	v_lshl_add_u64 v[136:137], v[136:137], 0, s[2:3]
	s_mov_b32 m0, s4
	s_nop 0
	global_load_lds_dwordx4 v[136:137], off
	s_barrier
	s_waitcnt lgkmcnt(0)
	s_setprio 1
	s_waitcnt lgkmcnt(0)
	v_mfma_f32_16x16x32_bf16 v[126:129], v[172:175], v[140:143], v[126:129]
	v_mfma_f32_16x16x32_bf16 v[114:117], v[176:179], v[168:171], v[114:117]
	v_mfma_f32_16x16x32_bf16 v[110:113], v[188:191], v[140:143], v[110:113]
	v_mfma_f32_16x16x32_bf16 v[106:109], v[188:191], v[168:171], v[106:109]
	v_mfma_f32_16x16x32_bf16 v[126:129], v[180:183], v[144:147], v[126:129]
	v_mfma_f32_16x16x32_bf16 v[122:125], v[172:175], v[168:171], v[122:125]
	v_mfma_f32_16x16x32_bf16 v[118:121], v[176:179], v[140:143], v[118:121]
	v_mfma_f32_16x16x32_bf16 v[114:117], v[184:187], v[164:167], v[114:117]
	v_mfma_f32_16x16x32_bf16 v[110:113], v[196:199], v[144:147], v[110:113]
	v_mfma_f32_16x16x32_bf16 v[106:109], v[196:199], v[164:167], v[106:109]
	v_mfma_f32_16x16x32_bf16 v[102:105], v[192:195], v[140:143], v[102:105]
	v_mfma_f32_16x16x32_bf16 v[98:101], v[192:195], v[168:171], v[98:101]
	v_mfma_f32_16x16x32_bf16 v[136:139], v[180:183], v[164:167], v[122:125]
	v_mfma_f32_16x16x32_bf16 v[206:209], v[184:187], v[144:147], v[118:121]
	v_mfma_f32_16x16x32_bf16 v[218:221], v[200:203], v[144:147], v[102:105]
	v_mfma_f32_16x16x32_bf16 v[222:225], v[200:203], v[164:167], v[98:101]
	s_setprio 0
	s_barrier
	s_nop 1
	ds_read_b128 v[98:101], v159
	ds_read_b128 v[102:105], v160
	ds_read_b128 v[118:121], v161
	ds_read_b128 v[122:125], v162
	s_barrier
	s_waitcnt lgkmcnt(0)
	s_setprio 1
	s_waitcnt lgkmcnt(0)
	v_mfma_f32_16x16x32_bf16 v[94:97], v[172:175], v[98:101], v[94:97]
	v_mfma_f32_16x16x32_bf16 v[90:93], v[172:175], v[118:121], v[90:93]
	v_mfma_f32_16x16x32_bf16 v[78:81], v[188:191], v[98:101], v[78:81]
	v_mfma_f32_16x16x32_bf16 v[74:77], v[188:191], v[118:121], v[74:77]
	v_mfma_f32_16x16x32_bf16 v[94:97], v[180:183], v[102:105], v[94:97]
	v_mfma_f32_16x16x32_bf16 v[90:93], v[180:183], v[122:125], v[90:93]
	v_mfma_f32_16x16x32_bf16 v[86:89], v[176:179], v[98:101], v[86:89]
	v_mfma_f32_16x16x32_bf16 v[82:85], v[176:179], v[118:121], v[82:85]
	v_mfma_f32_16x16x32_bf16 v[78:81], v[196:199], v[102:105], v[78:81]
	v_mfma_f32_16x16x32_bf16 v[74:77], v[196:199], v[122:125], v[74:77]
	v_mfma_f32_16x16x32_bf16 v[70:73], v[192:195], v[98:101], v[70:73]
	v_mfma_f32_16x16x32_bf16 v[66:69], v[192:195], v[118:121], v[66:69]
	v_mfma_f32_16x16x32_bf16 v[160:163], v[184:187], v[102:105], v[86:89]
	v_mfma_f32_16x16x32_bf16 v[172:175], v[184:187], v[122:125], v[82:85]
	v_mfma_f32_16x16x32_bf16 v[176:179], v[200:203], v[102:105], v[70:73]
	v_mfma_f32_16x16x32_bf16 v[180:183], v[200:203], v[122:125], v[66:69]
	s_setprio 0
	s_barrier
	s_nop 1
	ds_read_b128 v[66:69], v150 offset:16384
	ds_read_b128 v[70:73], v150 offset:18432
	ds_read_b128 v[82:85], v151 offset:16384
	ds_read_b128 v[86:89], v151 offset:18432
	ds_read_b128 v[184:187], v150 offset:20480
	ds_read_b128 v[188:191], v150 offset:22528
	ds_read_b128 v[192:195], v151 offset:20480
	ds_read_b128 v[196:199], v151 offset:22528
	s_waitcnt vmcnt(4)
	s_barrier
	s_waitcnt lgkmcnt(0)
	s_setprio 1
	s_waitcnt lgkmcnt(0)
	v_mfma_f32_16x16x32_bf16 v[62:65], v[66:69], v[140:143], v[62:65]
	v_mfma_f32_16x16x32_bf16 v[54:57], v[70:73], v[140:143], v[54:57]
	v_mfma_f32_16x16x32_bf16 v[46:49], v[184:187], v[140:143], v[46:49]
	v_mfma_f32_16x16x32_bf16 v[38:41], v[188:191], v[140:143], v[38:41]
	v_mfma_f32_16x16x32_bf16 v[62:65], v[82:85], v[144:147], v[62:65]
	v_mfma_f32_16x16x32_bf16 v[58:61], v[66:69], v[168:171], v[58:61]
	v_mfma_f32_16x16x32_bf16 v[54:57], v[86:89], v[144:147], v[54:57]
	v_mfma_f32_16x16x32_bf16 v[50:53], v[70:73], v[168:171], v[50:53]
	v_mfma_f32_16x16x32_bf16 v[46:49], v[192:195], v[144:147], v[46:49]
	v_mfma_f32_16x16x32_bf16 v[42:45], v[184:187], v[168:171], v[42:45]
	v_mfma_f32_16x16x32_bf16 v[38:41], v[196:199], v[144:147], v[38:41]
	v_mfma_f32_16x16x32_bf16 v[34:37], v[188:191], v[168:171], v[34:37]
	v_mfma_f32_16x16x32_bf16 v[200:203], v[82:85], v[164:167], v[58:61]
	v_mfma_f32_16x16x32_bf16 v[226:229], v[86:89], v[164:167], v[50:53]
	v_mfma_f32_16x16x32_bf16 v[230:233], v[192:195], v[164:167], v[42:45]
	v_mfma_f32_16x16x32_bf16 v[140:143], v[196:199], v[164:167], v[34:37]
	s_setprio 0
	s_setprio 1
	v_mfma_f32_16x16x32_bf16 v[30:33], v[66:69], v[98:101], v[30:33]
	v_mfma_f32_16x16x32_bf16 v[22:25], v[70:73], v[98:101], v[22:25]
	v_mfma_f32_16x16x32_bf16 v[14:17], v[184:187], v[98:101], v[14:17]
	v_mfma_f32_16x16x32_bf16 v[6:9], v[188:191], v[98:101], v[6:9]
	v_mfma_f32_16x16x32_bf16 v[30:33], v[82:85], v[102:105], v[30:33]
	v_mfma_f32_16x16x32_bf16 v[26:29], v[66:69], v[118:121], v[26:29]
	v_mfma_f32_16x16x32_bf16 v[22:25], v[86:89], v[102:105], v[22:25]
	v_mfma_f32_16x16x32_bf16 v[18:21], v[70:73], v[118:121], v[18:21]
	v_mfma_f32_16x16x32_bf16 v[14:17], v[192:195], v[102:105], v[14:17]
	v_mfma_f32_16x16x32_bf16 v[10:13], v[184:187], v[118:121], v[10:13]
	v_mfma_f32_16x16x32_bf16 v[6:9], v[196:199], v[102:105], v[6:9]
	v_mfma_f32_16x16x32_bf16 v[2:5], v[188:191], v[118:121], v[2:5]
	v_mfma_f32_16x16x32_bf16 v[144:147], v[82:85], v[122:125], v[26:29]
	v_mfma_f32_16x16x32_bf16 v[164:167], v[86:89], v[122:125], v[18:21]
	v_mfma_f32_16x16x32_bf16 v[168:171], v[192:195], v[122:125], v[10:13]
	v_mfma_f32_16x16x32_bf16 v[184:187], v[196:199], v[122:125], v[2:5]
	s_setprio 0
	s_barrier
	s_nop 1
	ds_read_b128 v[2:5], v155
	ds_read_b128 v[10:13], v156
	ds_read_b128 v[188:191], v157
	ds_read_b128 v[156:159], v158
	ds_read_b128 v[18:21], v150 offset:32768
	ds_read_b128 v[26:29], v150 offset:34816
	ds_read_b128 v[34:37], v151 offset:32768
	ds_read_b128 v[42:45], v151 offset:34816
	ds_read_b128 v[50:53], v150 offset:36864
	ds_read_b128 v[58:61], v150 offset:38912
	ds_read_b128 v[192:195], v151 offset:36864
	ds_read_b128 v[196:199], v151 offset:38912
	s_waitcnt vmcnt(2)
	s_barrier
	s_waitcnt lgkmcnt(0)
	s_setprio 1
	s_waitcnt lgkmcnt(0)
	v_mfma_f32_16x16x32_bf16 v[66:69], v[18:21], v[2:5], v[126:129]
	v_mfma_f32_16x16x32_bf16 v[122:125], v[34:37], v[10:13], v[66:69]
	v_mfma_f32_16x16x32_bf16 v[66:69], v[18:21], v[188:191], v[136:139]
	v_mfma_f32_16x16x32_bf16 v[118:121], v[34:37], v[156:159], v[66:69]
	v_mfma_f32_16x16x32_bf16 v[66:69], v[26:29], v[2:5], v[206:209]
	v_mfma_f32_16x16x32_bf16 v[102:105], v[42:45], v[10:13], v[66:69]
	v_mfma_f32_16x16x32_bf16 v[66:69], v[26:29], v[188:191], v[114:117]
	v_mfma_f32_16x16x32_bf16 v[98:101], v[42:45], v[156:159], v[66:69]
	v_mfma_f32_16x16x32_bf16 v[66:69], v[50:53], v[2:5], v[110:113]
	v_mfma_f32_16x16x32_bf16 v[86:89], v[192:195], v[10:13], v[66:69]
	v_mfma_f32_16x16x32_bf16 v[66:69], v[50:53], v[188:191], v[106:109]
	v_mfma_f32_16x16x32_bf16 v[82:85], v[192:195], v[156:159], v[66:69]
	v_mfma_f32_16x16x32_bf16 v[66:69], v[58:61], v[2:5], v[218:221]
	v_mfma_f32_16x16x32_bf16 v[70:73], v[196:199], v[10:13], v[66:69]
	v_mfma_f32_16x16x32_bf16 v[66:69], v[58:61], v[188:191], v[222:225]
	v_mfma_f32_16x16x32_bf16 v[66:69], v[196:199], v[156:159], v[66:69]
	s_setprio 0
	s_barrier
	ds_read_b128 v[136:139], v0
	ds_read_b128 v[206:209], v152
	ds_read_b128 v[218:221], v153
	ds_read_b128 v[152:155], v154
	s_waitcnt vmcnt(0)
	s_barrier
	s_waitcnt lgkmcnt(0)
	s_setprio 1
	s_waitcnt lgkmcnt(0)
	v_mfma_f32_16x16x32_bf16 v[94:97], v[18:21], v[136:139], v[94:97]
	v_mfma_f32_16x16x32_bf16 v[18:21], v[18:21], v[218:221], v[90:93]
	v_mfma_f32_16x16x32_bf16 v[114:117], v[34:37], v[152:155], v[18:21]
	v_mfma_f32_16x16x32_bf16 v[18:21], v[26:29], v[136:139], v[160:163]
	v_mfma_f32_16x16x32_bf16 v[110:113], v[42:45], v[206:209], v[18:21]
	v_mfma_f32_16x16x32_bf16 v[18:21], v[26:29], v[218:221], v[172:175]
	v_mfma_f32_16x16x32_bf16 v[106:109], v[42:45], v[152:155], v[18:21]
	v_mfma_f32_16x16x32_bf16 v[18:21], v[50:53], v[136:139], v[78:81]
	v_mfma_f32_16x16x32_bf16 v[126:129], v[34:37], v[206:209], v[94:97]
	v_mfma_f32_16x16x32_bf16 v[94:97], v[192:195], v[206:209], v[18:21]
	v_mfma_f32_16x16x32_bf16 v[18:21], v[50:53], v[218:221], v[74:77]
	v_mfma_f32_16x16x32_bf16 v[90:93], v[192:195], v[152:155], v[18:21]
	v_mfma_f32_16x16x32_bf16 v[18:21], v[58:61], v[136:139], v[176:179]
	v_mfma_f32_16x16x32_bf16 v[78:81], v[196:199], v[206:209], v[18:21]
	v_mfma_f32_16x16x32_bf16 v[18:21], v[58:61], v[218:221], v[180:183]
	v_mfma_f32_16x16x32_bf16 v[74:77], v[196:199], v[152:155], v[18:21]
	s_setprio 0
	s_barrier
	ds_read_b128 v[160:163], v150 offset:49152
	ds_read_b128 v[172:175], v150 offset:51200
	ds_read_b128 v[176:179], v151 offset:49152
	ds_read_b128 v[180:183], v151 offset:51200
	ds_read_b128 v[192:195], v150 offset:53248
	ds_read_b128 v[196:199], v150 offset:55296
	ds_read_b128 v[222:225], v151 offset:53248
	ds_read_b128 v[148:151], v151 offset:55296
	s_barrier
	s_waitcnt lgkmcnt(0)
	s_setprio 1
	s_waitcnt lgkmcnt(0)
	v_mfma_f32_16x16x32_bf16 v[18:21], v[160:163], v[2:5], v[62:65]
	v_mfma_f32_16x16x32_bf16 v[58:61], v[176:179], v[10:13], v[18:21]
	v_mfma_f32_16x16x32_bf16 v[18:21], v[160:163], v[188:191], v[200:203]
	v_mfma_f32_16x16x32_bf16 v[50:53], v[176:179], v[156:159], v[18:21]
	v_mfma_f32_16x16x32_bf16 v[18:21], v[172:175], v[2:5], v[54:57]
	v_mfma_f32_16x16x32_bf16 v[42:45], v[180:183], v[10:13], v[18:21]
	v_mfma_f32_16x16x32_bf16 v[18:21], v[172:175], v[188:191], v[226:229]
	v_mfma_f32_16x16x32_bf16 v[34:37], v[180:183], v[156:159], v[18:21]
	v_mfma_f32_16x16x32_bf16 v[18:21], v[192:195], v[2:5], v[46:49]
	v_mfma_f32_16x16x32_bf16 v[2:5], v[196:199], v[2:5], v[38:41]
	v_mfma_f32_16x16x32_bf16 v[26:29], v[222:225], v[10:13], v[18:21]
	v_mfma_f32_16x16x32_bf16 v[18:21], v[192:195], v[188:191], v[230:233]
	v_mfma_f32_16x16x32_bf16 v[10:13], v[148:151], v[10:13], v[2:5]
	v_mfma_f32_16x16x32_bf16 v[2:5], v[196:199], v[188:191], v[140:143]
	v_mfma_f32_16x16x32_bf16 v[18:21], v[222:225], v[156:159], v[18:21]
	v_mfma_f32_16x16x32_bf16 v[2:5], v[148:151], v[156:159], v[2:5]
	s_setprio 0
	s_setprio 1
	v_mfma_f32_16x16x32_bf16 v[30:33], v[160:163], v[136:139], v[30:33]
	v_mfma_f32_16x16x32_bf16 v[62:65], v[176:179], v[206:209], v[30:33]
	v_mfma_f32_16x16x32_bf16 v[30:33], v[160:163], v[218:221], v[144:147]
	v_mfma_f32_16x16x32_bf16 v[22:25], v[172:175], v[136:139], v[22:25]
	v_mfma_f32_16x16x32_bf16 v[14:17], v[192:195], v[136:139], v[14:17]
	v_mfma_f32_16x16x32_bf16 v[54:57], v[176:179], v[152:155], v[30:33]
	v_mfma_f32_16x16x32_bf16 v[46:49], v[180:183], v[206:209], v[22:25]
	v_mfma_f32_16x16x32_bf16 v[22:25], v[172:175], v[218:221], v[164:167]
	v_mfma_f32_16x16x32_bf16 v[30:33], v[222:225], v[206:209], v[14:17]
	v_mfma_f32_16x16x32_bf16 v[14:17], v[192:195], v[218:221], v[168:171]
	v_mfma_f32_16x16x32_bf16 v[6:9], v[196:199], v[136:139], v[6:9]
	v_mfma_f32_16x16x32_bf16 v[38:41], v[180:183], v[152:155], v[22:25]
	v_mfma_f32_16x16x32_bf16 v[22:25], v[222:225], v[152:155], v[14:17]
	v_mfma_f32_16x16x32_bf16 v[14:17], v[148:151], v[206:209], v[6:9]
	v_mfma_f32_16x16x32_bf16 v[6:9], v[196:199], v[218:221], v[184:187]
	v_mfma_f32_16x16x32_bf16 v[6:9], v[148:151], v[152:155], v[6:9]
	s_setprio 0
	s_cmpk_gt_u32 s0, 0xff
	s_barrier
	s_cbranch_scc1 .LBB0_104
	s_barrier

.LBB0_108:
	s_lshl_b32 s24, s24, 5
	v_and_b32_e32 v19, 15, v17
	s_and_b32 s24, s24, 0x60
	v_lshlrev_b32_e32 v20, 7, v19
	v_or_b32_e32 v19, s24, v19
	s_add_i32 s24, s1, 0x18000
	s_mov_b64 s[28:29], 0x80
	v_lshl_or_b32 v20, s25, 13, v20
	v_lshl_add_u64 v[6:7], v[6:7], 0, s[28:29]
	s_mov_b32 m0, s24
	s_add_i32 s25, s1, 0x1a000
	s_waitcnt vmcnt(4)
	s_barrier
	global_load_lds_dwordx4 v[6:7], off
	v_lshl_add_u64 v[6:7], v[8:9], 0, s[28:29]
	s_mov_b32 m0, s25
	s_add_i32 s26, s1, 0x8000
	global_load_lds_dwordx4 v[6:7], off
	v_lshl_add_u64 v[6:7], v[12:13], 0, s[28:29]
	s_mov_b32 m0, s26
	s_add_i32 s27, s1, 0xa000
	global_load_lds_dwordx4 v[6:7], off
	v_lshl_add_u64 v[6:7], v[10:11], 0, s[28:29]
	s_mov_b32 m0, s27
	v_lshl_add_u64 v[4:5], v[4:5], 0, s[50:51]
	s_add_i32 s28, s1, 0x1c000
	global_load_lds_dwordx4 v[6:7], off
	v_lshl_add_u64 v[6:7], v[0:1], 1, v[4:5]
	s_mov_b32 m0, s28
	s_add_i32 s29, s1, 0x1e000
	global_load_lds_dwordx4 v[6:7], off
	v_lshl_add_u64 v[2:3], v[2:3], 1, v[4:5]
	s_mov_b32 m0, s29
	v_and_b32_e32 v21, 3, v18
	global_load_lds_dwordx4 v[2:3], off
	v_bfe_u32 v17, v17, 1, 3
	v_add_u32_e32 v0, v16, v14
	v_bitop3_b32 v18, v18, v17, 3 bitop3:0x6c
	v_bitop3_b32 v17, v21, v17, 4 bitop3:0x36
	s_waitcnt vmcnt(6)
	v_lshlrev_b64 v[2:3], 1, v[0:1]
	v_add_u32_e32 v0, v15, v14
	v_lshlrev_b32_e32 v18, 4, v18
	v_lshlrev_b32_e32 v17, 4, v17
	v_lshlrev_b32_e32 v19, 7, v19
	v_lshl_add_u64 v[140:141], s[4:5], 0, v[2:3]
	v_lshlrev_b64 v[4:5], 1, v[0:1]
	v_lshl_add_u64 v[144:145], v[2:3], 0, s[90:91]
	v_mov_b32_e32 v2, 0
	v_or_b32_e32 v148, v18, v20
	v_or_b32_e32 v150, v19, v18
	v_or_b32_e32 v149, v17, v20
	v_or_b32_e32 v151, v19, v17
	v_lshl_add_u64 v[142:143], s[4:5], 0, v[4:5]
	v_lshl_add_u64 v[146:147], v[4:5], 0, s[90:91]
	s_mov_b32 s4, -2
	v_mov_b32_e32 v3, v2
	v_mov_b32_e32 v4, v2
	v_mov_b32_e32 v5, v2
	v_mov_b32_e32 v6, v2
	v_mov_b32_e32 v7, v2
	v_mov_b32_e32 v8, v2
	v_mov_b32_e32 v9, v2
	v_mov_b32_e32 v10, v2
	v_mov_b32_e32 v11, v2
	v_mov_b32_e32 v12, v2
	v_mov_b32_e32 v13, v2
	v_mov_b32_e32 v14, v2
	v_mov_b32_e32 v15, v2
	v_mov_b32_e32 v16, v2
	v_mov_b32_e32 v17, v2
	v_mov_b32_e32 v18, v2
	v_mov_b32_e32 v19, v2
	v_mov_b32_e32 v20, v2
	v_mov_b32_e32 v21, v2
	v_mov_b32_e32 v22, v2
	v_mov_b32_e32 v23, v2
	v_mov_b32_e32 v24, v2
	v_mov_b32_e32 v25, v2
	v_mov_b32_e32 v26, v2
	v_mov_b32_e32 v27, v2
	v_mov_b32_e32 v28, v2
	v_mov_b32_e32 v29, v2
	v_mov_b32_e32 v30, v2
	v_mov_b32_e32 v31, v2
	v_mov_b32_e32 v32, v2
	v_mov_b32_e32 v33, v2
	v_mov_b32_e32 v34, v2
	v_mov_b32_e32 v35, v2
	v_mov_b32_e32 v36, v2
	v_mov_b32_e32 v37, v2
	v_mov_b32_e32 v38, v2
	v_mov_b32_e32 v39, v2
	v_mov_b32_e32 v40, v2
	v_mov_b32_e32 v41, v2
	v_mov_b32_e32 v42, v2
	v_mov_b32_e32 v43, v2
	v_mov_b32_e32 v44, v2
	v_mov_b32_e32 v45, v2
	v_mov_b32_e32 v46, v2
	v_mov_b32_e32 v47, v2
	v_mov_b32_e32 v48, v2
	v_mov_b32_e32 v49, v2
	v_mov_b32_e32 v50, v2
	v_mov_b32_e32 v51, v2
	v_mov_b32_e32 v52, v2
	v_mov_b32_e32 v53, v2
	v_mov_b32_e32 v54, v2
	v_mov_b32_e32 v55, v2
	v_mov_b32_e32 v56, v2
	v_mov_b32_e32 v57, v2
	v_mov_b32_e32 v58, v2
	v_mov_b32_e32 v59, v2
	v_mov_b32_e32 v60, v2
	v_mov_b32_e32 v61, v2
	v_mov_b32_e32 v62, v2
	v_mov_b32_e32 v63, v2
	v_mov_b32_e32 v64, v2
	v_mov_b32_e32 v65, v2
	v_mov_b32_e32 v66, v2
	v_mov_b32_e32 v67, v2
	v_mov_b32_e32 v68, v2
	v_mov_b32_e32 v69, v2
	v_mov_b32_e32 v70, v2
	v_mov_b32_e32 v71, v2
	v_mov_b32_e32 v72, v2
	v_mov_b32_e32 v73, v2
	v_mov_b32_e32 v74, v2
	v_mov_b32_e32 v75, v2
	v_mov_b32_e32 v76, v2
	v_mov_b32_e32 v77, v2
	v_mov_b32_e32 v78, v2
	v_mov_b32_e32 v79, v2
	v_mov_b32_e32 v80, v2
	v_mov_b32_e32 v81, v2
	v_mov_b32_e32 v82, v2
	v_mov_b32_e32 v83, v2
	v_mov_b32_e32 v84, v2
	v_mov_b32_e32 v85, v2
	v_mov_b32_e32 v86, v2
	v_mov_b32_e32 v87, v2
	v_mov_b32_e32 v88, v2
	v_mov_b32_e32 v89, v2
	v_mov_b32_e32 v90, v2
	v_mov_b32_e32 v91, v2
	v_mov_b32_e32 v92, v2
	v_mov_b32_e32 v93, v2
	v_mov_b32_e32 v94, v2
	v_mov_b32_e32 v95, v2
	v_mov_b32_e32 v96, v2
	v_mov_b32_e32 v97, v2
	v_mov_b32_e32 v98, v2
	v_mov_b32_e32 v99, v2
	v_mov_b32_e32 v100, v2
	v_mov_b32_e32 v101, v2
	v_mov_b32_e32 v102, v2
	v_mov_b32_e32 v103, v2
	v_mov_b32_e32 v104, v2
	v_mov_b32_e32 v105, v2
	v_mov_b32_e32 v106, v2
	v_mov_b32_e32 v107, v2
	v_mov_b32_e32 v108, v2
	v_mov_b32_e32 v109, v2
	v_mov_b32_e32 v110, v2
	v_mov_b32_e32 v111, v2
	v_mov_b32_e32 v112, v2
	v_mov_b32_e32 v113, v2
	v_mov_b32_e32 v114, v2
	v_mov_b32_e32 v115, v2
	v_mov_b32_e32 v116, v2
	v_mov_b32_e32 v117, v2
	v_mov_b32_e32 v118, v2
	v_mov_b32_e32 v119, v2
	v_mov_b32_e32 v120, v2
	v_mov_b32_e32 v121, v2
	v_mov_b32_e32 v122, v2
	v_mov_b32_e32 v123, v2
	v_mov_b32_e32 v124, v2
	v_mov_b32_e32 v125, v2
	v_mov_b32_e32 v126, v2
	v_mov_b32_e32 v127, v2
	v_mov_b32_e32 v128, v2
	v_mov_b32_e32 v129, v2
	s_mov_b64 s[34:35], 0x82d4900
	s_mov_b64 s[36:37], 0x8254980
	s_mov_b64 s[38:39], 0x82d4980
	s_waitcnt lgkmcnt(0)
	s_sub_u32 s100, s100, 0x40000000
	s_subb_u32 s101, s101, 0
	s_mov_b64 vcc, s[100:101]
	v_lshl_add_u64 v[210:211], v[132:133], 0, v[142:143]
	v_subrev_u32_e32 v210, vcc_lo, v210
	v_lshl_add_u64 v[214:215], v[132:133], 0, v[140:141]
	v_subrev_u32_e32 v214, vcc_lo, v214
	v_lshl_add_u64 v[242:243], v[132:133], 0, v[146:147]
	v_subrev_u32_e32 v242, vcc_lo, v242
	v_lshl_add_u64 v[244:245], v[132:133], 0, v[144:145]
	v_subrev_u32_e32 v244, vcc_lo, v244
	v_add_u32_e32 v211, 0x10000, v150
	v_add_u32_e32 v215, 0x10000, v151
	s_barrier
.LBB0_109:
	ds_read_b128 v[160:163], v211
	ds_read_b128 v[164:167], v215
	ds_read_b128 v[168:171], v211 offset:2048
	ds_read_b128 v[172:175], v215 offset:2048
	s_add_i32 s30, s1, 0xc000
	s_mov_b32 m0, s30
	s_add_i32 s5, s1, 0xe000
	ds_read_b128 v[176:179], v148
	ds_read_b128 v[180:183], v148 offset:2048
	ds_read_b128 v[184:187], v149
	ds_read_b128 v[188:191], v149 offset:2048
	ds_read_b128 v[192:195], v148 offset:4096
	ds_read_b128 v[196:199], v148 offset:6144
	ds_read_b128 v[200:203], v149 offset:4096
	ds_read_b128 v[206:209], v149 offset:6144
	s_add_u32 s100, vcc_lo, s50
	s_addc_u32 s101, vcc_hi, s51
	global_load_lds_dwordx4 v210, s[100:101]
	s_mov_b32 m0, s5
	s_add_u32 s100, vcc_lo, s50
	s_addc_u32 s101, vcc_hi, s51
	global_load_lds_dwordx4 v214, s[100:101]
	s_waitcnt lgkmcnt(8)
	s_waitcnt vmcnt(10)
	s_barrier
	s_waitcnt lgkmcnt(0)
	s_setprio 1
	s_waitcnt lgkmcnt(0)
	v_mfma_f32_16x16x32_bf16 v[126:129], v[160:163], v[176:179], v[126:129]
	v_mfma_f32_16x16x32_bf16 v[122:125], v[168:171], v[176:179], v[122:125]
	v_mfma_f32_16x16x32_bf16 v[118:121], v[160:163], v[180:183], v[118:121]
	v_mfma_f32_16x16x32_bf16 v[114:117], v[168:171], v[180:183], v[114:117]
	v_mfma_f32_16x16x32_bf16 v[110:113], v[160:163], v[192:195], v[110:113]
	v_mfma_f32_16x16x32_bf16 v[106:109], v[168:171], v[192:195], v[106:109]
	v_mfma_f32_16x16x32_bf16 v[102:105], v[160:163], v[196:199], v[102:105]
	v_mfma_f32_16x16x32_bf16 v[98:101], v[168:171], v[196:199], v[98:101]
	v_mfma_f32_16x16x32_bf16 v[126:129], v[164:167], v[184:187], v[126:129]
	v_mfma_f32_16x16x32_bf16 v[122:125], v[172:175], v[184:187], v[122:125]
	v_mfma_f32_16x16x32_bf16 v[118:121], v[164:167], v[188:191], v[118:121]
	v_mfma_f32_16x16x32_bf16 v[114:117], v[172:175], v[188:191], v[114:117]
	v_mfma_f32_16x16x32_bf16 v[110:113], v[164:167], v[200:203], v[110:113]
	v_mfma_f32_16x16x32_bf16 v[106:109], v[172:175], v[200:203], v[106:109]
	v_mfma_f32_16x16x32_bf16 v[102:105], v[164:167], v[206:209], v[102:105]
	v_mfma_f32_16x16x32_bf16 v[98:101], v[172:175], v[206:209], v[98:101]
	s_setprio 0
	s_barrier
	s_mov_b32 m0, s2
	ds_read_b128 v[218:221], v211 offset:16384
	ds_read_b128 v[222:225], v215 offset:16384
	ds_read_b128 v[226:229], v211 offset:18432
	ds_read_b128 v[230:233], v215 offset:18432
	s_add_u32 s100, vcc_lo, s70
	s_addc_u32 s101, vcc_hi, s71
	global_load_lds_dwordx4 v242, s[100:101]
	s_mov_b32 m0, s3
	s_add_u32 s100, vcc_lo, s70
	s_addc_u32 s101, vcc_hi, s71
	global_load_lds_dwordx4 v244, s[100:101]
	s_waitcnt vmcnt(10)
	s_waitcnt lgkmcnt(0)
	s_barrier
	s_waitcnt lgkmcnt(0)
	s_setprio 1
	s_waitcnt lgkmcnt(0)
	v_mfma_f32_16x16x32_bf16 v[94:97], v[218:221], v[176:179], v[94:97]
	v_mfma_f32_16x16x32_bf16 v[90:93], v[226:229], v[176:179], v[90:93]
	v_mfma_f32_16x16x32_bf16 v[86:89], v[218:221], v[180:183], v[86:89]
	v_mfma_f32_16x16x32_bf16 v[82:85], v[226:229], v[180:183], v[82:85]
	v_mfma_f32_16x16x32_bf16 v[78:81], v[218:221], v[192:195], v[78:81]
	v_mfma_f32_16x16x32_bf16 v[74:77], v[226:229], v[192:195], v[74:77]
	v_mfma_f32_16x16x32_bf16 v[70:73], v[218:221], v[196:199], v[70:73]
	v_mfma_f32_16x16x32_bf16 v[66:69], v[226:229], v[196:199], v[66:69]
	v_mfma_f32_16x16x32_bf16 v[94:97], v[222:225], v[184:187], v[94:97]
	v_mfma_f32_16x16x32_bf16 v[90:93], v[230:233], v[184:187], v[90:93]
	v_mfma_f32_16x16x32_bf16 v[86:89], v[222:225], v[188:191], v[86:89]
	v_mfma_f32_16x16x32_bf16 v[82:85], v[230:233], v[188:191], v[82:85]
	v_mfma_f32_16x16x32_bf16 v[78:81], v[222:225], v[200:203], v[78:81]
	v_mfma_f32_16x16x32_bf16 v[74:77], v[230:233], v[200:203], v[74:77]
	v_mfma_f32_16x16x32_bf16 v[70:73], v[222:225], v[206:209], v[70:73]
	v_mfma_f32_16x16x32_bf16 v[66:69], v[230:233], v[206:209], v[66:69]
	s_setprio 0
	s_mov_b32 m0, s1
	s_barrier
	ds_read_b128 v[176:179], v148 offset:16384
	ds_read_b128 v[180:183], v148 offset:18432
	ds_read_b128 v[184:187], v149 offset:16384
	ds_read_b128 v[188:191], v149 offset:18432
	ds_read_b128 v[192:195], v148 offset:20480
	ds_read_b128 v[196:199], v148 offset:22528
	ds_read_b128 v[200:203], v149 offset:20480
	ds_read_b128 v[206:209], v149 offset:22528
	s_add_u32 s100, vcc_lo, s54
	s_addc_u32 s101, vcc_hi, s55
	global_load_lds_dwordx4 v210, s[100:101]
	s_mov_b32 m0, s9
	s_add_u32 s100, vcc_lo, s54
	s_addc_u32 s101, vcc_hi, s55
	global_load_lds_dwordx4 v214, s[100:101]
	s_mov_b32 m0, s11
	s_add_u32 s100, vcc_lo, s34
	s_addc_u32 s101, vcc_hi, s35
	global_load_lds_dwordx4 v242, s[100:101]
	s_mov_b32 m0, s12
	s_add_u32 s100, vcc_lo, s34
	s_addc_u32 s101, vcc_hi, s35
	global_load_lds_dwordx4 v244, s[100:101]
	s_waitcnt vmcnt(10)
	s_waitcnt lgkmcnt(0)
	s_barrier
	s_waitcnt lgkmcnt(0)
	s_setprio 1
	s_waitcnt lgkmcnt(0)
	v_mfma_f32_16x16x32_bf16 v[62:65], v[160:163], v[176:179], v[62:65]
	v_mfma_f32_16x16x32_bf16 v[58:61], v[168:171], v[176:179], v[58:61]
	v_mfma_f32_16x16x32_bf16 v[54:57], v[160:163], v[180:183], v[54:57]
	v_mfma_f32_16x16x32_bf16 v[50:53], v[168:171], v[180:183], v[50:53]
	v_mfma_f32_16x16x32_bf16 v[46:49], v[160:163], v[192:195], v[46:49]
	v_mfma_f32_16x16x32_bf16 v[42:45], v[168:171], v[192:195], v[42:45]
	v_mfma_f32_16x16x32_bf16 v[38:41], v[160:163], v[196:199], v[38:41]
	v_mfma_f32_16x16x32_bf16 v[34:37], v[168:171], v[196:199], v[34:37]
	v_mfma_f32_16x16x32_bf16 v[62:65], v[164:167], v[184:187], v[62:65]
	v_mfma_f32_16x16x32_bf16 v[58:61], v[172:175], v[184:187], v[58:61]
	v_mfma_f32_16x16x32_bf16 v[54:57], v[164:167], v[188:191], v[54:57]
	v_mfma_f32_16x16x32_bf16 v[50:53], v[172:175], v[188:191], v[50:53]
	v_mfma_f32_16x16x32_bf16 v[46:49], v[164:167], v[200:203], v[46:49]
	v_mfma_f32_16x16x32_bf16 v[42:45], v[172:175], v[200:203], v[42:45]
	v_mfma_f32_16x16x32_bf16 v[38:41], v[164:167], v[206:209], v[38:41]
	v_mfma_f32_16x16x32_bf16 v[34:37], v[172:175], v[206:209], v[34:37]
	v_mfma_f32_16x16x32_bf16 v[30:33], v[218:221], v[176:179], v[30:33]
	v_mfma_f32_16x16x32_bf16 v[26:29], v[226:229], v[176:179], v[26:29]
	v_mfma_f32_16x16x32_bf16 v[22:25], v[218:221], v[180:183], v[22:25]
	v_mfma_f32_16x16x32_bf16 v[18:21], v[226:229], v[180:183], v[18:21]
	v_mfma_f32_16x16x32_bf16 v[14:17], v[218:221], v[192:195], v[14:17]
	v_mfma_f32_16x16x32_bf16 v[10:13], v[226:229], v[192:195], v[10:13]
	v_mfma_f32_16x16x32_bf16 v[6:9], v[218:221], v[196:199], v[6:9]
	v_mfma_f32_16x16x32_bf16 v[2:5], v[226:229], v[196:199], v[2:5]
	v_mfma_f32_16x16x32_bf16 v[30:33], v[222:225], v[184:187], v[30:33]
	v_mfma_f32_16x16x32_bf16 v[26:29], v[230:233], v[184:187], v[26:29]
	v_mfma_f32_16x16x32_bf16 v[22:25], v[222:225], v[188:191], v[22:25]
	v_mfma_f32_16x16x32_bf16 v[18:21], v[230:233], v[188:191], v[18:21]
	v_mfma_f32_16x16x32_bf16 v[14:17], v[222:225], v[200:203], v[14:17]
	v_mfma_f32_16x16x32_bf16 v[10:13], v[230:233], v[200:203], v[10:13]
	v_mfma_f32_16x16x32_bf16 v[6:9], v[222:225], v[206:209], v[6:9]
	v_mfma_f32_16x16x32_bf16 v[2:5], v[230:233], v[206:209], v[2:5]
	s_setprio 0
	s_barrier
	ds_read_b128 v[168:171], v211 offset:32768
	ds_read_b128 v[172:175], v215 offset:32768
	ds_read_b128 v[176:179], v211 offset:34816
	ds_read_b128 v[180:183], v215 offset:34816
	s_mov_b32 m0, s13
	ds_read_b128 v[184:187], v148 offset:32768
	ds_read_b128 v[188:191], v148 offset:34816
	ds_read_b128 v[192:195], v149 offset:32768
	ds_read_b128 v[196:199], v149 offset:34816
	ds_read_b128 v[200:203], v148 offset:36864
	ds_read_b128 v[206:209], v148 offset:38912
	ds_read_b128 v[218:221], v149 offset:36864
	ds_read_b128 v[222:225], v149 offset:38912
	s_add_u32 s100, vcc_lo, s58
	s_addc_u32 s101, vcc_hi, s59
	global_load_lds_dwordx4 v210, s[100:101]
	s_mov_b32 m0, s23
	s_add_u32 s100, vcc_lo, s58
	s_addc_u32 s101, vcc_hi, s59
	global_load_lds_dwordx4 v214, s[100:101]
	s_waitcnt lgkmcnt(8)
	s_waitcnt vmcnt(10)
	s_barrier
	s_waitcnt lgkmcnt(0)
	s_setprio 1
	s_waitcnt lgkmcnt(0)
	v_mfma_f32_16x16x32_bf16 v[126:129], v[168:171], v[184:187], v[126:129]
	v_mfma_f32_16x16x32_bf16 v[122:125], v[176:179], v[184:187], v[122:125]
	v_mfma_f32_16x16x32_bf16 v[118:121], v[168:171], v[188:191], v[118:121]
	v_mfma_f32_16x16x32_bf16 v[114:117], v[176:179], v[188:191], v[114:117]
	v_mfma_f32_16x16x32_bf16 v[110:113], v[168:171], v[200:203], v[110:113]
	v_mfma_f32_16x16x32_bf16 v[106:109], v[176:179], v[200:203], v[106:109]
	v_mfma_f32_16x16x32_bf16 v[102:105], v[168:171], v[206:209], v[102:105]
	v_mfma_f32_16x16x32_bf16 v[98:101], v[176:179], v[206:209], v[98:101]
	v_mfma_f32_16x16x32_bf16 v[126:129], v[172:175], v[192:195], v[126:129]
	v_mfma_f32_16x16x32_bf16 v[122:125], v[180:183], v[192:195], v[122:125]
	v_mfma_f32_16x16x32_bf16 v[118:121], v[172:175], v[196:199], v[118:121]
	v_mfma_f32_16x16x32_bf16 v[114:117], v[180:183], v[196:199], v[114:117]
	v_mfma_f32_16x16x32_bf16 v[110:113], v[172:175], v[218:221], v[110:113]
	v_mfma_f32_16x16x32_bf16 v[106:109], v[180:183], v[218:221], v[106:109]
	v_mfma_f32_16x16x32_bf16 v[102:105], v[172:175], v[222:225], v[102:105]
	v_mfma_f32_16x16x32_bf16 v[98:101], v[180:183], v[222:225], v[98:101]
	s_setprio 0
	s_barrier
	s_mov_b32 m0, s24
	ds_read_b128 v[226:229], v211 offset:49152
	ds_read_b128 v[230:233], v215 offset:49152
	ds_read_b128 v[234:237], v211 offset:51200
	ds_read_b128 v[238:241], v215 offset:51200
	s_add_u32 s100, vcc_lo, s36
	s_addc_u32 s101, vcc_hi, s37
	global_load_lds_dwordx4 v242, s[100:101]
	s_mov_b32 m0, s25
	s_add_u32 s100, vcc_lo, s36
	s_addc_u32 s101, vcc_hi, s37
	global_load_lds_dwordx4 v244, s[100:101]
	s_waitcnt vmcnt(10)
	s_waitcnt lgkmcnt(0)
	s_barrier
	s_waitcnt lgkmcnt(0)
	s_setprio 1
	s_waitcnt lgkmcnt(0)
	v_mfma_f32_16x16x32_bf16 v[94:97], v[226:229], v[184:187], v[94:97]
	v_mfma_f32_16x16x32_bf16 v[90:93], v[234:237], v[184:187], v[90:93]
	v_mfma_f32_16x16x32_bf16 v[86:89], v[226:229], v[188:191], v[86:89]
	v_mfma_f32_16x16x32_bf16 v[82:85], v[234:237], v[188:191], v[82:85]
	v_mfma_f32_16x16x32_bf16 v[78:81], v[226:229], v[200:203], v[78:81]
	v_mfma_f32_16x16x32_bf16 v[74:77], v[234:237], v[200:203], v[74:77]
	v_mfma_f32_16x16x32_bf16 v[70:73], v[226:229], v[206:209], v[70:73]
	v_mfma_f32_16x16x32_bf16 v[66:69], v[234:237], v[206:209], v[66:69]
	v_mfma_f32_16x16x32_bf16 v[94:97], v[230:233], v[192:195], v[94:97]
	v_mfma_f32_16x16x32_bf16 v[90:93], v[238:241], v[192:195], v[90:93]
	v_mfma_f32_16x16x32_bf16 v[86:89], v[230:233], v[196:199], v[86:89]
	v_mfma_f32_16x16x32_bf16 v[82:85], v[238:241], v[196:199], v[82:85]
	v_mfma_f32_16x16x32_bf16 v[78:81], v[230:233], v[218:221], v[78:81]
	v_mfma_f32_16x16x32_bf16 v[74:77], v[238:241], v[218:221], v[74:77]
	v_mfma_f32_16x16x32_bf16 v[70:73], v[230:233], v[222:225], v[70:73]
	v_mfma_f32_16x16x32_bf16 v[66:69], v[238:241], v[222:225], v[66:69]
	s_setprio 0
	s_mov_b32 m0, s26
	s_barrier
	ds_read_b128 v[184:187], v148 offset:49152
	ds_read_b128 v[188:191], v148 offset:51200
	ds_read_b128 v[192:195], v149 offset:49152
	ds_read_b128 v[196:199], v149 offset:51200
	ds_read_b128 v[200:203], v148 offset:53248
	ds_read_b128 v[206:209], v148 offset:55296
	ds_read_b128 v[218:221], v149 offset:53248
	ds_read_b128 v[222:225], v149 offset:55296
	s_add_u32 s100, vcc_lo, s62
	s_addc_u32 s101, vcc_hi, s63
	global_load_lds_dwordx4 v210, s[100:101]
	s_mov_b32 m0, s27
	s_add_u32 s100, vcc_lo, s62
	s_addc_u32 s101, vcc_hi, s63
	global_load_lds_dwordx4 v214, s[100:101]
	s_mov_b32 m0, s28
	s_add_u32 s100, vcc_lo, s38
	s_addc_u32 s101, vcc_hi, s39
	global_load_lds_dwordx4 v242, s[100:101]
	s_mov_b32 m0, s29
	s_add_u32 s100, vcc_lo, s38
	s_addc_u32 s101, vcc_hi, s39
	global_load_lds_dwordx4 v244, s[100:101]
	s_waitcnt vmcnt(10)
	s_waitcnt lgkmcnt(0)
	s_barrier
	s_waitcnt lgkmcnt(0)
	s_setprio 1
	s_waitcnt lgkmcnt(0)
	v_mfma_f32_16x16x32_bf16 v[62:65], v[168:171], v[184:187], v[62:65]
	v_mfma_f32_16x16x32_bf16 v[58:61], v[176:179], v[184:187], v[58:61]
	v_mfma_f32_16x16x32_bf16 v[54:57], v[168:171], v[188:191], v[54:57]
	v_mfma_f32_16x16x32_bf16 v[50:53], v[176:179], v[188:191], v[50:53]
	v_mfma_f32_16x16x32_bf16 v[46:49], v[168:171], v[200:203], v[46:49]
	v_mfma_f32_16x16x32_bf16 v[42:45], v[176:179], v[200:203], v[42:45]
	v_mfma_f32_16x16x32_bf16 v[38:41], v[168:171], v[206:209], v[38:41]
	v_mfma_f32_16x16x32_bf16 v[34:37], v[176:179], v[206:209], v[34:37]
	v_mfma_f32_16x16x32_bf16 v[62:65], v[172:175], v[192:195], v[62:65]
	v_mfma_f32_16x16x32_bf16 v[58:61], v[180:183], v[192:195], v[58:61]
	v_mfma_f32_16x16x32_bf16 v[54:57], v[172:175], v[196:199], v[54:57]
	v_mfma_f32_16x16x32_bf16 v[50:53], v[180:183], v[196:199], v[50:53]
	v_mfma_f32_16x16x32_bf16 v[46:49], v[172:175], v[218:221], v[46:49]
	v_mfma_f32_16x16x32_bf16 v[42:45], v[180:183], v[218:221], v[42:45]
	v_mfma_f32_16x16x32_bf16 v[38:41], v[172:175], v[222:225], v[38:41]
	v_mfma_f32_16x16x32_bf16 v[34:37], v[180:183], v[222:225], v[34:37]
	v_mfma_f32_16x16x32_bf16 v[30:33], v[226:229], v[184:187], v[30:33]
	v_mfma_f32_16x16x32_bf16 v[26:29], v[234:237], v[184:187], v[26:29]
	v_mfma_f32_16x16x32_bf16 v[22:25], v[226:229], v[188:191], v[22:25]
	v_mfma_f32_16x16x32_bf16 v[18:21], v[234:237], v[188:191], v[18:21]
	v_mfma_f32_16x16x32_bf16 v[14:17], v[226:229], v[200:203], v[14:17]
	v_mfma_f32_16x16x32_bf16 v[10:13], v[234:237], v[200:203], v[10:13]
	v_mfma_f32_16x16x32_bf16 v[6:9], v[226:229], v[206:209], v[6:9]
	v_mfma_f32_16x16x32_bf16 v[2:5], v[234:237], v[206:209], v[2:5]
	v_mfma_f32_16x16x32_bf16 v[30:33], v[230:233], v[192:195], v[30:33]
	v_mfma_f32_16x16x32_bf16 v[26:29], v[238:241], v[192:195], v[26:29]
	v_mfma_f32_16x16x32_bf16 v[22:25], v[230:233], v[196:199], v[22:25]
	v_mfma_f32_16x16x32_bf16 v[18:21], v[238:241], v[196:199], v[18:21]
	v_mfma_f32_16x16x32_bf16 v[14:17], v[230:233], v[218:221], v[14:17]
	v_mfma_f32_16x16x32_bf16 v[10:13], v[238:241], v[218:221], v[10:13]
	v_mfma_f32_16x16x32_bf16 v[6:9], v[230:233], v[222:225], v[6:9]
	v_mfma_f32_16x16x32_bf16 v[2:5], v[238:241], v[222:225], v[2:5]
	s_setprio 0
	s_add_u32 vcc_lo, vcc_lo, s54
	s_addc_u32 vcc_hi, vcc_hi, s55
	s_add_i32 s4, s4, 2
	s_cmp_lt_u32 s4, 28
	v_lshl_add_u64 v[132:133], v[132:133], 0, s[54:55]
	s_barrier
	s_cbranch_scc1 .LBB0_109
	s_waitcnt vmcnt(6)
	v_or_b32_e32 v0, 0x10000, v150
	v_add_u32_e32 v153, 0x10800, v150
	v_or_b32_e32 v152, 0x10000, v151
	v_add_u32_e32 v154, 0x10800, v151
	v_or_b32_e32 v155, 0x14000, v150
	v_add_u32_e32 v157, 0x14800, v150
	v_or_b32_e32 v156, 0x14000, v151
	v_add_u32_e32 v158, 0x14800, v151
	v_or_b32_e32 v159, 0x18000, v150
	v_add_u32_e32 v161, 0x18800, v150
	v_or_b32_e32 v160, 0x18000, v151
	v_add_u32_e32 v162, 0x18800, v151
	v_or_b32_e32 v163, 0x1c000, v150
	v_add_u32_e32 v165, 0x1c800, v150
	v_or_b32_e32 v164, 0x1c000, v151
	v_add_u32_e32 v166, 0x1c800, v151
	s_mov_b64 s[2:3], 0xf80
	s_mov_b32 m0, s30
	v_lshl_add_u64 v[132:133], v[138:139], 0, s[2:3]
	ds_read_b128 v[140:143], v0
	ds_read_b128 v[144:147], v152
	ds_read_b128 v[150:153], v153
	ds_read_b128 v[168:171], v154
	ds_read_b128 v[172:175], v148
	ds_read_b128 v[176:179], v148 offset:2048
	ds_read_b128 v[180:183], v149
	ds_read_b128 v[184:187], v149 offset:2048
	ds_read_b128 v[188:191], v148 offset:4096
	ds_read_b128 v[192:195], v148 offset:6144
	ds_read_b128 v[196:199], v149 offset:4096
	ds_read_b128 v[200:203], v149 offset:6144
	global_load_lds_dwordx4 v[132:133], off
	v_lshl_add_u64 v[132:133], v[136:137], 0, s[2:3]
	s_mov_b32 m0, s5
	s_nop 0
	global_load_lds_dwordx4 v[132:133], off
	s_barrier
	s_waitcnt lgkmcnt(0)
	s_setprio 1
	s_waitcnt lgkmcnt(0)
	v_mfma_f32_16x16x32_bf16 v[126:129], v[140:143], v[172:175], v[126:129]
	v_mfma_f32_16x16x32_bf16 v[122:125], v[150:153], v[172:175], v[122:125]
	v_mfma_f32_16x16x32_bf16 v[118:121], v[140:143], v[176:179], v[118:121]
	v_mfma_f32_16x16x32_bf16 v[110:113], v[140:143], v[188:191], v[110:113]
	v_mfma_f32_16x16x32_bf16 v[106:109], v[150:153], v[188:191], v[106:109]
	v_mfma_f32_16x16x32_bf16 v[126:129], v[144:147], v[180:183], v[126:129]
	v_mfma_f32_16x16x32_bf16 v[122:125], v[168:171], v[180:183], v[122:125]
	v_mfma_f32_16x16x32_bf16 v[118:121], v[144:147], v[184:187], v[118:121]
	v_mfma_f32_16x16x32_bf16 v[114:117], v[150:153], v[176:179], v[114:117]
	v_mfma_f32_16x16x32_bf16 v[110:113], v[144:147], v[196:199], v[110:113]
	v_mfma_f32_16x16x32_bf16 v[106:109], v[168:171], v[196:199], v[106:109]
	v_mfma_f32_16x16x32_bf16 v[102:105], v[140:143], v[192:195], v[102:105]
	v_mfma_f32_16x16x32_bf16 v[98:101], v[150:153], v[192:195], v[98:101]
	v_mfma_f32_16x16x32_bf16 v[136:139], v[168:171], v[184:187], v[114:117]
	v_mfma_f32_16x16x32_bf16 v[206:209], v[144:147], v[200:203], v[102:105]
	v_mfma_f32_16x16x32_bf16 v[218:221], v[168:171], v[200:203], v[98:101]
	s_setprio 0
	s_barrier
	s_nop 2
	ds_read_b128 v[98:101], v155
	ds_read_b128 v[102:105], v156
	ds_read_b128 v[114:117], v157
	ds_read_b128 v[154:157], v158
	s_barrier
	s_waitcnt lgkmcnt(0)
	s_setprio 1
	s_waitcnt lgkmcnt(0)
	v_mfma_f32_16x16x32_bf16 v[94:97], v[98:101], v[172:175], v[94:97]
	v_mfma_f32_16x16x32_bf16 v[90:93], v[114:117], v[172:175], v[90:93]
	v_mfma_f32_16x16x32_bf16 v[78:81], v[98:101], v[188:191], v[78:81]
	v_mfma_f32_16x16x32_bf16 v[74:77], v[114:117], v[188:191], v[74:77]
	v_mfma_f32_16x16x32_bf16 v[94:97], v[102:105], v[180:183], v[94:97]
	v_mfma_f32_16x16x32_bf16 v[90:93], v[154:157], v[180:183], v[90:93]
	v_mfma_f32_16x16x32_bf16 v[86:89], v[98:101], v[176:179], v[86:89]
	v_mfma_f32_16x16x32_bf16 v[82:85], v[114:117], v[176:179], v[82:85]
	v_mfma_f32_16x16x32_bf16 v[78:81], v[102:105], v[196:199], v[78:81]
	v_mfma_f32_16x16x32_bf16 v[74:77], v[154:157], v[196:199], v[74:77]
	v_mfma_f32_16x16x32_bf16 v[70:73], v[98:101], v[192:195], v[70:73]
	v_mfma_f32_16x16x32_bf16 v[66:69], v[114:117], v[192:195], v[66:69]
	v_mfma_f32_16x16x32_bf16 v[172:175], v[102:105], v[184:187], v[86:89]
	v_mfma_f32_16x16x32_bf16 v[176:179], v[154:157], v[184:187], v[82:85]
	v_mfma_f32_16x16x32_bf16 v[180:183], v[102:105], v[200:203], v[70:73]
	v_mfma_f32_16x16x32_bf16 v[184:187], v[154:157], v[200:203], v[66:69]
	s_setprio 0
	s_barrier
	s_nop 1
	ds_read_b128 v[66:69], v148 offset:16384
	ds_read_b128 v[70:73], v148 offset:18432
	ds_read_b128 v[82:85], v149 offset:16384
	ds_read_b128 v[86:89], v149 offset:18432
	ds_read_b128 v[188:191], v148 offset:20480
	ds_read_b128 v[192:195], v148 offset:22528
	ds_read_b128 v[196:199], v149 offset:20480
	ds_read_b128 v[200:203], v149 offset:22528
	s_waitcnt vmcnt(4)
	s_barrier
	s_waitcnt lgkmcnt(0)
	s_setprio 1
	s_waitcnt lgkmcnt(0)
	v_mfma_f32_16x16x32_bf16 v[62:65], v[140:143], v[66:69], v[62:65]
	v_mfma_f32_16x16x32_bf16 v[58:61], v[150:153], v[66:69], v[58:61]
	v_mfma_f32_16x16x32_bf16 v[46:49], v[140:143], v[188:191], v[46:49]
	v_mfma_f32_16x16x32_bf16 v[42:45], v[150:153], v[188:191], v[42:45]
	v_mfma_f32_16x16x32_bf16 v[62:65], v[144:147], v[82:85], v[62:65]
	v_mfma_f32_16x16x32_bf16 v[58:61], v[168:171], v[82:85], v[58:61]
	v_mfma_f32_16x16x32_bf16 v[54:57], v[140:143], v[70:73], v[54:57]
	v_mfma_f32_16x16x32_bf16 v[50:53], v[150:153], v[70:73], v[50:53]
	v_mfma_f32_16x16x32_bf16 v[46:49], v[144:147], v[196:199], v[46:49]
	v_mfma_f32_16x16x32_bf16 v[42:45], v[168:171], v[196:199], v[42:45]
	v_mfma_f32_16x16x32_bf16 v[38:41], v[140:143], v[192:195], v[38:41]
	v_mfma_f32_16x16x32_bf16 v[34:37], v[150:153], v[192:195], v[34:37]
	v_mfma_f32_16x16x32_bf16 v[222:225], v[144:147], v[86:89], v[54:57]
	v_mfma_f32_16x16x32_bf16 v[226:229], v[168:171], v[86:89], v[50:53]
	v_mfma_f32_16x16x32_bf16 v[140:143], v[144:147], v[200:203], v[38:41]
	v_mfma_f32_16x16x32_bf16 v[144:147], v[168:171], v[200:203], v[34:37]
	s_setprio 0
	s_setprio 1
	v_mfma_f32_16x16x32_bf16 v[30:33], v[98:101], v[66:69], v[30:33]
	v_mfma_f32_16x16x32_bf16 v[26:29], v[114:117], v[66:69], v[26:29]
	v_mfma_f32_16x16x32_bf16 v[14:17], v[98:101], v[188:191], v[14:17]
	v_mfma_f32_16x16x32_bf16 v[10:13], v[114:117], v[188:191], v[10:13]
	v_mfma_f32_16x16x32_bf16 v[30:33], v[102:105], v[82:85], v[30:33]
	v_mfma_f32_16x16x32_bf16 v[26:29], v[154:157], v[82:85], v[26:29]
	v_mfma_f32_16x16x32_bf16 v[22:25], v[98:101], v[70:73], v[22:25]
	v_mfma_f32_16x16x32_bf16 v[18:21], v[114:117], v[70:73], v[18:21]
	v_mfma_f32_16x16x32_bf16 v[14:17], v[102:105], v[196:199], v[14:17]
	v_mfma_f32_16x16x32_bf16 v[10:13], v[154:157], v[196:199], v[10:13]
	v_mfma_f32_16x16x32_bf16 v[6:9], v[98:101], v[192:195], v[6:9]
	v_mfma_f32_16x16x32_bf16 v[2:5], v[114:117], v[192:195], v[2:5]
	v_mfma_f32_16x16x32_bf16 v[150:153], v[102:105], v[86:89], v[22:25]
	v_mfma_f32_16x16x32_bf16 v[168:171], v[154:157], v[86:89], v[18:21]
	v_mfma_f32_16x16x32_bf16 v[188:191], v[102:105], v[200:203], v[6:9]
	v_mfma_f32_16x16x32_bf16 v[154:157], v[154:157], v[200:203], v[2:5]
	s_setprio 0
	s_barrier
	s_nop 1
	ds_read_b128 v[2:5], v159
	ds_read_b128 v[6:9], v160
	ds_read_b128 v[158:161], v161
	ds_read_b128 v[192:195], v162
	ds_read_b128 v[18:21], v148 offset:32768
	ds_read_b128 v[22:25], v148 offset:34816
	ds_read_b128 v[34:37], v149 offset:32768
	ds_read_b128 v[38:41], v149 offset:34816
	ds_read_b128 v[50:53], v148 offset:36864
	ds_read_b128 v[54:57], v148 offset:38912
	ds_read_b128 v[196:199], v149 offset:36864
	ds_read_b128 v[200:203], v149 offset:38912
	s_waitcnt vmcnt(2)
	s_barrier
	s_waitcnt lgkmcnt(0)
	s_setprio 1
	s_waitcnt lgkmcnt(0)
	v_mfma_f32_16x16x32_bf16 v[66:69], v[2:5], v[18:21], v[126:129]
	v_mfma_f32_16x16x32_bf16 v[126:129], v[6:9], v[34:37], v[66:69]
	v_mfma_f32_16x16x32_bf16 v[66:69], v[158:161], v[18:21], v[122:125]
	v_mfma_f32_16x16x32_bf16 v[114:117], v[192:195], v[34:37], v[66:69]
	v_mfma_f32_16x16x32_bf16 v[66:69], v[2:5], v[22:25], v[118:121]
	v_mfma_f32_16x16x32_bf16 v[102:105], v[6:9], v[38:41], v[66:69]
	v_mfma_f32_16x16x32_bf16 v[66:69], v[158:161], v[22:25], v[136:139]
	v_mfma_f32_16x16x32_bf16 v[98:101], v[192:195], v[38:41], v[66:69]
	v_mfma_f32_16x16x32_bf16 v[66:69], v[2:5], v[50:53], v[110:113]
	v_mfma_f32_16x16x32_bf16 v[86:89], v[6:9], v[196:199], v[66:69]
	v_mfma_f32_16x16x32_bf16 v[66:69], v[158:161], v[50:53], v[106:109]
	v_mfma_f32_16x16x32_bf16 v[82:85], v[192:195], v[196:199], v[66:69]
	v_mfma_f32_16x16x32_bf16 v[66:69], v[2:5], v[54:57], v[206:209]
	v_mfma_f32_16x16x32_bf16 v[70:73], v[6:9], v[200:203], v[66:69]
	v_mfma_f32_16x16x32_bf16 v[66:69], v[158:161], v[54:57], v[218:221]
	v_mfma_f32_16x16x32_bf16 v[66:69], v[192:195], v[200:203], v[66:69]
	s_setprio 0
	s_barrier
	ds_read_b128 v[136:139], v163
	ds_read_b128 v[206:209], v164
	ds_read_b128 v[162:165], v165
	ds_read_b128 v[218:221], v166
	s_waitcnt vmcnt(0)
	s_barrier
	s_waitcnt lgkmcnt(0)
	s_setprio 1
	s_waitcnt lgkmcnt(0)
	v_mfma_f32_16x16x32_bf16 v[94:97], v[136:139], v[18:21], v[94:97]
	v_mfma_f32_16x16x32_bf16 v[18:21], v[162:165], v[18:21], v[90:93]
	v_mfma_f32_16x16x32_bf16 v[118:121], v[218:221], v[34:37], v[18:21]
	v_mfma_f32_16x16x32_bf16 v[18:21], v[136:139], v[22:25], v[172:175]
	v_mfma_f32_16x16x32_bf16 v[110:113], v[206:209], v[38:41], v[18:21]
	v_mfma_f32_16x16x32_bf16 v[18:21], v[162:165], v[22:25], v[176:179]
	v_mfma_f32_16x16x32_bf16 v[106:109], v[218:221], v[38:41], v[18:21]
	v_mfma_f32_16x16x32_bf16 v[18:21], v[136:139], v[50:53], v[78:81]
	v_mfma_f32_16x16x32_bf16 v[122:125], v[206:209], v[34:37], v[94:97]
	v_mfma_f32_16x16x32_bf16 v[94:97], v[206:209], v[196:199], v[18:21]
	v_mfma_f32_16x16x32_bf16 v[18:21], v[162:165], v[50:53], v[74:77]
	v_mfma_f32_16x16x32_bf16 v[90:93], v[218:221], v[196:199], v[18:21]
	v_mfma_f32_16x16x32_bf16 v[18:21], v[136:139], v[54:57], v[180:183]
	v_mfma_f32_16x16x32_bf16 v[78:81], v[206:209], v[200:203], v[18:21]
	v_mfma_f32_16x16x32_bf16 v[18:21], v[162:165], v[54:57], v[184:187]
	v_mfma_f32_16x16x32_bf16 v[74:77], v[218:221], v[200:203], v[18:21]
	s_setprio 0
	s_barrier
	ds_read_b128 v[172:175], v148 offset:49152
	ds_read_b128 v[176:179], v148 offset:51200
	ds_read_b128 v[180:183], v149 offset:49152
	ds_read_b128 v[184:187], v149 offset:51200
	ds_read_b128 v[196:199], v148 offset:53248
	ds_read_b128 v[200:203], v148 offset:55296
	ds_read_b128 v[230:233], v149 offset:53248
	ds_read_b128 v[234:237], v149 offset:55296
	s_barrier
	s_waitcnt lgkmcnt(0)
	s_setprio 1
	s_waitcnt lgkmcnt(0)
	v_mfma_f32_16x16x32_bf16 v[18:21], v[2:5], v[172:175], v[62:65]
	v_mfma_f32_16x16x32_bf16 v[54:57], v[6:9], v[180:183], v[18:21]
	v_mfma_f32_16x16x32_bf16 v[18:21], v[158:161], v[172:175], v[58:61]
	v_mfma_f32_16x16x32_bf16 v[50:53], v[192:195], v[180:183], v[18:21]
	v_mfma_f32_16x16x32_bf16 v[18:21], v[2:5], v[176:179], v[222:225]
	v_mfma_f32_16x16x32_bf16 v[38:41], v[6:9], v[184:187], v[18:21]
	v_mfma_f32_16x16x32_bf16 v[18:21], v[158:161], v[176:179], v[226:229]
	v_mfma_f32_16x16x32_bf16 v[34:37], v[192:195], v[184:187], v[18:21]
	v_mfma_f32_16x16x32_bf16 v[18:21], v[2:5], v[196:199], v[46:49]
	v_mfma_f32_16x16x32_bf16 v[2:5], v[2:5], v[200:203], v[140:143]
	v_mfma_f32_16x16x32_bf16 v[22:25], v[6:9], v[230:233], v[18:21]
	v_mfma_f32_16x16x32_bf16 v[18:21], v[158:161], v[196:199], v[42:45]
	v_mfma_f32_16x16x32_bf16 v[6:9], v[6:9], v[234:237], v[2:5]
	v_mfma_f32_16x16x32_bf16 v[2:5], v[158:161], v[200:203], v[144:147]
	v_mfma_f32_16x16x32_bf16 v[18:21], v[192:195], v[230:233], v[18:21]
	v_mfma_f32_16x16x32_bf16 v[2:5], v[192:195], v[234:237], v[2:5]
	s_setprio 0
	s_setprio 1
	v_mfma_f32_16x16x32_bf16 v[26:29], v[162:165], v[172:175], v[26:29]
	v_mfma_f32_16x16x32_bf16 v[58:61], v[218:221], v[180:183], v[26:29]
	v_mfma_f32_16x16x32_bf16 v[26:29], v[136:139], v[176:179], v[150:153]
	v_mfma_f32_16x16x32_bf16 v[46:49], v[206:209], v[184:187], v[26:29]
	v_mfma_f32_16x16x32_bf16 v[26:29], v[162:165], v[176:179], v[168:171]
	v_mfma_f32_16x16x32_bf16 v[10:13], v[162:165], v[196:199], v[10:13]
	v_mfma_f32_16x16x32_bf16 v[30:33], v[136:139], v[172:175], v[30:33]
	v_mfma_f32_16x16x32_bf16 v[42:45], v[218:221], v[184:187], v[26:29]
	v_mfma_f32_16x16x32_bf16 v[14:17], v[136:139], v[196:199], v[14:17]
	v_mfma_f32_16x16x32_bf16 v[26:29], v[218:221], v[230:233], v[10:13]
	v_mfma_f32_16x16x32_bf16 v[10:13], v[136:139], v[200:203], v[188:191]
	v_mfma_f32_16x16x32_bf16 v[62:65], v[206:209], v[180:183], v[30:33]
	v_mfma_f32_16x16x32_bf16 v[30:33], v[206:209], v[230:233], v[14:17]
	v_mfma_f32_16x16x32_bf16 v[14:17], v[206:209], v[234:237], v[10:13]
	v_mfma_f32_16x16x32_bf16 v[10:13], v[162:165], v[200:203], v[154:157]
	v_mfma_f32_16x16x32_bf16 v[10:13], v[218:221], v[234:237], v[10:13]
	s_setprio 0
	s_cmpk_gt_u32 s0, 0xff
	s_barrier
	s_cbranch_scc1 .LBB0_112
	s_barrier

.LBB0_114:
	v_mov_b64_e32 v[2:3], s[6:7]
	flat_load_dwordx2 v[134:135], v[2:3] offset:160
	s_load_dwordx2 s[100:101], s[78:79], 0xa0
	v_mov_b32_e32 v19, v204
	s_ashr_i32 s9, s8, 31
	v_lshrrev_b32_e32 v20, 4, v19
	v_xor_b32_e32 v0, v19, v20
	v_lshlrev_b32_e32 v0, 3, v0
	v_readfirstlane_b32 s0, v19
	v_and_b32_e32 v16, 56, v0
	v_lshlrev_b32_e32 v0, 8, v19
	s_ashr_i32 s27, s0, 6
	v_and_b32_e32 v17, 0xfffff800, v0
	v_or_b32_e32 v0, v16, v17
	v_add_u32_e32 v18, 0x20000, v17
	s_lshl_b64 s[4:5], s[8:9], 12
	s_lshl_b32 s1, s27, 10
	v_or_b32_e32 v4, v16, v18
	s_add_i32 s2, s1, 0x10000
	v_lshlrev_b64 v[14:15], 1, v[0:1]
	v_mov_b32_e32 v5, v1
	s_ashr_i32 s11, s10, 31
	s_mov_b32 m0, s2
	v_lshlrev_b64 v[22:23], 1, v[4:5]
	s_add_i32 s3, s1, 0x12000
	s_lshl_b64 s[12:13], s[10:11], 12
	s_or_b32 s24, s8, 0x80
	s_ashr_i32 s25, s24, 31
	s_add_i32 s11, s1, 0x2000
	s_lshl_b64 s[24:25], s[24:25], 12
	s_or_b32 s30, s10, 0x80
	s_add_i32 s23, s1, 0x14000
	s_ashr_i32 s31, s30, 31
	s_lshl_b64 s[30:31], s[30:31], 12
	s_add_i32 s26, s1, 0x6000
	s_ashr_i32 s28, s0, 8
	s_waitcnt vmcnt(0) lgkmcnt(0)
	v_lshl_add_u64 v[10:11], v[134:135], 0, s[94:95]
	v_lshl_add_u64 v[6:7], v[10:11], 0, s[4:5]
	v_lshl_add_u64 v[2:3], v[6:7], 0, v[14:15]
	global_load_lds_dwordx4 v[2:3], off
	v_lshl_add_u64 v[4:5], v[6:7], 0, v[22:23]
	s_mov_b32 m0, s3
	v_lshl_add_u64 v[132:133], v[134:135], 0, s[12:13]
	global_load_lds_dwordx4 v[4:5], off
	v_lshl_add_u64 v[8:9], v[132:133], 0, v[14:15]
	s_mov_b32 m0, s1
	v_lshl_add_u64 v[6:7], v[132:133], 0, v[22:23]
	global_load_lds_dwordx4 v[8:9], off
	s_mov_b32 m0, s11
	v_lshl_add_u64 v[10:11], v[10:11], 0, s[24:25]
	global_load_lds_dwordx4 v[6:7], off
	v_lshl_add_u64 v[12:13], v[10:11], 0, v[14:15]
	s_mov_b32 m0, s23
	s_add_i32 s24, s1, 0x16000
	global_load_lds_dwordx4 v[12:13], off
	v_lshl_add_u64 v[10:11], v[10:11], 0, v[22:23]
	s_mov_b32 m0, s24
	v_lshl_add_u64 v[24:25], v[134:135], 0, s[30:31]
	s_add_i32 s25, s1, 0x4000
	global_load_lds_dwordx4 v[10:11], off
	v_lshl_add_u64 v[138:139], v[24:25], 0, v[14:15]
	s_mov_b32 m0, s25
	v_lshl_add_u64 v[136:137], v[24:25], 0, v[22:23]
	global_load_lds_dwordx4 v[138:139], off
	s_mov_b32 m0, s26
	s_cmp_lg_u32 s28, 1
	global_load_lds_dwordx4 v[136:137], off
	s_cbranch_scc1 .LBB0_116
	s_barrier
.LBB0_116:
	s_lshl_b32 s27, s27, 5
	v_and_b32_e32 v0, 15, v19
	s_and_b32 s27, s27, 0x60
	v_lshlrev_b32_e32 v14, 7, v0
	v_or_b32_e32 v0, s27, v0
	s_add_i32 s27, s1, 0x18000
	s_mov_b64 s[34:35], 0x80
	v_lshl_or_b32 v14, s28, 13, v14
	v_lshl_add_u64 v[2:3], v[2:3], 0, s[34:35]
	s_mov_b32 m0, s27
	s_add_i32 s28, s1, 0x1a000
	s_waitcnt vmcnt(4)
	s_barrier
	global_load_lds_dwordx4 v[2:3], off
	v_lshl_add_u64 v[2:3], v[4:5], 0, s[34:35]
	s_mov_b32 m0, s28
	s_add_i32 s29, s1, 0x8000
	global_load_lds_dwordx4 v[2:3], off
	v_lshl_add_u64 v[2:3], v[8:9], 0, s[34:35]
	s_mov_b32 m0, s29
	s_add_i32 s30, s1, 0xa000
	global_load_lds_dwordx4 v[2:3], off
	v_lshl_add_u64 v[2:3], v[6:7], 0, s[34:35]
	s_mov_b32 m0, s30
	s_add_i32 s31, s1, 0x1c000
	global_load_lds_dwordx4 v[2:3], off
	v_lshl_add_u64 v[2:3], v[12:13], 0, s[34:35]
	s_mov_b32 m0, s31
	v_and_b32_e32 v15, 3, v20
	global_load_lds_dwordx4 v[2:3], off
	v_lshl_add_u64 v[2:3], v[10:11], 0, s[34:35]
	s_add_i32 s34, s1, 0x1e000
	s_mov_b32 m0, s34
	v_bfe_u32 v19, v19, 1, 3
	global_load_lds_dwordx4 v[2:3], off
	v_bitop3_b32 v20, v20, v19, 3 bitop3:0x6c
	v_bitop3_b32 v15, v15, v19, 4 bitop3:0x36
	v_lshlrev_b32_e32 v20, 4, v20
	v_lshlrev_b32_e32 v15, 4, v15
	v_lshlrev_b32_e32 v0, 7, v0
	v_or_b32_e32 v150, v0, v20
	v_or_b32_e32 v151, v0, v15
	s_waitcnt vmcnt(6)
	v_add_u32_e32 v0, v18, v16
	v_lshlrev_b64 v[2:3], 1, v[0:1]
	v_add_u32_e32 v0, v17, v16
	v_lshl_add_u64 v[140:141], s[12:13], 0, v[2:3]
	v_lshlrev_b64 v[4:5], 1, v[0:1]
	v_lshl_add_u64 v[144:145], s[4:5], 0, v[2:3]
	v_mov_b32_e32 v2, 0
	v_or_b32_e32 v148, v20, v14
	v_or_b32_e32 v149, v15, v14
	s_barrier
	v_lshl_add_u64 v[142:143], s[12:13], 0, v[4:5]
	v_lshl_add_u64 v[146:147], s[4:5], 0, v[4:5]
	s_mov_b32 s4, -2
	v_mov_b32_e32 v3, v2
	v_mov_b32_e32 v4, v2
	v_mov_b32_e32 v5, v2
	v_mov_b32_e32 v6, v2
	v_mov_b32_e32 v7, v2
	v_mov_b32_e32 v8, v2
	v_mov_b32_e32 v9, v2
	v_mov_b32_e32 v10, v2
	v_mov_b32_e32 v11, v2
	v_mov_b32_e32 v12, v2
	v_mov_b32_e32 v13, v2
	v_mov_b32_e32 v14, v2
	v_mov_b32_e32 v15, v2
	v_mov_b32_e32 v16, v2
	v_mov_b32_e32 v17, v2
	v_mov_b32_e32 v18, v2
	v_mov_b32_e32 v19, v2
	v_mov_b32_e32 v20, v2
	v_mov_b32_e32 v21, v2
	v_mov_b32_e32 v22, v2
	v_mov_b32_e32 v23, v2
	v_mov_b32_e32 v24, v2
	v_mov_b32_e32 v25, v2
	v_mov_b32_e32 v26, v2
	v_mov_b32_e32 v27, v2
	v_mov_b32_e32 v28, v2
	v_mov_b32_e32 v29, v2
	v_mov_b32_e32 v30, v2
	v_mov_b32_e32 v31, v2
	v_mov_b32_e32 v32, v2
	v_mov_b32_e32 v33, v2
	v_mov_b32_e32 v34, v2
	v_mov_b32_e32 v35, v2
	v_mov_b32_e32 v36, v2
	v_mov_b32_e32 v37, v2
	v_mov_b32_e32 v38, v2
	v_mov_b32_e32 v39, v2
	v_mov_b32_e32 v40, v2
	v_mov_b32_e32 v41, v2
	v_mov_b32_e32 v42, v2
	v_mov_b32_e32 v43, v2
	v_mov_b32_e32 v44, v2
	v_mov_b32_e32 v45, v2
	v_mov_b32_e32 v46, v2
	v_mov_b32_e32 v47, v2
	v_mov_b32_e32 v48, v2
	v_mov_b32_e32 v49, v2
	v_mov_b32_e32 v50, v2
	v_mov_b32_e32 v51, v2
	v_mov_b32_e32 v52, v2
	v_mov_b32_e32 v53, v2
	v_mov_b32_e32 v54, v2
	v_mov_b32_e32 v55, v2
	v_mov_b32_e32 v56, v2
	v_mov_b32_e32 v57, v2
	v_mov_b32_e32 v58, v2
	v_mov_b32_e32 v59, v2
	v_mov_b32_e32 v60, v2
	v_mov_b32_e32 v61, v2
	v_mov_b32_e32 v62, v2
	v_mov_b32_e32 v63, v2
	v_mov_b32_e32 v64, v2
	v_mov_b32_e32 v65, v2
	v_mov_b32_e32 v66, v2
	v_mov_b32_e32 v67, v2
	v_mov_b32_e32 v68, v2
	v_mov_b32_e32 v69, v2
	v_mov_b32_e32 v70, v2
	v_mov_b32_e32 v71, v2
	v_mov_b32_e32 v72, v2
	v_mov_b32_e32 v73, v2
	v_mov_b32_e32 v74, v2
	v_mov_b32_e32 v75, v2
	v_mov_b32_e32 v76, v2
	v_mov_b32_e32 v77, v2
	v_mov_b32_e32 v78, v2
	v_mov_b32_e32 v79, v2
	v_mov_b32_e32 v80, v2
	v_mov_b32_e32 v81, v2
	v_mov_b32_e32 v82, v2
	v_mov_b32_e32 v83, v2
	v_mov_b32_e32 v84, v2
	v_mov_b32_e32 v85, v2
	v_mov_b32_e32 v86, v2
	v_mov_b32_e32 v87, v2
	v_mov_b32_e32 v88, v2
	v_mov_b32_e32 v89, v2
	v_mov_b32_e32 v90, v2
	v_mov_b32_e32 v91, v2
	v_mov_b32_e32 v92, v2
	v_mov_b32_e32 v93, v2
	v_mov_b32_e32 v94, v2
	v_mov_b32_e32 v95, v2
	v_mov_b32_e32 v96, v2
	v_mov_b32_e32 v97, v2
	v_mov_b32_e32 v98, v2
	v_mov_b32_e32 v99, v2
	v_mov_b32_e32 v100, v2
	v_mov_b32_e32 v101, v2
	v_mov_b32_e32 v102, v2
	v_mov_b32_e32 v103, v2
	v_mov_b32_e32 v104, v2
	v_mov_b32_e32 v105, v2
	v_mov_b32_e32 v106, v2
	v_mov_b32_e32 v107, v2
	v_mov_b32_e32 v108, v2
	v_mov_b32_e32 v109, v2
	v_mov_b32_e32 v110, v2
	v_mov_b32_e32 v111, v2
	v_mov_b32_e32 v112, v2
	v_mov_b32_e32 v113, v2
	v_mov_b32_e32 v114, v2
	v_mov_b32_e32 v115, v2
	v_mov_b32_e32 v116, v2
	v_mov_b32_e32 v117, v2
	v_mov_b32_e32 v118, v2
	v_mov_b32_e32 v119, v2
	v_mov_b32_e32 v120, v2
	v_mov_b32_e32 v121, v2
	v_mov_b32_e32 v122, v2
	v_mov_b32_e32 v123, v2
	v_mov_b32_e32 v124, v2
	v_mov_b32_e32 v125, v2
	v_mov_b32_e32 v126, v2
	v_mov_b32_e32 v127, v2
	v_mov_b32_e32 v128, v2
	v_mov_b32_e32 v129, v2
	s_mov_b64 s[36:37], 0x82d4900
	s_mov_b64 s[38:39], 0x8254980
	s_mov_b64 s[40:41], 0x82d4980
	s_waitcnt lgkmcnt(0)
	s_sub_u32 s100, s100, 0x40000000
	s_subb_u32 s101, s101, 0
	s_mov_b64 vcc, s[100:101]
	v_lshl_add_u64 v[210:211], v[134:135], 0, v[142:143]
	v_subrev_u32_e32 v210, vcc_lo, v210
	v_lshl_add_u64 v[214:215], v[134:135], 0, v[140:141]
	v_subrev_u32_e32 v214, vcc_lo, v214
	v_lshl_add_u64 v[242:243], v[134:135], 0, v[146:147]
	v_subrev_u32_e32 v242, vcc_lo, v242
	v_lshl_add_u64 v[244:245], v[134:135], 0, v[144:145]
	v_subrev_u32_e32 v244, vcc_lo, v244
	v_add_u32_e32 v211, 0x10000, v150
	v_add_u32_e32 v215, 0x10000, v151
.LBB0_117:
	ds_read_b128 v[160:163], v211
	ds_read_b128 v[164:167], v215
	ds_read_b128 v[168:171], v211 offset:2048
	ds_read_b128 v[172:175], v215 offset:2048
	s_add_i32 s12, s1, 0xc000
	s_mov_b32 m0, s12
	s_add_i32 s5, s1, 0xe000
	ds_read_b128 v[176:179], v148
	ds_read_b128 v[180:183], v148 offset:2048
	ds_read_b128 v[184:187], v149
	ds_read_b128 v[188:191], v149 offset:2048
	ds_read_b128 v[192:195], v148 offset:4096
	ds_read_b128 v[196:199], v148 offset:6144
	ds_read_b128 v[200:203], v149 offset:4096
	ds_read_b128 v[206:209], v149 offset:6144
	s_add_u32 s100, vcc_lo, s50
	s_addc_u32 s101, vcc_hi, s51
	global_load_lds_dwordx4 v210, s[100:101]
	s_mov_b32 m0, s5
	s_add_u32 s100, vcc_lo, s50
	s_addc_u32 s101, vcc_hi, s51
	global_load_lds_dwordx4 v214, s[100:101]
	s_waitcnt lgkmcnt(8)
	s_waitcnt vmcnt(10)
	s_barrier
	s_waitcnt lgkmcnt(0)
	s_setprio 1
	s_waitcnt lgkmcnt(0)
	v_mfma_f32_16x16x32_bf16 v[126:129], v[160:163], v[176:179], v[126:129]
	v_mfma_f32_16x16x32_bf16 v[122:125], v[168:171], v[176:179], v[122:125]
	v_mfma_f32_16x16x32_bf16 v[118:121], v[160:163], v[180:183], v[118:121]
	v_mfma_f32_16x16x32_bf16 v[114:117], v[168:171], v[180:183], v[114:117]
	v_mfma_f32_16x16x32_bf16 v[110:113], v[160:163], v[192:195], v[110:113]
	v_mfma_f32_16x16x32_bf16 v[106:109], v[168:171], v[192:195], v[106:109]
	v_mfma_f32_16x16x32_bf16 v[102:105], v[160:163], v[196:199], v[102:105]
	v_mfma_f32_16x16x32_bf16 v[98:101], v[168:171], v[196:199], v[98:101]
	v_mfma_f32_16x16x32_bf16 v[126:129], v[164:167], v[184:187], v[126:129]
	v_mfma_f32_16x16x32_bf16 v[122:125], v[172:175], v[184:187], v[122:125]
	v_mfma_f32_16x16x32_bf16 v[118:121], v[164:167], v[188:191], v[118:121]
	v_mfma_f32_16x16x32_bf16 v[114:117], v[172:175], v[188:191], v[114:117]
	v_mfma_f32_16x16x32_bf16 v[110:113], v[164:167], v[200:203], v[110:113]
	v_mfma_f32_16x16x32_bf16 v[106:109], v[172:175], v[200:203], v[106:109]
	v_mfma_f32_16x16x32_bf16 v[102:105], v[164:167], v[206:209], v[102:105]
	v_mfma_f32_16x16x32_bf16 v[98:101], v[172:175], v[206:209], v[98:101]
	s_setprio 0
	s_barrier
	s_mov_b32 m0, s2
	ds_read_b128 v[218:221], v211 offset:16384
	ds_read_b128 v[222:225], v215 offset:16384
	ds_read_b128 v[226:229], v211 offset:18432
	ds_read_b128 v[230:233], v215 offset:18432
	s_add_u32 s100, vcc_lo, s70
	s_addc_u32 s101, vcc_hi, s71
	global_load_lds_dwordx4 v242, s[100:101]
	s_mov_b32 m0, s3
	s_add_u32 s100, vcc_lo, s70
	s_addc_u32 s101, vcc_hi, s71
	global_load_lds_dwordx4 v244, s[100:101]
	s_waitcnt vmcnt(10)
	s_waitcnt lgkmcnt(0)
	s_barrier
	s_waitcnt lgkmcnt(0)
	s_setprio 1
	s_waitcnt lgkmcnt(0)
	v_mfma_f32_16x16x32_bf16 v[94:97], v[218:221], v[176:179], v[94:97]
	v_mfma_f32_16x16x32_bf16 v[90:93], v[226:229], v[176:179], v[90:93]
	v_mfma_f32_16x16x32_bf16 v[86:89], v[218:221], v[180:183], v[86:89]
	v_mfma_f32_16x16x32_bf16 v[82:85], v[226:229], v[180:183], v[82:85]
	v_mfma_f32_16x16x32_bf16 v[78:81], v[218:221], v[192:195], v[78:81]
	v_mfma_f32_16x16x32_bf16 v[74:77], v[226:229], v[192:195], v[74:77]
	v_mfma_f32_16x16x32_bf16 v[70:73], v[218:221], v[196:199], v[70:73]
	v_mfma_f32_16x16x32_bf16 v[66:69], v[226:229], v[196:199], v[66:69]
	v_mfma_f32_16x16x32_bf16 v[94:97], v[222:225], v[184:187], v[94:97]
	v_mfma_f32_16x16x32_bf16 v[90:93], v[230:233], v[184:187], v[90:93]
	v_mfma_f32_16x16x32_bf16 v[86:89], v[222:225], v[188:191], v[86:89]
	v_mfma_f32_16x16x32_bf16 v[82:85], v[230:233], v[188:191], v[82:85]
	v_mfma_f32_16x16x32_bf16 v[78:81], v[222:225], v[200:203], v[78:81]
	v_mfma_f32_16x16x32_bf16 v[74:77], v[230:233], v[200:203], v[74:77]
	v_mfma_f32_16x16x32_bf16 v[70:73], v[222:225], v[206:209], v[70:73]
	v_mfma_f32_16x16x32_bf16 v[66:69], v[230:233], v[206:209], v[66:69]
	s_setprio 0
	s_mov_b32 m0, s1
	s_barrier
	ds_read_b128 v[176:179], v148 offset:16384
	ds_read_b128 v[180:183], v148 offset:18432
	ds_read_b128 v[184:187], v149 offset:16384
	ds_read_b128 v[188:191], v149 offset:18432
	ds_read_b128 v[192:195], v148 offset:20480
	ds_read_b128 v[196:199], v148 offset:22528
	ds_read_b128 v[200:203], v149 offset:20480
	ds_read_b128 v[206:209], v149 offset:22528
	s_add_u32 s100, vcc_lo, s54
	s_addc_u32 s101, vcc_hi, s55
	global_load_lds_dwordx4 v210, s[100:101]
	s_mov_b32 m0, s11
	s_add_u32 s100, vcc_lo, s54
	s_addc_u32 s101, vcc_hi, s55
	global_load_lds_dwordx4 v214, s[100:101]
	s_mov_b32 m0, s23
	s_add_u32 s100, vcc_lo, s36
	s_addc_u32 s101, vcc_hi, s37
	global_load_lds_dwordx4 v242, s[100:101]
	s_mov_b32 m0, s24
	s_add_u32 s100, vcc_lo, s36
	s_addc_u32 s101, vcc_hi, s37
	global_load_lds_dwordx4 v244, s[100:101]
	s_waitcnt vmcnt(10)
	s_waitcnt lgkmcnt(0)
	s_barrier
	s_waitcnt lgkmcnt(0)
	s_setprio 1
	s_waitcnt lgkmcnt(0)
	v_mfma_f32_16x16x32_bf16 v[62:65], v[160:163], v[176:179], v[62:65]
	v_mfma_f32_16x16x32_bf16 v[58:61], v[168:171], v[176:179], v[58:61]
	v_mfma_f32_16x16x32_bf16 v[54:57], v[160:163], v[180:183], v[54:57]
	v_mfma_f32_16x16x32_bf16 v[50:53], v[168:171], v[180:183], v[50:53]
	v_mfma_f32_16x16x32_bf16 v[46:49], v[160:163], v[192:195], v[46:49]
	v_mfma_f32_16x16x32_bf16 v[42:45], v[168:171], v[192:195], v[42:45]
	v_mfma_f32_16x16x32_bf16 v[38:41], v[160:163], v[196:199], v[38:41]
	v_mfma_f32_16x16x32_bf16 v[34:37], v[168:171], v[196:199], v[34:37]
	v_mfma_f32_16x16x32_bf16 v[62:65], v[164:167], v[184:187], v[62:65]
	v_mfma_f32_16x16x32_bf16 v[58:61], v[172:175], v[184:187], v[58:61]
	v_mfma_f32_16x16x32_bf16 v[54:57], v[164:167], v[188:191], v[54:57]
	v_mfma_f32_16x16x32_bf16 v[50:53], v[172:175], v[188:191], v[50:53]
	v_mfma_f32_16x16x32_bf16 v[46:49], v[164:167], v[200:203], v[46:49]
	v_mfma_f32_16x16x32_bf16 v[42:45], v[172:175], v[200:203], v[42:45]
	v_mfma_f32_16x16x32_bf16 v[38:41], v[164:167], v[206:209], v[38:41]
	v_mfma_f32_16x16x32_bf16 v[34:37], v[172:175], v[206:209], v[34:37]
	v_mfma_f32_16x16x32_bf16 v[30:33], v[218:221], v[176:179], v[30:33]
	v_mfma_f32_16x16x32_bf16 v[26:29], v[226:229], v[176:179], v[26:29]
	v_mfma_f32_16x16x32_bf16 v[22:25], v[218:221], v[180:183], v[22:25]
	v_mfma_f32_16x16x32_bf16 v[18:21], v[226:229], v[180:183], v[18:21]
	v_mfma_f32_16x16x32_bf16 v[14:17], v[218:221], v[192:195], v[14:17]
	v_mfma_f32_16x16x32_bf16 v[10:13], v[226:229], v[192:195], v[10:13]
	v_mfma_f32_16x16x32_bf16 v[6:9], v[218:221], v[196:199], v[6:9]
	v_mfma_f32_16x16x32_bf16 v[2:5], v[226:229], v[196:199], v[2:5]
	v_mfma_f32_16x16x32_bf16 v[30:33], v[222:225], v[184:187], v[30:33]
	v_mfma_f32_16x16x32_bf16 v[26:29], v[230:233], v[184:187], v[26:29]
	v_mfma_f32_16x16x32_bf16 v[22:25], v[222:225], v[188:191], v[22:25]
	v_mfma_f32_16x16x32_bf16 v[18:21], v[230:233], v[188:191], v[18:21]
	v_mfma_f32_16x16x32_bf16 v[14:17], v[222:225], v[200:203], v[14:17]
	v_mfma_f32_16x16x32_bf16 v[10:13], v[230:233], v[200:203], v[10:13]
	v_mfma_f32_16x16x32_bf16 v[6:9], v[222:225], v[206:209], v[6:9]
	v_mfma_f32_16x16x32_bf16 v[2:5], v[230:233], v[206:209], v[2:5]
	s_setprio 0
	s_barrier
	ds_read_b128 v[168:171], v211 offset:32768
	ds_read_b128 v[172:175], v215 offset:32768
	ds_read_b128 v[176:179], v211 offset:34816
	ds_read_b128 v[180:183], v215 offset:34816
	s_mov_b32 m0, s25
	ds_read_b128 v[184:187], v148 offset:32768
	ds_read_b128 v[188:191], v148 offset:34816
	ds_read_b128 v[192:195], v149 offset:32768
	ds_read_b128 v[196:199], v149 offset:34816
	ds_read_b128 v[200:203], v148 offset:36864
	ds_read_b128 v[206:209], v148 offset:38912
	ds_read_b128 v[218:221], v149 offset:36864
	ds_read_b128 v[222:225], v149 offset:38912
	s_add_u32 s100, vcc_lo, s58
	s_addc_u32 s101, vcc_hi, s59
	global_load_lds_dwordx4 v210, s[100:101]
	s_mov_b32 m0, s26
	s_add_u32 s100, vcc_lo, s58
	s_addc_u32 s101, vcc_hi, s59
	global_load_lds_dwordx4 v214, s[100:101]
	s_waitcnt lgkmcnt(8)
	s_waitcnt vmcnt(10)
	s_barrier
	s_waitcnt lgkmcnt(0)
	s_setprio 1
	s_waitcnt lgkmcnt(0)
	v_mfma_f32_16x16x32_bf16 v[126:129], v[168:171], v[184:187], v[126:129]
	v_mfma_f32_16x16x32_bf16 v[122:125], v[176:179], v[184:187], v[122:125]
	v_mfma_f32_16x16x32_bf16 v[118:121], v[168:171], v[188:191], v[118:121]
	v_mfma_f32_16x16x32_bf16 v[114:117], v[176:179], v[188:191], v[114:117]
	v_mfma_f32_16x16x32_bf16 v[110:113], v[168:171], v[200:203], v[110:113]
	v_mfma_f32_16x16x32_bf16 v[106:109], v[176:179], v[200:203], v[106:109]
	v_mfma_f32_16x16x32_bf16 v[102:105], v[168:171], v[206:209], v[102:105]
	v_mfma_f32_16x16x32_bf16 v[98:101], v[176:179], v[206:209], v[98:101]
	v_mfma_f32_16x16x32_bf16 v[126:129], v[172:175], v[192:195], v[126:129]
	v_mfma_f32_16x16x32_bf16 v[122:125], v[180:183], v[192:195], v[122:125]
	v_mfma_f32_16x16x32_bf16 v[118:121], v[172:175], v[196:199], v[118:121]
	v_mfma_f32_16x16x32_bf16 v[114:117], v[180:183], v[196:199], v[114:117]
	v_mfma_f32_16x16x32_bf16 v[110:113], v[172:175], v[218:221], v[110:113]
	v_mfma_f32_16x16x32_bf16 v[106:109], v[180:183], v[218:221], v[106:109]
	v_mfma_f32_16x16x32_bf16 v[102:105], v[172:175], v[222:225], v[102:105]
	v_mfma_f32_16x16x32_bf16 v[98:101], v[180:183], v[222:225], v[98:101]
	s_setprio 0
	s_barrier
	s_mov_b32 m0, s27
	ds_read_b128 v[226:229], v211 offset:49152
	ds_read_b128 v[230:233], v215 offset:49152
	ds_read_b128 v[234:237], v211 offset:51200
	ds_read_b128 v[238:241], v215 offset:51200
	s_add_u32 s100, vcc_lo, s38
	s_addc_u32 s101, vcc_hi, s39
	global_load_lds_dwordx4 v242, s[100:101]
	s_mov_b32 m0, s28
	s_add_u32 s100, vcc_lo, s38
	s_addc_u32 s101, vcc_hi, s39
	global_load_lds_dwordx4 v244, s[100:101]
	s_waitcnt vmcnt(10)
	s_waitcnt lgkmcnt(0)
	s_barrier
	s_waitcnt lgkmcnt(0)
	s_setprio 1
	s_waitcnt lgkmcnt(0)
	v_mfma_f32_16x16x32_bf16 v[94:97], v[226:229], v[184:187], v[94:97]
	v_mfma_f32_16x16x32_bf16 v[90:93], v[234:237], v[184:187], v[90:93]
	v_mfma_f32_16x16x32_bf16 v[86:89], v[226:229], v[188:191], v[86:89]
	v_mfma_f32_16x16x32_bf16 v[82:85], v[234:237], v[188:191], v[82:85]
	v_mfma_f32_16x16x32_bf16 v[78:81], v[226:229], v[200:203], v[78:81]
	v_mfma_f32_16x16x32_bf16 v[74:77], v[234:237], v[200:203], v[74:77]
	v_mfma_f32_16x16x32_bf16 v[70:73], v[226:229], v[206:209], v[70:73]
	v_mfma_f32_16x16x32_bf16 v[66:69], v[234:237], v[206:209], v[66:69]
	v_mfma_f32_16x16x32_bf16 v[94:97], v[230:233], v[192:195], v[94:97]
	v_mfma_f32_16x16x32_bf16 v[90:93], v[238:241], v[192:195], v[90:93]
	v_mfma_f32_16x16x32_bf16 v[86:89], v[230:233], v[196:199], v[86:89]
	v_mfma_f32_16x16x32_bf16 v[82:85], v[238:241], v[196:199], v[82:85]
	v_mfma_f32_16x16x32_bf16 v[78:81], v[230:233], v[218:221], v[78:81]
	v_mfma_f32_16x16x32_bf16 v[74:77], v[238:241], v[218:221], v[74:77]
	v_mfma_f32_16x16x32_bf16 v[70:73], v[230:233], v[222:225], v[70:73]
	v_mfma_f32_16x16x32_bf16 v[66:69], v[238:241], v[222:225], v[66:69]
	s_setprio 0
	s_mov_b32 m0, s29
	s_barrier
	ds_read_b128 v[184:187], v148 offset:49152
	ds_read_b128 v[188:191], v148 offset:51200
	ds_read_b128 v[192:195], v149 offset:49152
	ds_read_b128 v[196:199], v149 offset:51200
	ds_read_b128 v[200:203], v148 offset:53248
	ds_read_b128 v[206:209], v148 offset:55296
	ds_read_b128 v[218:221], v149 offset:53248
	ds_read_b128 v[222:225], v149 offset:55296
	s_add_u32 s100, vcc_lo, s62
	s_addc_u32 s101, vcc_hi, s63
	global_load_lds_dwordx4 v210, s[100:101]
	s_mov_b32 m0, s30
	s_add_u32 s100, vcc_lo, s62
	s_addc_u32 s101, vcc_hi, s63
	global_load_lds_dwordx4 v214, s[100:101]
	s_mov_b32 m0, s31
	s_add_u32 s100, vcc_lo, s40
	s_addc_u32 s101, vcc_hi, s41
	global_load_lds_dwordx4 v242, s[100:101]
	s_mov_b32 m0, s34
	s_add_u32 s100, vcc_lo, s40
	s_addc_u32 s101, vcc_hi, s41
	global_load_lds_dwordx4 v244, s[100:101]
	s_waitcnt vmcnt(10)
	s_waitcnt lgkmcnt(0)
	s_barrier
	s_waitcnt lgkmcnt(0)
	s_setprio 1
	s_waitcnt lgkmcnt(0)
	v_mfma_f32_16x16x32_bf16 v[62:65], v[168:171], v[184:187], v[62:65]
	v_mfma_f32_16x16x32_bf16 v[58:61], v[176:179], v[184:187], v[58:61]
	v_mfma_f32_16x16x32_bf16 v[54:57], v[168:171], v[188:191], v[54:57]
	v_mfma_f32_16x16x32_bf16 v[50:53], v[176:179], v[188:191], v[50:53]
	v_mfma_f32_16x16x32_bf16 v[46:49], v[168:171], v[200:203], v[46:49]
	v_mfma_f32_16x16x32_bf16 v[42:45], v[176:179], v[200:203], v[42:45]
	v_mfma_f32_16x16x32_bf16 v[38:41], v[168:171], v[206:209], v[38:41]
	v_mfma_f32_16x16x32_bf16 v[34:37], v[176:179], v[206:209], v[34:37]
	v_mfma_f32_16x16x32_bf16 v[62:65], v[172:175], v[192:195], v[62:65]
	v_mfma_f32_16x16x32_bf16 v[58:61], v[180:183], v[192:195], v[58:61]
	v_mfma_f32_16x16x32_bf16 v[54:57], v[172:175], v[196:199], v[54:57]
	v_mfma_f32_16x16x32_bf16 v[50:53], v[180:183], v[196:199], v[50:53]
	v_mfma_f32_16x16x32_bf16 v[46:49], v[172:175], v[218:221], v[46:49]
	v_mfma_f32_16x16x32_bf16 v[42:45], v[180:183], v[218:221], v[42:45]
	v_mfma_f32_16x16x32_bf16 v[38:41], v[172:175], v[222:225], v[38:41]
	v_mfma_f32_16x16x32_bf16 v[34:37], v[180:183], v[222:225], v[34:37]
	v_mfma_f32_16x16x32_bf16 v[30:33], v[226:229], v[184:187], v[30:33]
	v_mfma_f32_16x16x32_bf16 v[26:29], v[234:237], v[184:187], v[26:29]
	v_mfma_f32_16x16x32_bf16 v[22:25], v[226:229], v[188:191], v[22:25]
	v_mfma_f32_16x16x32_bf16 v[18:21], v[234:237], v[188:191], v[18:21]
	v_mfma_f32_16x16x32_bf16 v[14:17], v[226:229], v[200:203], v[14:17]
	v_mfma_f32_16x16x32_bf16 v[10:13], v[234:237], v[200:203], v[10:13]
	v_mfma_f32_16x16x32_bf16 v[6:9], v[226:229], v[206:209], v[6:9]
	v_mfma_f32_16x16x32_bf16 v[2:5], v[234:237], v[206:209], v[2:5]
	v_mfma_f32_16x16x32_bf16 v[30:33], v[230:233], v[192:195], v[30:33]
	v_mfma_f32_16x16x32_bf16 v[26:29], v[238:241], v[192:195], v[26:29]
	v_mfma_f32_16x16x32_bf16 v[22:25], v[230:233], v[196:199], v[22:25]
	v_mfma_f32_16x16x32_bf16 v[18:21], v[238:241], v[196:199], v[18:21]
	v_mfma_f32_16x16x32_bf16 v[14:17], v[230:233], v[218:221], v[14:17]
	v_mfma_f32_16x16x32_bf16 v[10:13], v[238:241], v[218:221], v[10:13]
	v_mfma_f32_16x16x32_bf16 v[6:9], v[230:233], v[222:225], v[6:9]
	v_mfma_f32_16x16x32_bf16 v[2:5], v[238:241], v[222:225], v[2:5]
	s_setprio 0
	s_add_u32 vcc_lo, vcc_lo, s54
	s_addc_u32 vcc_hi, vcc_hi, s55
	s_add_i32 s4, s4, 2
	s_cmp_lt_u32 s4, 28
	v_lshl_add_u64 v[134:135], v[134:135], 0, s[54:55]
	s_barrier
	s_cbranch_scc1 .LBB0_117
	s_waitcnt vmcnt(6)
	v_or_b32_e32 v0, 0x10000, v150
	v_add_u32_e32 v153, 0x10800, v150
	v_or_b32_e32 v152, 0x10000, v151
	v_add_u32_e32 v154, 0x10800, v151
	v_or_b32_e32 v155, 0x14000, v150
	v_add_u32_e32 v157, 0x14800, v150
	v_or_b32_e32 v156, 0x14000, v151
	v_add_u32_e32 v158, 0x14800, v151
	v_or_b32_e32 v159, 0x18000, v150
	v_add_u32_e32 v161, 0x18800, v150
	v_or_b32_e32 v160, 0x18000, v151
	v_add_u32_e32 v162, 0x18800, v151
	v_or_b32_e32 v163, 0x1c000, v150
	v_add_u32_e32 v165, 0x1c800, v150
	v_or_b32_e32 v164, 0x1c000, v151
	v_add_u32_e32 v166, 0x1c800, v151
	s_mov_b64 s[2:3], 0xf80
	s_mov_b32 m0, s12
	v_lshl_add_u64 v[134:135], v[138:139], 0, s[2:3]
	ds_read_b128 v[140:143], v0
	ds_read_b128 v[144:147], v152
	ds_read_b128 v[150:153], v153
	ds_read_b128 v[168:171], v154
	ds_read_b128 v[172:175], v148
	ds_read_b128 v[176:179], v148 offset:2048
	ds_read_b128 v[180:183], v149
	ds_read_b128 v[184:187], v149 offset:2048
	ds_read_b128 v[188:191], v148 offset:4096
	ds_read_b128 v[192:195], v148 offset:6144
	ds_read_b128 v[196:199], v149 offset:4096
	ds_read_b128 v[200:203], v149 offset:6144
	global_load_lds_dwordx4 v[134:135], off
	v_lshl_add_u64 v[134:135], v[136:137], 0, s[2:3]
	s_mov_b32 m0, s5
	s_nop 0
	global_load_lds_dwordx4 v[134:135], off
	s_barrier
	s_waitcnt lgkmcnt(0)
	s_setprio 1
	s_waitcnt lgkmcnt(0)
	v_mfma_f32_16x16x32_bf16 v[126:129], v[140:143], v[172:175], v[126:129]
	v_mfma_f32_16x16x32_bf16 v[122:125], v[150:153], v[172:175], v[122:125]
	v_mfma_f32_16x16x32_bf16 v[118:121], v[140:143], v[176:179], v[118:121]
	v_mfma_f32_16x16x32_bf16 v[110:113], v[140:143], v[188:191], v[110:113]
	v_mfma_f32_16x16x32_bf16 v[106:109], v[150:153], v[188:191], v[106:109]
	v_mfma_f32_16x16x32_bf16 v[126:129], v[144:147], v[180:183], v[126:129]
	v_mfma_f32_16x16x32_bf16 v[122:125], v[168:171], v[180:183], v[122:125]
	v_mfma_f32_16x16x32_bf16 v[118:121], v[144:147], v[184:187], v[118:121]
	v_mfma_f32_16x16x32_bf16 v[114:117], v[150:153], v[176:179], v[114:117]
	v_mfma_f32_16x16x32_bf16 v[110:113], v[144:147], v[196:199], v[110:113]
	v_mfma_f32_16x16x32_bf16 v[106:109], v[168:171], v[196:199], v[106:109]
	v_mfma_f32_16x16x32_bf16 v[102:105], v[140:143], v[192:195], v[102:105]
	v_mfma_f32_16x16x32_bf16 v[98:101], v[150:153], v[192:195], v[98:101]
	v_mfma_f32_16x16x32_bf16 v[134:137], v[168:171], v[184:187], v[114:117]
	v_mfma_f32_16x16x32_bf16 v[206:209], v[144:147], v[200:203], v[102:105]
	v_mfma_f32_16x16x32_bf16 v[218:221], v[168:171], v[200:203], v[98:101]
	s_setprio 0
	s_barrier
	s_nop 2
	ds_read_b128 v[98:101], v155
	ds_read_b128 v[102:105], v156
	ds_read_b128 v[114:117], v157
	ds_read_b128 v[154:157], v158
	s_barrier
	s_waitcnt lgkmcnt(0)
	s_setprio 1
	s_waitcnt lgkmcnt(0)
	v_mfma_f32_16x16x32_bf16 v[94:97], v[98:101], v[172:175], v[94:97]
	v_mfma_f32_16x16x32_bf16 v[90:93], v[114:117], v[172:175], v[90:93]
	v_mfma_f32_16x16x32_bf16 v[78:81], v[98:101], v[188:191], v[78:81]
	v_mfma_f32_16x16x32_bf16 v[74:77], v[114:117], v[188:191], v[74:77]
	v_mfma_f32_16x16x32_bf16 v[94:97], v[102:105], v[180:183], v[94:97]
	v_mfma_f32_16x16x32_bf16 v[90:93], v[154:157], v[180:183], v[90:93]
	v_mfma_f32_16x16x32_bf16 v[86:89], v[98:101], v[176:179], v[86:89]
	v_mfma_f32_16x16x32_bf16 v[82:85], v[114:117], v[176:179], v[82:85]
	v_mfma_f32_16x16x32_bf16 v[78:81], v[102:105], v[196:199], v[78:81]
	v_mfma_f32_16x16x32_bf16 v[74:77], v[154:157], v[196:199], v[74:77]
	v_mfma_f32_16x16x32_bf16 v[70:73], v[98:101], v[192:195], v[70:73]
	v_mfma_f32_16x16x32_bf16 v[66:69], v[114:117], v[192:195], v[66:69]
	v_mfma_f32_16x16x32_bf16 v[172:175], v[102:105], v[184:187], v[86:89]
	v_mfma_f32_16x16x32_bf16 v[176:179], v[154:157], v[184:187], v[82:85]
	v_mfma_f32_16x16x32_bf16 v[180:183], v[102:105], v[200:203], v[70:73]
	v_mfma_f32_16x16x32_bf16 v[184:187], v[154:157], v[200:203], v[66:69]
	s_setprio 0
	s_barrier
	s_nop 1
	ds_read_b128 v[66:69], v148 offset:16384
	ds_read_b128 v[70:73], v148 offset:18432
	ds_read_b128 v[82:85], v149 offset:16384
	ds_read_b128 v[86:89], v149 offset:18432
	ds_read_b128 v[188:191], v148 offset:20480
	ds_read_b128 v[192:195], v148 offset:22528
	ds_read_b128 v[196:199], v149 offset:20480
	ds_read_b128 v[200:203], v149 offset:22528
	s_waitcnt vmcnt(4)
	s_barrier
	s_waitcnt lgkmcnt(0)
	s_setprio 1
	s_waitcnt lgkmcnt(0)
	v_mfma_f32_16x16x32_bf16 v[62:65], v[140:143], v[66:69], v[62:65]
	v_mfma_f32_16x16x32_bf16 v[58:61], v[150:153], v[66:69], v[58:61]
	v_mfma_f32_16x16x32_bf16 v[46:49], v[140:143], v[188:191], v[46:49]
	v_mfma_f32_16x16x32_bf16 v[42:45], v[150:153], v[188:191], v[42:45]
	v_mfma_f32_16x16x32_bf16 v[62:65], v[144:147], v[82:85], v[62:65]
	v_mfma_f32_16x16x32_bf16 v[58:61], v[168:171], v[82:85], v[58:61]
	v_mfma_f32_16x16x32_bf16 v[54:57], v[140:143], v[70:73], v[54:57]
	v_mfma_f32_16x16x32_bf16 v[50:53], v[150:153], v[70:73], v[50:53]
	v_mfma_f32_16x16x32_bf16 v[46:49], v[144:147], v[196:199], v[46:49]
	v_mfma_f32_16x16x32_bf16 v[42:45], v[168:171], v[196:199], v[42:45]
	v_mfma_f32_16x16x32_bf16 v[38:41], v[140:143], v[192:195], v[38:41]
	v_mfma_f32_16x16x32_bf16 v[34:37], v[150:153], v[192:195], v[34:37]
	v_mfma_f32_16x16x32_bf16 v[222:225], v[144:147], v[86:89], v[54:57]
	v_mfma_f32_16x16x32_bf16 v[226:229], v[168:171], v[86:89], v[50:53]
	v_mfma_f32_16x16x32_bf16 v[138:141], v[144:147], v[200:203], v[38:41]
	v_mfma_f32_16x16x32_bf16 v[142:145], v[168:171], v[200:203], v[34:37]
	s_setprio 0
	s_setprio 1
	v_mfma_f32_16x16x32_bf16 v[30:33], v[98:101], v[66:69], v[30:33]
	v_mfma_f32_16x16x32_bf16 v[26:29], v[114:117], v[66:69], v[26:29]
	v_mfma_f32_16x16x32_bf16 v[14:17], v[98:101], v[188:191], v[14:17]
	v_mfma_f32_16x16x32_bf16 v[10:13], v[114:117], v[188:191], v[10:13]
	v_mfma_f32_16x16x32_bf16 v[30:33], v[102:105], v[82:85], v[30:33]
	v_mfma_f32_16x16x32_bf16 v[26:29], v[154:157], v[82:85], v[26:29]
	v_mfma_f32_16x16x32_bf16 v[22:25], v[98:101], v[70:73], v[22:25]
	v_mfma_f32_16x16x32_bf16 v[18:21], v[114:117], v[70:73], v[18:21]
	v_mfma_f32_16x16x32_bf16 v[14:17], v[102:105], v[196:199], v[14:17]
	v_mfma_f32_16x16x32_bf16 v[10:13], v[154:157], v[196:199], v[10:13]
	v_mfma_f32_16x16x32_bf16 v[6:9], v[98:101], v[192:195], v[6:9]
	v_mfma_f32_16x16x32_bf16 v[2:5], v[114:117], v[192:195], v[2:5]
	v_mfma_f32_16x16x32_bf16 v[150:153], v[102:105], v[86:89], v[22:25]
	v_mfma_f32_16x16x32_bf16 v[168:171], v[154:157], v[86:89], v[18:21]
	v_mfma_f32_16x16x32_bf16 v[188:191], v[102:105], v[200:203], v[6:9]
	v_mfma_f32_16x16x32_bf16 v[154:157], v[154:157], v[200:203], v[2:5]
	s_setprio 0
	s_barrier
	s_nop 1
	ds_read_b128 v[2:5], v159
	ds_read_b128 v[6:9], v160
	ds_read_b128 v[158:161], v161
	ds_read_b128 v[192:195], v162
	ds_read_b128 v[18:21], v148 offset:32768
	ds_read_b128 v[22:25], v148 offset:34816
	ds_read_b128 v[34:37], v149 offset:32768
	ds_read_b128 v[38:41], v149 offset:34816
	ds_read_b128 v[50:53], v148 offset:36864
	ds_read_b128 v[54:57], v148 offset:38912
	ds_read_b128 v[196:199], v149 offset:36864
	ds_read_b128 v[200:203], v149 offset:38912
	s_waitcnt vmcnt(2)
	s_barrier
	s_waitcnt lgkmcnt(0)
	s_setprio 1
	s_waitcnt lgkmcnt(0)
	v_mfma_f32_16x16x32_bf16 v[66:69], v[2:5], v[18:21], v[126:129]
	v_mfma_f32_16x16x32_bf16 v[126:129], v[6:9], v[34:37], v[66:69]
	v_mfma_f32_16x16x32_bf16 v[66:69], v[158:161], v[18:21], v[122:125]
	v_mfma_f32_16x16x32_bf16 v[114:117], v[192:195], v[34:37], v[66:69]
	v_mfma_f32_16x16x32_bf16 v[66:69], v[2:5], v[22:25], v[118:121]
	v_mfma_f32_16x16x32_bf16 v[102:105], v[6:9], v[38:41], v[66:69]
	v_mfma_f32_16x16x32_bf16 v[66:69], v[158:161], v[22:25], v[134:137]
	v_mfma_f32_16x16x32_bf16 v[98:101], v[192:195], v[38:41], v[66:69]
	v_mfma_f32_16x16x32_bf16 v[66:69], v[2:5], v[50:53], v[110:113]
	v_mfma_f32_16x16x32_bf16 v[86:89], v[6:9], v[196:199], v[66:69]
	v_mfma_f32_16x16x32_bf16 v[66:69], v[158:161], v[50:53], v[106:109]
	v_mfma_f32_16x16x32_bf16 v[82:85], v[192:195], v[196:199], v[66:69]
	v_mfma_f32_16x16x32_bf16 v[66:69], v[2:5], v[54:57], v[206:209]
	v_mfma_f32_16x16x32_bf16 v[70:73], v[6:9], v[200:203], v[66:69]
	v_mfma_f32_16x16x32_bf16 v[66:69], v[158:161], v[54:57], v[218:221]
	v_mfma_f32_16x16x32_bf16 v[66:69], v[192:195], v[200:203], v[66:69]
	s_setprio 0
	s_barrier
	ds_read_b128 v[134:137], v163
	ds_read_b128 v[206:209], v164
	ds_read_b128 v[162:165], v165
	ds_read_b128 v[218:221], v166
	s_waitcnt vmcnt(0)
	s_barrier
	s_waitcnt lgkmcnt(0)
	s_setprio 1
	s_waitcnt lgkmcnt(0)
	v_mfma_f32_16x16x32_bf16 v[94:97], v[134:137], v[18:21], v[94:97]
	v_mfma_f32_16x16x32_bf16 v[18:21], v[162:165], v[18:21], v[90:93]
	v_mfma_f32_16x16x32_bf16 v[118:121], v[218:221], v[34:37], v[18:21]
	v_mfma_f32_16x16x32_bf16 v[18:21], v[134:137], v[22:25], v[172:175]
	v_mfma_f32_16x16x32_bf16 v[110:113], v[206:209], v[38:41], v[18:21]
	v_mfma_f32_16x16x32_bf16 v[18:21], v[162:165], v[22:25], v[176:179]
	v_mfma_f32_16x16x32_bf16 v[106:109], v[218:221], v[38:41], v[18:21]
	v_mfma_f32_16x16x32_bf16 v[18:21], v[134:137], v[50:53], v[78:81]
	v_mfma_f32_16x16x32_bf16 v[122:125], v[206:209], v[34:37], v[94:97]
	v_mfma_f32_16x16x32_bf16 v[94:97], v[206:209], v[196:199], v[18:21]
	v_mfma_f32_16x16x32_bf16 v[18:21], v[162:165], v[50:53], v[74:77]
	v_mfma_f32_16x16x32_bf16 v[90:93], v[218:221], v[196:199], v[18:21]
	v_mfma_f32_16x16x32_bf16 v[18:21], v[134:137], v[54:57], v[180:183]
	v_mfma_f32_16x16x32_bf16 v[78:81], v[206:209], v[200:203], v[18:21]
	v_mfma_f32_16x16x32_bf16 v[18:21], v[162:165], v[54:57], v[184:187]
	v_mfma_f32_16x16x32_bf16 v[74:77], v[218:221], v[200:203], v[18:21]
	s_setprio 0
	s_barrier
	ds_read_b128 v[172:175], v148 offset:49152
	ds_read_b128 v[176:179], v148 offset:51200
	ds_read_b128 v[180:183], v149 offset:49152
	ds_read_b128 v[184:187], v149 offset:51200
	ds_read_b128 v[196:199], v148 offset:53248
	ds_read_b128 v[200:203], v148 offset:55296
	ds_read_b128 v[230:233], v149 offset:53248
	ds_read_b128 v[146:149], v149 offset:55296
	s_barrier
	s_waitcnt lgkmcnt(0)
	s_setprio 1
	s_waitcnt lgkmcnt(0)
	v_mfma_f32_16x16x32_bf16 v[18:21], v[2:5], v[172:175], v[62:65]
	v_mfma_f32_16x16x32_bf16 v[54:57], v[6:9], v[180:183], v[18:21]
	v_mfma_f32_16x16x32_bf16 v[18:21], v[158:161], v[172:175], v[58:61]
	v_mfma_f32_16x16x32_bf16 v[50:53], v[192:195], v[180:183], v[18:21]
	v_mfma_f32_16x16x32_bf16 v[18:21], v[2:5], v[176:179], v[222:225]
	v_mfma_f32_16x16x32_bf16 v[38:41], v[6:9], v[184:187], v[18:21]
	v_mfma_f32_16x16x32_bf16 v[18:21], v[158:161], v[176:179], v[226:229]
	v_mfma_f32_16x16x32_bf16 v[34:37], v[192:195], v[184:187], v[18:21]
	v_mfma_f32_16x16x32_bf16 v[18:21], v[2:5], v[196:199], v[46:49]
	v_mfma_f32_16x16x32_bf16 v[2:5], v[2:5], v[200:203], v[138:141]
	v_mfma_f32_16x16x32_bf16 v[22:25], v[6:9], v[230:233], v[18:21]
	v_mfma_f32_16x16x32_bf16 v[18:21], v[158:161], v[196:199], v[42:45]
	v_mfma_f32_16x16x32_bf16 v[6:9], v[6:9], v[146:149], v[2:5]
	v_mfma_f32_16x16x32_bf16 v[2:5], v[158:161], v[200:203], v[142:145]
	v_mfma_f32_16x16x32_bf16 v[18:21], v[192:195], v[230:233], v[18:21]
	v_mfma_f32_16x16x32_bf16 v[2:5], v[192:195], v[146:149], v[2:5]
	s_setprio 0
	s_setprio 1
	v_mfma_f32_16x16x32_bf16 v[26:29], v[162:165], v[172:175], v[26:29]
	v_mfma_f32_16x16x32_bf16 v[58:61], v[218:221], v[180:183], v[26:29]
	v_mfma_f32_16x16x32_bf16 v[26:29], v[134:137], v[176:179], v[150:153]
	v_mfma_f32_16x16x32_bf16 v[46:49], v[206:209], v[184:187], v[26:29]
	v_mfma_f32_16x16x32_bf16 v[26:29], v[162:165], v[176:179], v[168:171]
	v_mfma_f32_16x16x32_bf16 v[10:13], v[162:165], v[196:199], v[10:13]
	v_mfma_f32_16x16x32_bf16 v[30:33], v[134:137], v[172:175], v[30:33]
	v_mfma_f32_16x16x32_bf16 v[42:45], v[218:221], v[184:187], v[26:29]
	v_mfma_f32_16x16x32_bf16 v[14:17], v[134:137], v[196:199], v[14:17]
	v_mfma_f32_16x16x32_bf16 v[26:29], v[218:221], v[230:233], v[10:13]
	v_mfma_f32_16x16x32_bf16 v[10:13], v[134:137], v[200:203], v[188:191]
	v_mfma_f32_16x16x32_bf16 v[62:65], v[206:209], v[180:183], v[30:33]
	v_mfma_f32_16x16x32_bf16 v[30:33], v[206:209], v[230:233], v[14:17]
	v_mfma_f32_16x16x32_bf16 v[14:17], v[206:209], v[146:149], v[10:13]
	v_mfma_f32_16x16x32_bf16 v[10:13], v[162:165], v[200:203], v[154:157]
	v_mfma_f32_16x16x32_bf16 v[10:13], v[218:221], v[146:149], v[10:13]
	s_setprio 0
	s_cmpk_gt_u32 s0, 0xff
	s_barrier
	s_cbranch_scc1 .LBB0_90
	s_barrier
	s_branch .LBB0_90

.LBB0_336:
	s_lshl_b32 s10, s0, 8
	s_lshl_b32 s8, s15, 8
	s_cmp_gt_i32 s15, 7
	s_mov_b64 s[4:5], -1
	s_cbranch_scc0 .LBB0_353
	v_mov_b64_e32 v[2:3], s[6:7]
	flat_load_dwordx2 v[132:133], v[2:3] offset:160
	s_load_dwordx2 s[100:101], s[78:79], 0xa0
	s_load_dwordx2 s[100:101], s[78:79], 0xa0
	s_cmp_gt_u32 s15, 15
	s_waitcnt vmcnt(0) lgkmcnt(0)
	v_lshl_add_u64 v[134:135], v[132:133], 0, s[94:95]
	s_cbranch_scc0 .LBB0_345
	v_mov_b32_e32 v17, v204
	s_ashr_i32 s9, s8, 31
	v_lshrrev_b32_e32 v18, 4, v17
	v_xor_b32_e32 v0, v17, v18
	v_lshlrev_b32_e32 v0, 3, v0
	v_readfirstlane_b32 s0, v17
	v_and_b32_e32 v14, 56, v0
	v_lshlrev_b32_e32 v0, 8, v17
	s_ashr_i32 s19, s0, 6
	v_and_b32_e32 v15, 0xfffff800, v0
	v_or_b32_e32 v0, v14, v15
	v_add_u32_e32 v16, 0x20000, v15
	s_lshl_b64 s[4:5], s[8:9], 12
	s_lshl_b32 s1, s19, 10
	v_or_b32_e32 v4, v14, v16
	v_lshl_add_u64 v[6:7], v[134:135], 0, s[4:5]
	s_add_i32 s2, s1, 0x10000
	v_lshlrev_b64 v[20:21], 1, v[0:1]
	v_mov_b32_e32 v5, v1
	s_ashr_i32 s11, s10, 31
	v_lshl_add_u64 v[2:3], v[6:7], 0, v[20:21]
	s_mov_b32 m0, s2
	v_lshlrev_b64 v[22:23], 1, v[4:5]
	s_add_i32 s3, s1, 0x12000
	s_lshl_b64 s[12:13], s[10:11], 12
	s_or_b32 s16, s8, 0x80
	global_load_lds_dwordx4 v[2:3], off
	v_lshl_add_u64 v[4:5], v[6:7], 0, v[22:23]
	s_mov_b32 m0, s3
	v_lshl_add_u64 v[6:7], v[132:133], 0, s[12:13]
	s_ashr_i32 s17, s16, 31
	global_load_lds_dwordx4 v[4:5], off
	v_lshl_add_u64 v[8:9], v[6:7], 0, v[20:21]
	s_mov_b32 m0, s1
	s_add_i32 s9, s1, 0x2000
	s_lshl_b64 s[16:17], s[16:17], 12
	s_or_b32 s20, s10, 0x80
	global_load_lds_dwordx4 v[8:9], off
	v_lshl_add_u64 v[6:7], v[6:7], 0, v[22:23]
	s_mov_b32 m0, s9
	v_lshl_add_u64 v[10:11], v[134:135], 0, s[16:17]
	s_add_i32 s11, s1, 0x14000
	s_ashr_i32 s21, s20, 31
	global_load_lds_dwordx4 v[6:7], off
	v_lshl_add_u64 v[12:13], v[10:11], 0, v[20:21]
	s_mov_b32 m0, s11
	s_add_i32 s16, s1, 0x16000
	s_lshl_b64 s[20:21], s[20:21], 12
	global_load_lds_dwordx4 v[12:13], off
	v_lshl_add_u64 v[10:11], v[10:11], 0, v[22:23]
	s_mov_b32 m0, s16
	v_lshl_add_u64 v[24:25], v[132:133], 0, s[20:21]
	s_add_i32 s17, s1, 0x4000
	global_load_lds_dwordx4 v[10:11], off
	v_lshl_add_u64 v[138:139], v[24:25], 0, v[20:21]
	s_mov_b32 m0, s17
	s_add_i32 s18, s1, 0x6000
	global_load_lds_dwordx4 v[138:139], off
	v_lshl_add_u64 v[136:137], v[24:25], 0, v[22:23]
	s_mov_b32 m0, s18
	s_ashr_i32 s20, s0, 8
	global_load_lds_dwordx4 v[136:137], off
	s_cmp_lg_u32 s20, 1
	s_cbranch_scc1 .LBB0_340
	s_barrier
.LBB0_340:
	s_lshl_b32 s19, s19, 5
	v_and_b32_e32 v0, 15, v17
	s_and_b32 s19, s19, 0x60
	v_lshlrev_b32_e32 v19, 7, v0
	v_or_b32_e32 v0, s19, v0
	s_add_i32 s19, s1, 0x18000
	s_mov_b64 s[24:25], 0x80
	v_lshl_or_b32 v19, s20, 13, v19
	v_lshl_add_u64 v[2:3], v[2:3], 0, s[24:25]
	s_mov_b32 m0, s19
	s_add_i32 s20, s1, 0x1a000
	s_waitcnt vmcnt(4)
	s_barrier
	global_load_lds_dwordx4 v[2:3], off
	v_lshl_add_u64 v[2:3], v[4:5], 0, s[24:25]
	s_mov_b32 m0, s20
	s_add_i32 s21, s1, 0x8000
	global_load_lds_dwordx4 v[2:3], off
	v_lshl_add_u64 v[2:3], v[8:9], 0, s[24:25]
	s_mov_b32 m0, s21
	s_add_i32 s22, s1, 0xa000
	global_load_lds_dwordx4 v[2:3], off
	v_lshl_add_u64 v[2:3], v[6:7], 0, s[24:25]
	s_mov_b32 m0, s22
	s_add_i32 s23, s1, 0x1c000
	global_load_lds_dwordx4 v[2:3], off
	v_lshl_add_u64 v[2:3], v[12:13], 0, s[24:25]
	s_mov_b32 m0, s23
	v_and_b32_e32 v20, 3, v18
	global_load_lds_dwordx4 v[2:3], off
	v_lshl_add_u64 v[2:3], v[10:11], 0, s[24:25]
	s_add_i32 s24, s1, 0x1e000
	s_mov_b32 m0, s24
	v_bfe_u32 v17, v17, 1, 3
	global_load_lds_dwordx4 v[2:3], off
	v_bitop3_b32 v18, v18, v17, 3 bitop3:0x6c
	v_bitop3_b32 v17, v20, v17, 4 bitop3:0x36
	v_lshlrev_b32_e32 v18, 4, v18
	v_lshlrev_b32_e32 v17, 4, v17
	v_lshlrev_b32_e32 v0, 7, v0
	v_or_b32_e32 v152, v0, v18
	v_or_b32_e32 v153, v0, v17
	v_add_u32_e32 v0, v16, v14
	s_waitcnt vmcnt(6)
	v_lshlrev_b64 v[2:3], 1, v[0:1]
	v_add_u32_e32 v0, v15, v14
	v_lshl_add_u64 v[140:141], s[12:13], 0, v[2:3]
	v_lshlrev_b64 v[4:5], 1, v[0:1]
	v_lshl_add_u64 v[144:145], s[4:5], 0, v[2:3]
	v_mov_b32_e32 v2, 0
	v_or_b32_e32 v150, v18, v19
	v_or_b32_e32 v151, v17, v19
	v_lshl_add_u64 v[142:143], s[12:13], 0, v[4:5]
	v_lshl_add_u64 v[146:147], s[4:5], 0, v[4:5]
	s_mov_b32 s4, -2
	v_mov_b64_e32 v[148:149], v[132:133]
	v_mov_b32_e32 v3, v2
	v_mov_b32_e32 v4, v2
	v_mov_b32_e32 v5, v2
	v_mov_b32_e32 v6, v2
	v_mov_b32_e32 v7, v2
	v_mov_b32_e32 v8, v2
	v_mov_b32_e32 v9, v2
	v_mov_b32_e32 v10, v2
	v_mov_b32_e32 v11, v2
	v_mov_b32_e32 v12, v2
	v_mov_b32_e32 v13, v2
	v_mov_b32_e32 v14, v2
	v_mov_b32_e32 v15, v2
	v_mov_b32_e32 v16, v2
	v_mov_b32_e32 v17, v2
	v_mov_b32_e32 v18, v2
	v_mov_b32_e32 v19, v2
	v_mov_b32_e32 v20, v2
	v_mov_b32_e32 v21, v2
	v_mov_b32_e32 v22, v2
	v_mov_b32_e32 v23, v2
	v_mov_b32_e32 v24, v2
	v_mov_b32_e32 v25, v2
	v_mov_b32_e32 v26, v2
	v_mov_b32_e32 v27, v2
	v_mov_b32_e32 v28, v2
	v_mov_b32_e32 v29, v2
	v_mov_b32_e32 v30, v2
	v_mov_b32_e32 v31, v2
	v_mov_b32_e32 v32, v2
	v_mov_b32_e32 v33, v2
	v_mov_b32_e32 v34, v2
	v_mov_b32_e32 v35, v2
	v_mov_b32_e32 v36, v2
	v_mov_b32_e32 v37, v2
	v_mov_b32_e32 v38, v2
	v_mov_b32_e32 v39, v2
	v_mov_b32_e32 v40, v2
	v_mov_b32_e32 v41, v2
	v_mov_b32_e32 v42, v2
	v_mov_b32_e32 v43, v2
	v_mov_b32_e32 v44, v2
	v_mov_b32_e32 v45, v2
	v_mov_b32_e32 v46, v2
	v_mov_b32_e32 v47, v2
	v_mov_b32_e32 v48, v2
	v_mov_b32_e32 v49, v2
	v_mov_b32_e32 v50, v2
	v_mov_b32_e32 v51, v2
	v_mov_b32_e32 v52, v2
	v_mov_b32_e32 v53, v2
	v_mov_b32_e32 v54, v2
	v_mov_b32_e32 v55, v2
	v_mov_b32_e32 v56, v2
	v_mov_b32_e32 v57, v2
	v_mov_b32_e32 v58, v2
	v_mov_b32_e32 v59, v2
	v_mov_b32_e32 v60, v2
	v_mov_b32_e32 v61, v2
	v_mov_b32_e32 v62, v2
	v_mov_b32_e32 v63, v2
	v_mov_b32_e32 v64, v2
	v_mov_b32_e32 v65, v2
	v_mov_b32_e32 v66, v2
	v_mov_b32_e32 v67, v2
	v_mov_b32_e32 v68, v2
	v_mov_b32_e32 v69, v2
	v_mov_b32_e32 v70, v2
	v_mov_b32_e32 v71, v2
	v_mov_b32_e32 v72, v2
	v_mov_b32_e32 v73, v2
	v_mov_b32_e32 v74, v2
	v_mov_b32_e32 v75, v2
	v_mov_b32_e32 v76, v2
	v_mov_b32_e32 v77, v2
	v_mov_b32_e32 v78, v2
	v_mov_b32_e32 v79, v2
	v_mov_b32_e32 v80, v2
	v_mov_b32_e32 v81, v2
	v_mov_b32_e32 v82, v2
	v_mov_b32_e32 v83, v2
	v_mov_b32_e32 v84, v2
	v_mov_b32_e32 v85, v2
	v_mov_b32_e32 v86, v2
	v_mov_b32_e32 v87, v2
	v_mov_b32_e32 v88, v2
	v_mov_b32_e32 v89, v2
	v_mov_b32_e32 v90, v2
	v_mov_b32_e32 v91, v2
	v_mov_b32_e32 v92, v2
	v_mov_b32_e32 v93, v2
	v_mov_b32_e32 v94, v2
	v_mov_b32_e32 v95, v2
	v_mov_b32_e32 v96, v2
	v_mov_b32_e32 v97, v2
	v_mov_b32_e32 v98, v2
	v_mov_b32_e32 v99, v2
	v_mov_b32_e32 v100, v2
	v_mov_b32_e32 v101, v2
	v_mov_b32_e32 v102, v2
	v_mov_b32_e32 v103, v2
	v_mov_b32_e32 v104, v2
	v_mov_b32_e32 v105, v2
	v_mov_b32_e32 v106, v2
	v_mov_b32_e32 v107, v2
	v_mov_b32_e32 v108, v2
	v_mov_b32_e32 v109, v2
	v_mov_b32_e32 v110, v2
	v_mov_b32_e32 v111, v2
	v_mov_b32_e32 v112, v2
	v_mov_b32_e32 v113, v2
	v_mov_b32_e32 v114, v2
	v_mov_b32_e32 v115, v2
	v_mov_b32_e32 v116, v2
	v_mov_b32_e32 v117, v2
	v_mov_b32_e32 v118, v2
	v_mov_b32_e32 v119, v2
	v_mov_b32_e32 v120, v2
	v_mov_b32_e32 v121, v2
	v_mov_b32_e32 v122, v2
	v_mov_b32_e32 v123, v2
	v_mov_b32_e32 v124, v2
	v_mov_b32_e32 v125, v2
	v_mov_b32_e32 v126, v2
	v_mov_b32_e32 v127, v2
	v_mov_b32_e32 v128, v2
	v_mov_b32_e32 v129, v2
	s_mov_b64 s[26:27], 0x82d4900
	s_mov_b64 s[28:29], 0x8254980
	s_mov_b64 s[30:31], 0x82d4980
	s_waitcnt lgkmcnt(0)
	s_sub_u32 s100, s100, 0x40000000
	s_subb_u32 s101, s101, 0
	s_mov_b64 vcc, s[100:101]
	v_lshl_add_u64 v[202:203], v[148:149], 0, v[142:143]
	v_subrev_u32_e32 v202, vcc_lo, v202
	v_lshl_add_u64 v[206:207], v[148:149], 0, v[140:141]
	v_subrev_u32_e32 v206, vcc_lo, v206
	v_lshl_add_u64 v[208:209], v[148:149], 0, v[146:147]
	v_subrev_u32_e32 v208, vcc_lo, v208
	v_lshl_add_u64 v[210:211], v[148:149], 0, v[144:145]
	v_subrev_u32_e32 v210, vcc_lo, v210
	v_add_u32_e32 v203, 0x10000, v152
	v_add_u32_e32 v207, 0x10000, v153
	s_barrier
.LBB0_341:
	ds_read_b128 v[162:165], v203
	ds_read_b128 v[166:169], v207
	ds_read_b128 v[170:173], v203 offset:2048
	ds_read_b128 v[174:177], v207 offset:2048
	s_add_i32 s12, s1, 0xc000
	s_mov_b32 m0, s12
	s_add_i32 s5, s1, 0xe000
	ds_read_b128 v[178:181], v150
	ds_read_b128 v[182:185], v150 offset:2048
	ds_read_b128 v[186:189], v151
	ds_read_b128 v[190:193], v151 offset:2048
	ds_read_b128 v[194:197], v150 offset:4096
	ds_read_b128 v[198:201], v150 offset:6144
	ds_read_b128 v[218:221], v151 offset:4096
	ds_read_b128 v[222:225], v151 offset:6144
	s_add_u32 s100, vcc_lo, s50
	s_addc_u32 s101, vcc_hi, s51
	global_load_lds_dwordx4 v202, s[100:101]
	s_mov_b32 m0, s5
	s_add_u32 s100, vcc_lo, s50
	s_addc_u32 s101, vcc_hi, s51
	global_load_lds_dwordx4 v206, s[100:101]
	s_waitcnt lgkmcnt(8)
	s_waitcnt vmcnt(10)
	s_barrier
	s_waitcnt lgkmcnt(0)
	s_setprio 1
	s_waitcnt lgkmcnt(0)
	v_mfma_f32_16x16x32_bf16 v[126:129], v[178:181], v[162:165], v[126:129]
	v_mfma_f32_16x16x32_bf16 v[122:125], v[178:181], v[170:173], v[122:125]
	v_mfma_f32_16x16x32_bf16 v[118:121], v[182:185], v[162:165], v[118:121]
	v_mfma_f32_16x16x32_bf16 v[114:117], v[182:185], v[170:173], v[114:117]
	v_mfma_f32_16x16x32_bf16 v[110:113], v[194:197], v[162:165], v[110:113]
	v_mfma_f32_16x16x32_bf16 v[106:109], v[194:197], v[170:173], v[106:109]
	v_mfma_f32_16x16x32_bf16 v[102:105], v[198:201], v[162:165], v[102:105]
	v_mfma_f32_16x16x32_bf16 v[98:101], v[198:201], v[170:173], v[98:101]
	v_mfma_f32_16x16x32_bf16 v[126:129], v[186:189], v[166:169], v[126:129]
	v_mfma_f32_16x16x32_bf16 v[122:125], v[186:189], v[174:177], v[122:125]
	v_mfma_f32_16x16x32_bf16 v[118:121], v[190:193], v[166:169], v[118:121]
	v_mfma_f32_16x16x32_bf16 v[114:117], v[190:193], v[174:177], v[114:117]
	v_mfma_f32_16x16x32_bf16 v[110:113], v[218:221], v[166:169], v[110:113]
	v_mfma_f32_16x16x32_bf16 v[106:109], v[218:221], v[174:177], v[106:109]
	v_mfma_f32_16x16x32_bf16 v[102:105], v[222:225], v[166:169], v[102:105]
	v_mfma_f32_16x16x32_bf16 v[98:101], v[222:225], v[174:177], v[98:101]
	s_setprio 0
	s_barrier
	s_mov_b32 m0, s2
	ds_read_b128 v[226:229], v203 offset:16384
	ds_read_b128 v[230:233], v207 offset:16384
	ds_read_b128 v[234:237], v203 offset:18432
	ds_read_b128 v[238:241], v207 offset:18432
	s_add_u32 s100, vcc_lo, s70
	s_addc_u32 s101, vcc_hi, s71
	global_load_lds_dwordx4 v208, s[100:101]
	s_mov_b32 m0, s3
	s_add_u32 s100, vcc_lo, s70
	s_addc_u32 s101, vcc_hi, s71
	global_load_lds_dwordx4 v210, s[100:101]
	s_waitcnt vmcnt(10)
	s_waitcnt lgkmcnt(0)
	s_barrier
	s_waitcnt lgkmcnt(0)
	s_setprio 1
	s_waitcnt lgkmcnt(0)
	v_mfma_f32_16x16x32_bf16 v[94:97], v[178:181], v[226:229], v[94:97]
	v_mfma_f32_16x16x32_bf16 v[90:93], v[178:181], v[234:237], v[90:93]
	v_mfma_f32_16x16x32_bf16 v[86:89], v[182:185], v[226:229], v[86:89]
	v_mfma_f32_16x16x32_bf16 v[82:85], v[182:185], v[234:237], v[82:85]
	v_mfma_f32_16x16x32_bf16 v[78:81], v[194:197], v[226:229], v[78:81]
	v_mfma_f32_16x16x32_bf16 v[74:77], v[194:197], v[234:237], v[74:77]
	v_mfma_f32_16x16x32_bf16 v[70:73], v[198:201], v[226:229], v[70:73]
	v_mfma_f32_16x16x32_bf16 v[66:69], v[198:201], v[234:237], v[66:69]
	v_mfma_f32_16x16x32_bf16 v[94:97], v[186:189], v[230:233], v[94:97]
	v_mfma_f32_16x16x32_bf16 v[90:93], v[186:189], v[238:241], v[90:93]
	v_mfma_f32_16x16x32_bf16 v[86:89], v[190:193], v[230:233], v[86:89]
	v_mfma_f32_16x16x32_bf16 v[82:85], v[190:193], v[238:241], v[82:85]
	v_mfma_f32_16x16x32_bf16 v[78:81], v[218:221], v[230:233], v[78:81]
	v_mfma_f32_16x16x32_bf16 v[74:77], v[218:221], v[238:241], v[74:77]
	v_mfma_f32_16x16x32_bf16 v[70:73], v[222:225], v[230:233], v[70:73]
	v_mfma_f32_16x16x32_bf16 v[66:69], v[222:225], v[238:241], v[66:69]
	s_setprio 0
	s_mov_b32 m0, s1
	s_barrier
	ds_read_b128 v[178:181], v150 offset:16384
	ds_read_b128 v[182:185], v150 offset:18432
	ds_read_b128 v[186:189], v151 offset:16384
	ds_read_b128 v[190:193], v151 offset:18432
	ds_read_b128 v[194:197], v150 offset:20480
	ds_read_b128 v[198:201], v150 offset:22528
	ds_read_b128 v[218:221], v151 offset:20480
	ds_read_b128 v[222:225], v151 offset:22528
	s_add_u32 s100, vcc_lo, s54
	s_addc_u32 s101, vcc_hi, s55
	global_load_lds_dwordx4 v202, s[100:101]
	s_mov_b32 m0, s9
	s_add_u32 s100, vcc_lo, s54
	s_addc_u32 s101, vcc_hi, s55
	global_load_lds_dwordx4 v206, s[100:101]
	s_mov_b32 m0, s11
	s_add_u32 s100, vcc_lo, s26
	s_addc_u32 s101, vcc_hi, s27
	global_load_lds_dwordx4 v208, s[100:101]
	s_mov_b32 m0, s16
	s_add_u32 s100, vcc_lo, s26
	s_addc_u32 s101, vcc_hi, s27
	global_load_lds_dwordx4 v210, s[100:101]
	s_waitcnt vmcnt(10)
	s_waitcnt lgkmcnt(0)
	s_barrier
	s_waitcnt lgkmcnt(0)
	s_setprio 1
	s_waitcnt lgkmcnt(0)
	v_mfma_f32_16x16x32_bf16 v[62:65], v[178:181], v[162:165], v[62:65]
	v_mfma_f32_16x16x32_bf16 v[58:61], v[178:181], v[170:173], v[58:61]
	v_mfma_f32_16x16x32_bf16 v[54:57], v[182:185], v[162:165], v[54:57]
	v_mfma_f32_16x16x32_bf16 v[50:53], v[182:185], v[170:173], v[50:53]
	v_mfma_f32_16x16x32_bf16 v[46:49], v[194:197], v[162:165], v[46:49]
	v_mfma_f32_16x16x32_bf16 v[42:45], v[194:197], v[170:173], v[42:45]
	v_mfma_f32_16x16x32_bf16 v[38:41], v[198:201], v[162:165], v[38:41]
	v_mfma_f32_16x16x32_bf16 v[34:37], v[198:201], v[170:173], v[34:37]
	v_mfma_f32_16x16x32_bf16 v[62:65], v[186:189], v[166:169], v[62:65]
	v_mfma_f32_16x16x32_bf16 v[58:61], v[186:189], v[174:177], v[58:61]
	v_mfma_f32_16x16x32_bf16 v[54:57], v[190:193], v[166:169], v[54:57]
	v_mfma_f32_16x16x32_bf16 v[50:53], v[190:193], v[174:177], v[50:53]
	v_mfma_f32_16x16x32_bf16 v[46:49], v[218:221], v[166:169], v[46:49]
	v_mfma_f32_16x16x32_bf16 v[42:45], v[218:221], v[174:177], v[42:45]
	v_mfma_f32_16x16x32_bf16 v[38:41], v[222:225], v[166:169], v[38:41]
	v_mfma_f32_16x16x32_bf16 v[34:37], v[222:225], v[174:177], v[34:37]
	v_mfma_f32_16x16x32_bf16 v[30:33], v[178:181], v[226:229], v[30:33]
	v_mfma_f32_16x16x32_bf16 v[26:29], v[178:181], v[234:237], v[26:29]
	v_mfma_f32_16x16x32_bf16 v[22:25], v[182:185], v[226:229], v[22:25]
	v_mfma_f32_16x16x32_bf16 v[18:21], v[182:185], v[234:237], v[18:21]
	v_mfma_f32_16x16x32_bf16 v[14:17], v[194:197], v[226:229], v[14:17]
	v_mfma_f32_16x16x32_bf16 v[10:13], v[194:197], v[234:237], v[10:13]
	v_mfma_f32_16x16x32_bf16 v[6:9], v[198:201], v[226:229], v[6:9]
	v_mfma_f32_16x16x32_bf16 v[2:5], v[198:201], v[234:237], v[2:5]
	v_mfma_f32_16x16x32_bf16 v[30:33], v[186:189], v[230:233], v[30:33]
	v_mfma_f32_16x16x32_bf16 v[26:29], v[186:189], v[238:241], v[26:29]
	v_mfma_f32_16x16x32_bf16 v[22:25], v[190:193], v[230:233], v[22:25]
	v_mfma_f32_16x16x32_bf16 v[18:21], v[190:193], v[238:241], v[18:21]
	v_mfma_f32_16x16x32_bf16 v[14:17], v[218:221], v[230:233], v[14:17]
	v_mfma_f32_16x16x32_bf16 v[10:13], v[218:221], v[238:241], v[10:13]
	v_mfma_f32_16x16x32_bf16 v[6:9], v[222:225], v[230:233], v[6:9]
	v_mfma_f32_16x16x32_bf16 v[2:5], v[222:225], v[238:241], v[2:5]
	s_setprio 0
	s_barrier
	ds_read_b128 v[170:173], v203 offset:32768
	ds_read_b128 v[174:177], v207 offset:32768
	ds_read_b128 v[178:181], v203 offset:34816
	ds_read_b128 v[182:185], v207 offset:34816
	s_mov_b32 m0, s17
	ds_read_b128 v[186:189], v150 offset:32768
	ds_read_b128 v[190:193], v150 offset:34816
	ds_read_b128 v[194:197], v151 offset:32768
	ds_read_b128 v[198:201], v151 offset:34816
	ds_read_b128 v[218:221], v150 offset:36864
	ds_read_b128 v[222:225], v150 offset:38912
	ds_read_b128 v[226:229], v151 offset:36864
	ds_read_b128 v[230:233], v151 offset:38912
	s_add_u32 s100, vcc_lo, s58
	s_addc_u32 s101, vcc_hi, s59
	global_load_lds_dwordx4 v202, s[100:101]
	s_mov_b32 m0, s18
	s_add_u32 s100, vcc_lo, s58
	s_addc_u32 s101, vcc_hi, s59
	global_load_lds_dwordx4 v206, s[100:101]
	s_waitcnt lgkmcnt(8)
	s_waitcnt vmcnt(10)
	s_barrier
	s_waitcnt lgkmcnt(0)
	s_setprio 1
	s_waitcnt lgkmcnt(0)
	v_mfma_f32_16x16x32_bf16 v[126:129], v[186:189], v[170:173], v[126:129]
	v_mfma_f32_16x16x32_bf16 v[122:125], v[186:189], v[178:181], v[122:125]
	v_mfma_f32_16x16x32_bf16 v[118:121], v[190:193], v[170:173], v[118:121]
	v_mfma_f32_16x16x32_bf16 v[114:117], v[190:193], v[178:181], v[114:117]
	v_mfma_f32_16x16x32_bf16 v[110:113], v[218:221], v[170:173], v[110:113]
	v_mfma_f32_16x16x32_bf16 v[106:109], v[218:221], v[178:181], v[106:109]
	v_mfma_f32_16x16x32_bf16 v[102:105], v[222:225], v[170:173], v[102:105]
	v_mfma_f32_16x16x32_bf16 v[98:101], v[222:225], v[178:181], v[98:101]
	v_mfma_f32_16x16x32_bf16 v[126:129], v[194:197], v[174:177], v[126:129]
	v_mfma_f32_16x16x32_bf16 v[122:125], v[194:197], v[182:185], v[122:125]
	v_mfma_f32_16x16x32_bf16 v[118:121], v[198:201], v[174:177], v[118:121]
	v_mfma_f32_16x16x32_bf16 v[114:117], v[198:201], v[182:185], v[114:117]
	v_mfma_f32_16x16x32_bf16 v[110:113], v[226:229], v[174:177], v[110:113]
	v_mfma_f32_16x16x32_bf16 v[106:109], v[226:229], v[182:185], v[106:109]
	v_mfma_f32_16x16x32_bf16 v[102:105], v[230:233], v[174:177], v[102:105]
	v_mfma_f32_16x16x32_bf16 v[98:101], v[230:233], v[182:185], v[98:101]
	s_setprio 0
	s_barrier
	s_mov_b32 m0, s19
	ds_read_b128 v[234:237], v203 offset:49152
	ds_read_b128 v[238:241], v207 offset:49152
	ds_read_b128 v[242:245], v203 offset:51200
	ds_read_b128 v[246:249], v207 offset:51200
	s_add_u32 s100, vcc_lo, s28
	s_addc_u32 s101, vcc_hi, s29
	global_load_lds_dwordx4 v208, s[100:101]
	s_mov_b32 m0, s20
	s_add_u32 s100, vcc_lo, s28
	s_addc_u32 s101, vcc_hi, s29
	global_load_lds_dwordx4 v210, s[100:101]
	s_waitcnt vmcnt(10)
	s_waitcnt lgkmcnt(0)
	s_barrier
	s_waitcnt lgkmcnt(0)
	s_setprio 1
	s_waitcnt lgkmcnt(0)
	v_mfma_f32_16x16x32_bf16 v[94:97], v[186:189], v[234:237], v[94:97]
	v_mfma_f32_16x16x32_bf16 v[90:93], v[186:189], v[242:245], v[90:93]
	v_mfma_f32_16x16x32_bf16 v[86:89], v[190:193], v[234:237], v[86:89]
	v_mfma_f32_16x16x32_bf16 v[82:85], v[190:193], v[242:245], v[82:85]
	v_mfma_f32_16x16x32_bf16 v[78:81], v[218:221], v[234:237], v[78:81]
	v_mfma_f32_16x16x32_bf16 v[74:77], v[218:221], v[242:245], v[74:77]
	v_mfma_f32_16x16x32_bf16 v[70:73], v[222:225], v[234:237], v[70:73]
	v_mfma_f32_16x16x32_bf16 v[66:69], v[222:225], v[242:245], v[66:69]
	v_mfma_f32_16x16x32_bf16 v[94:97], v[194:197], v[238:241], v[94:97]
	v_mfma_f32_16x16x32_bf16 v[90:93], v[194:197], v[246:249], v[90:93]
	v_mfma_f32_16x16x32_bf16 v[86:89], v[198:201], v[238:241], v[86:89]
	v_mfma_f32_16x16x32_bf16 v[82:85], v[198:201], v[246:249], v[82:85]
	v_mfma_f32_16x16x32_bf16 v[78:81], v[226:229], v[238:241], v[78:81]
	v_mfma_f32_16x16x32_bf16 v[74:77], v[226:229], v[246:249], v[74:77]
	v_mfma_f32_16x16x32_bf16 v[70:73], v[230:233], v[238:241], v[70:73]
	v_mfma_f32_16x16x32_bf16 v[66:69], v[230:233], v[246:249], v[66:69]
	s_setprio 0
	s_mov_b32 m0, s21
	s_barrier
	ds_read_b128 v[186:189], v150 offset:49152
	ds_read_b128 v[190:193], v150 offset:51200
	ds_read_b128 v[194:197], v151 offset:49152
	ds_read_b128 v[198:201], v151 offset:51200
	ds_read_b128 v[218:221], v150 offset:53248
	ds_read_b128 v[222:225], v150 offset:55296
	ds_read_b128 v[226:229], v151 offset:53248
	ds_read_b128 v[230:233], v151 offset:55296
	s_add_u32 s100, vcc_lo, s62
	s_addc_u32 s101, vcc_hi, s63
	global_load_lds_dwordx4 v202, s[100:101]
	s_mov_b32 m0, s22
	s_add_u32 s100, vcc_lo, s62
	s_addc_u32 s101, vcc_hi, s63
	global_load_lds_dwordx4 v206, s[100:101]
	s_mov_b32 m0, s23
	s_add_u32 s100, vcc_lo, s30
	s_addc_u32 s101, vcc_hi, s31
	global_load_lds_dwordx4 v208, s[100:101]
	s_mov_b32 m0, s24
	s_add_u32 s100, vcc_lo, s30
	s_addc_u32 s101, vcc_hi, s31
	global_load_lds_dwordx4 v210, s[100:101]
	s_waitcnt vmcnt(10)
	s_waitcnt lgkmcnt(0)
	s_barrier
	s_waitcnt lgkmcnt(0)
	s_setprio 1
	s_waitcnt lgkmcnt(0)
	v_mfma_f32_16x16x32_bf16 v[62:65], v[186:189], v[170:173], v[62:65]
	v_mfma_f32_16x16x32_bf16 v[58:61], v[186:189], v[178:181], v[58:61]
	v_mfma_f32_16x16x32_bf16 v[54:57], v[190:193], v[170:173], v[54:57]
	v_mfma_f32_16x16x32_bf16 v[50:53], v[190:193], v[178:181], v[50:53]
	v_mfma_f32_16x16x32_bf16 v[46:49], v[218:221], v[170:173], v[46:49]
	v_mfma_f32_16x16x32_bf16 v[42:45], v[218:221], v[178:181], v[42:45]
	v_mfma_f32_16x16x32_bf16 v[38:41], v[222:225], v[170:173], v[38:41]
	v_mfma_f32_16x16x32_bf16 v[34:37], v[222:225], v[178:181], v[34:37]
	v_mfma_f32_16x16x32_bf16 v[62:65], v[194:197], v[174:177], v[62:65]
	v_mfma_f32_16x16x32_bf16 v[58:61], v[194:197], v[182:185], v[58:61]
	v_mfma_f32_16x16x32_bf16 v[54:57], v[198:201], v[174:177], v[54:57]
	v_mfma_f32_16x16x32_bf16 v[50:53], v[198:201], v[182:185], v[50:53]
	v_mfma_f32_16x16x32_bf16 v[46:49], v[226:229], v[174:177], v[46:49]
	v_mfma_f32_16x16x32_bf16 v[42:45], v[226:229], v[182:185], v[42:45]
	v_mfma_f32_16x16x32_bf16 v[38:41], v[230:233], v[174:177], v[38:41]
	v_mfma_f32_16x16x32_bf16 v[34:37], v[230:233], v[182:185], v[34:37]
	v_mfma_f32_16x16x32_bf16 v[30:33], v[186:189], v[234:237], v[30:33]
	v_mfma_f32_16x16x32_bf16 v[26:29], v[186:189], v[242:245], v[26:29]
	v_mfma_f32_16x16x32_bf16 v[22:25], v[190:193], v[234:237], v[22:25]
	v_mfma_f32_16x16x32_bf16 v[18:21], v[190:193], v[242:245], v[18:21]
	v_mfma_f32_16x16x32_bf16 v[14:17], v[218:221], v[234:237], v[14:17]
	v_mfma_f32_16x16x32_bf16 v[10:13], v[218:221], v[242:245], v[10:13]
	v_mfma_f32_16x16x32_bf16 v[6:9], v[222:225], v[234:237], v[6:9]
	v_mfma_f32_16x16x32_bf16 v[2:5], v[222:225], v[242:245], v[2:5]
	v_mfma_f32_16x16x32_bf16 v[30:33], v[194:197], v[238:241], v[30:33]
	v_mfma_f32_16x16x32_bf16 v[26:29], v[194:197], v[246:249], v[26:29]
	v_mfma_f32_16x16x32_bf16 v[22:25], v[198:201], v[238:241], v[22:25]
	v_mfma_f32_16x16x32_bf16 v[18:21], v[198:201], v[246:249], v[18:21]
	v_mfma_f32_16x16x32_bf16 v[14:17], v[226:229], v[238:241], v[14:17]
	v_mfma_f32_16x16x32_bf16 v[10:13], v[226:229], v[246:249], v[10:13]
	v_mfma_f32_16x16x32_bf16 v[6:9], v[230:233], v[238:241], v[6:9]
	v_mfma_f32_16x16x32_bf16 v[2:5], v[230:233], v[246:249], v[2:5]
	s_setprio 0
	s_add_u32 vcc_lo, vcc_lo, s54
	s_addc_u32 vcc_hi, vcc_hi, s55
	s_add_i32 s4, s4, 2
	s_cmp_lt_u32 s4, 28
	v_lshl_add_u64 v[148:149], v[148:149], 0, s[54:55]
	s_barrier
	s_cbranch_scc1 .LBB0_341
	s_waitcnt vmcnt(6)
	v_or_b32_e32 v0, 0x10000, v152
	v_add_u32_e32 v155, 0x10800, v152
	v_or_b32_e32 v154, 0x10000, v153
	v_add_u32_e32 v156, 0x10800, v153
	v_or_b32_e32 v157, 0x14000, v152
	v_add_u32_e32 v159, 0x14800, v152
	v_or_b32_e32 v158, 0x14000, v153
	v_add_u32_e32 v160, 0x14800, v153
	v_or_b32_e32 v161, 0x18000, v152
	v_add_u32_e32 v163, 0x18800, v152
	v_or_b32_e32 v162, 0x18000, v153
	v_add_u32_e32 v164, 0x18800, v153
	v_or_b32_e32 v165, 0x1c000, v152
	v_add_u32_e32 v167, 0x1c800, v152
	v_or_b32_e32 v166, 0x1c000, v153
	v_add_u32_e32 v168, 0x1c800, v153
	s_mov_b64 s[2:3], 0xf80
	s_mov_b32 m0, s12
	v_lshl_add_u64 v[138:139], v[138:139], 0, s[2:3]
	ds_read_b128 v[140:143], v0
	ds_read_b128 v[144:147], v154
	ds_read_b128 v[152:155], v155
	ds_read_b128 v[170:173], v156
	ds_read_b128 v[174:177], v150
	ds_read_b128 v[178:181], v150 offset:2048
	ds_read_b128 v[182:185], v151
	ds_read_b128 v[186:189], v151 offset:2048
	ds_read_b128 v[190:193], v150 offset:4096
	ds_read_b128 v[194:197], v150 offset:6144
	ds_read_b128 v[198:201], v151 offset:4096
	ds_read_b128 v[218:221], v151 offset:6144
	global_load_lds_dwordx4 v[138:139], off
	v_lshl_add_u64 v[136:137], v[136:137], 0, s[2:3]
	s_mov_b32 m0, s5
	s_nop 0
	global_load_lds_dwordx4 v[136:137], off
	s_barrier
	s_waitcnt lgkmcnt(0)
	s_setprio 1
	s_waitcnt lgkmcnt(0)
	v_mfma_f32_16x16x32_bf16 v[126:129], v[174:177], v[140:143], v[126:129]
	v_mfma_f32_16x16x32_bf16 v[114:117], v[178:181], v[152:155], v[114:117]
	v_mfma_f32_16x16x32_bf16 v[110:113], v[190:193], v[140:143], v[110:113]
	v_mfma_f32_16x16x32_bf16 v[106:109], v[190:193], v[152:155], v[106:109]
	v_mfma_f32_16x16x32_bf16 v[126:129], v[182:185], v[144:147], v[126:129]
	v_mfma_f32_16x16x32_bf16 v[122:125], v[174:177], v[152:155], v[122:125]
	v_mfma_f32_16x16x32_bf16 v[118:121], v[178:181], v[140:143], v[118:121]
	v_mfma_f32_16x16x32_bf16 v[114:117], v[186:189], v[170:173], v[114:117]
	v_mfma_f32_16x16x32_bf16 v[110:113], v[198:201], v[144:147], v[110:113]
	v_mfma_f32_16x16x32_bf16 v[106:109], v[198:201], v[170:173], v[106:109]
	v_mfma_f32_16x16x32_bf16 v[102:105], v[194:197], v[140:143], v[102:105]
	v_mfma_f32_16x16x32_bf16 v[98:101], v[194:197], v[152:155], v[98:101]
	v_mfma_f32_16x16x32_bf16 v[136:139], v[182:185], v[170:173], v[122:125]
	v_mfma_f32_16x16x32_bf16 v[222:225], v[186:189], v[144:147], v[118:121]
	v_mfma_f32_16x16x32_bf16 v[226:229], v[218:221], v[144:147], v[102:105]
	v_mfma_f32_16x16x32_bf16 v[230:233], v[218:221], v[170:173], v[98:101]
	s_setprio 0
	s_barrier
	s_nop 1
	ds_read_b128 v[98:101], v157
	ds_read_b128 v[102:105], v158
	ds_read_b128 v[118:121], v159
	ds_read_b128 v[122:125], v160
	s_barrier
	s_waitcnt lgkmcnt(0)
	s_setprio 1
	s_waitcnt lgkmcnt(0)
	v_mfma_f32_16x16x32_bf16 v[94:97], v[174:177], v[98:101], v[94:97]
	v_mfma_f32_16x16x32_bf16 v[90:93], v[174:177], v[118:121], v[90:93]
	v_mfma_f32_16x16x32_bf16 v[78:81], v[190:193], v[98:101], v[78:81]
	v_mfma_f32_16x16x32_bf16 v[74:77], v[190:193], v[118:121], v[74:77]
	v_mfma_f32_16x16x32_bf16 v[94:97], v[182:185], v[102:105], v[94:97]
	v_mfma_f32_16x16x32_bf16 v[90:93], v[182:185], v[122:125], v[90:93]
	v_mfma_f32_16x16x32_bf16 v[86:89], v[178:181], v[98:101], v[86:89]
	v_mfma_f32_16x16x32_bf16 v[82:85], v[178:181], v[118:121], v[82:85]
	v_mfma_f32_16x16x32_bf16 v[78:81], v[198:201], v[102:105], v[78:81]
	v_mfma_f32_16x16x32_bf16 v[74:77], v[198:201], v[122:125], v[74:77]
	v_mfma_f32_16x16x32_bf16 v[70:73], v[194:197], v[98:101], v[70:73]
	v_mfma_f32_16x16x32_bf16 v[66:69], v[194:197], v[118:121], v[66:69]
	v_mfma_f32_16x16x32_bf16 v[156:159], v[186:189], v[102:105], v[86:89]
	v_mfma_f32_16x16x32_bf16 v[174:177], v[186:189], v[122:125], v[82:85]
	v_mfma_f32_16x16x32_bf16 v[178:181], v[218:221], v[102:105], v[70:73]
	v_mfma_f32_16x16x32_bf16 v[182:185], v[218:221], v[122:125], v[66:69]
	s_setprio 0
	s_barrier
	s_nop 1
	ds_read_b128 v[66:69], v150 offset:16384
	ds_read_b128 v[70:73], v150 offset:18432
	ds_read_b128 v[82:85], v151 offset:16384
	ds_read_b128 v[86:89], v151 offset:18432
	ds_read_b128 v[186:189], v150 offset:20480
	ds_read_b128 v[190:193], v150 offset:22528
	ds_read_b128 v[194:197], v151 offset:20480
	ds_read_b128 v[198:201], v151 offset:22528
	s_waitcnt vmcnt(4)
	s_barrier
	s_waitcnt lgkmcnt(0)
	s_setprio 1
	s_waitcnt lgkmcnt(0)
	v_mfma_f32_16x16x32_bf16 v[62:65], v[66:69], v[140:143], v[62:65]
	v_mfma_f32_16x16x32_bf16 v[54:57], v[70:73], v[140:143], v[54:57]
	v_mfma_f32_16x16x32_bf16 v[46:49], v[186:189], v[140:143], v[46:49]
	v_mfma_f32_16x16x32_bf16 v[38:41], v[190:193], v[140:143], v[38:41]
	v_mfma_f32_16x16x32_bf16 v[62:65], v[82:85], v[144:147], v[62:65]
	v_mfma_f32_16x16x32_bf16 v[58:61], v[66:69], v[152:155], v[58:61]
	v_mfma_f32_16x16x32_bf16 v[54:57], v[86:89], v[144:147], v[54:57]
	v_mfma_f32_16x16x32_bf16 v[50:53], v[70:73], v[152:155], v[50:53]
	v_mfma_f32_16x16x32_bf16 v[46:49], v[194:197], v[144:147], v[46:49]
	v_mfma_f32_16x16x32_bf16 v[42:45], v[186:189], v[152:155], v[42:45]
	v_mfma_f32_16x16x32_bf16 v[38:41], v[198:201], v[144:147], v[38:41]
	v_mfma_f32_16x16x32_bf16 v[34:37], v[190:193], v[152:155], v[34:37]
	v_mfma_f32_16x16x32_bf16 v[218:221], v[82:85], v[170:173], v[58:61]
	v_mfma_f32_16x16x32_bf16 v[234:237], v[86:89], v[170:173], v[50:53]
	v_mfma_f32_16x16x32_bf16 v[238:241], v[194:197], v[170:173], v[42:45]
	v_mfma_f32_16x16x32_bf16 v[140:143], v[198:201], v[170:173], v[34:37]
	s_setprio 0
	s_setprio 1
	v_mfma_f32_16x16x32_bf16 v[30:33], v[66:69], v[98:101], v[30:33]
	v_mfma_f32_16x16x32_bf16 v[22:25], v[70:73], v[98:101], v[22:25]
	v_mfma_f32_16x16x32_bf16 v[14:17], v[186:189], v[98:101], v[14:17]
	v_mfma_f32_16x16x32_bf16 v[6:9], v[190:193], v[98:101], v[6:9]
	v_mfma_f32_16x16x32_bf16 v[30:33], v[82:85], v[102:105], v[30:33]
	v_mfma_f32_16x16x32_bf16 v[26:29], v[66:69], v[118:121], v[26:29]
	v_mfma_f32_16x16x32_bf16 v[22:25], v[86:89], v[102:105], v[22:25]
	v_mfma_f32_16x16x32_bf16 v[18:21], v[70:73], v[118:121], v[18:21]
	v_mfma_f32_16x16x32_bf16 v[14:17], v[194:197], v[102:105], v[14:17]
	v_mfma_f32_16x16x32_bf16 v[10:13], v[186:189], v[118:121], v[10:13]
	v_mfma_f32_16x16x32_bf16 v[6:9], v[198:201], v[102:105], v[6:9]
	v_mfma_f32_16x16x32_bf16 v[2:5], v[190:193], v[118:121], v[2:5]
	v_mfma_f32_16x16x32_bf16 v[144:147], v[82:85], v[122:125], v[26:29]
	v_mfma_f32_16x16x32_bf16 v[152:155], v[86:89], v[122:125], v[18:21]
	v_mfma_f32_16x16x32_bf16 v[170:173], v[194:197], v[122:125], v[10:13]
	v_mfma_f32_16x16x32_bf16 v[186:189], v[198:201], v[122:125], v[2:5]
	s_setprio 0
	s_barrier
	s_nop 1
	ds_read_b128 v[2:5], v161
	ds_read_b128 v[10:13], v162
	ds_read_b128 v[160:163], v163
	ds_read_b128 v[190:193], v164
	ds_read_b128 v[18:21], v150 offset:32768
	ds_read_b128 v[26:29], v150 offset:34816
	ds_read_b128 v[34:37], v151 offset:32768
	ds_read_b128 v[42:45], v151 offset:34816
	ds_read_b128 v[50:53], v150 offset:36864
	ds_read_b128 v[58:61], v150 offset:38912
	ds_read_b128 v[194:197], v151 offset:36864
	ds_read_b128 v[198:201], v151 offset:38912
	s_waitcnt vmcnt(2)
	s_barrier
	s_waitcnt lgkmcnt(0)
	s_setprio 1
	s_waitcnt lgkmcnt(0)
	v_mfma_f32_16x16x32_bf16 v[66:69], v[18:21], v[2:5], v[126:129]
	v_mfma_f32_16x16x32_bf16 v[122:125], v[34:37], v[10:13], v[66:69]
	v_mfma_f32_16x16x32_bf16 v[66:69], v[18:21], v[160:163], v[136:139]
	v_mfma_f32_16x16x32_bf16 v[118:121], v[34:37], v[190:193], v[66:69]
	v_mfma_f32_16x16x32_bf16 v[66:69], v[26:29], v[2:5], v[222:225]
	v_mfma_f32_16x16x32_bf16 v[102:105], v[42:45], v[10:13], v[66:69]
	v_mfma_f32_16x16x32_bf16 v[66:69], v[26:29], v[160:163], v[114:117]
	v_mfma_f32_16x16x32_bf16 v[98:101], v[42:45], v[190:193], v[66:69]
	v_mfma_f32_16x16x32_bf16 v[66:69], v[50:53], v[2:5], v[110:113]
	v_mfma_f32_16x16x32_bf16 v[86:89], v[194:197], v[10:13], v[66:69]
	v_mfma_f32_16x16x32_bf16 v[66:69], v[50:53], v[160:163], v[106:109]
	v_mfma_f32_16x16x32_bf16 v[82:85], v[194:197], v[190:193], v[66:69]
	v_mfma_f32_16x16x32_bf16 v[66:69], v[58:61], v[2:5], v[226:229]
	v_mfma_f32_16x16x32_bf16 v[70:73], v[198:201], v[10:13], v[66:69]
	v_mfma_f32_16x16x32_bf16 v[66:69], v[58:61], v[160:163], v[230:233]
	v_mfma_f32_16x16x32_bf16 v[66:69], v[198:201], v[190:193], v[66:69]
	s_setprio 0
	s_barrier
	ds_read_b128 v[136:139], v165
	ds_read_b128 v[222:225], v166
	ds_read_b128 v[164:167], v167
	ds_read_b128 v[226:229], v168
	s_waitcnt vmcnt(0)
	s_barrier
	s_waitcnt lgkmcnt(0)
	s_setprio 1
	s_waitcnt lgkmcnt(0)
	v_mfma_f32_16x16x32_bf16 v[94:97], v[18:21], v[136:139], v[94:97]
	v_mfma_f32_16x16x32_bf16 v[18:21], v[18:21], v[164:167], v[90:93]
	v_mfma_f32_16x16x32_bf16 v[114:117], v[34:37], v[226:229], v[18:21]
	v_mfma_f32_16x16x32_bf16 v[18:21], v[26:29], v[136:139], v[156:159]
	v_mfma_f32_16x16x32_bf16 v[110:113], v[42:45], v[222:225], v[18:21]
	v_mfma_f32_16x16x32_bf16 v[18:21], v[26:29], v[164:167], v[174:177]
	v_mfma_f32_16x16x32_bf16 v[106:109], v[42:45], v[226:229], v[18:21]
	v_mfma_f32_16x16x32_bf16 v[18:21], v[50:53], v[136:139], v[78:81]
	v_mfma_f32_16x16x32_bf16 v[126:129], v[34:37], v[222:225], v[94:97]
	v_mfma_f32_16x16x32_bf16 v[94:97], v[194:197], v[222:225], v[18:21]
	v_mfma_f32_16x16x32_bf16 v[18:21], v[50:53], v[164:167], v[74:77]
	v_mfma_f32_16x16x32_bf16 v[90:93], v[194:197], v[226:229], v[18:21]
	v_mfma_f32_16x16x32_bf16 v[18:21], v[58:61], v[136:139], v[178:181]
	v_mfma_f32_16x16x32_bf16 v[78:81], v[198:201], v[222:225], v[18:21]
	v_mfma_f32_16x16x32_bf16 v[18:21], v[58:61], v[164:167], v[182:185]
	v_mfma_f32_16x16x32_bf16 v[74:77], v[198:201], v[226:229], v[18:21]
	s_setprio 0
	s_barrier
	ds_read_b128 v[156:159], v150 offset:49152
	ds_read_b128 v[174:177], v150 offset:51200
	ds_read_b128 v[178:181], v151 offset:49152
	ds_read_b128 v[182:185], v151 offset:51200
	ds_read_b128 v[194:197], v150 offset:53248
	ds_read_b128 v[198:201], v150 offset:55296
	ds_read_b128 v[230:233], v151 offset:53248
	ds_read_b128 v[148:151], v151 offset:55296
	s_barrier
	s_waitcnt lgkmcnt(0)
	s_setprio 1
	s_waitcnt lgkmcnt(0)
	v_mfma_f32_16x16x32_bf16 v[18:21], v[156:159], v[2:5], v[62:65]
	v_mfma_f32_16x16x32_bf16 v[58:61], v[178:181], v[10:13], v[18:21]
	v_mfma_f32_16x16x32_bf16 v[18:21], v[156:159], v[160:163], v[218:221]
	v_mfma_f32_16x16x32_bf16 v[50:53], v[178:181], v[190:193], v[18:21]
	v_mfma_f32_16x16x32_bf16 v[18:21], v[174:177], v[2:5], v[54:57]
	v_mfma_f32_16x16x32_bf16 v[42:45], v[182:185], v[10:13], v[18:21]
	v_mfma_f32_16x16x32_bf16 v[18:21], v[174:177], v[160:163], v[234:237]
	v_mfma_f32_16x16x32_bf16 v[34:37], v[182:185], v[190:193], v[18:21]
	v_mfma_f32_16x16x32_bf16 v[18:21], v[194:197], v[2:5], v[46:49]
	v_mfma_f32_16x16x32_bf16 v[2:5], v[198:201], v[2:5], v[38:41]
	v_mfma_f32_16x16x32_bf16 v[26:29], v[230:233], v[10:13], v[18:21]
	v_mfma_f32_16x16x32_bf16 v[18:21], v[194:197], v[160:163], v[238:241]
	v_mfma_f32_16x16x32_bf16 v[10:13], v[148:151], v[10:13], v[2:5]
	v_mfma_f32_16x16x32_bf16 v[2:5], v[198:201], v[160:163], v[140:143]
	v_mfma_f32_16x16x32_bf16 v[18:21], v[230:233], v[190:193], v[18:21]
	v_mfma_f32_16x16x32_bf16 v[2:5], v[148:151], v[190:193], v[2:5]
	s_setprio 0
	s_setprio 1
	v_mfma_f32_16x16x32_bf16 v[30:33], v[156:159], v[136:139], v[30:33]
	v_mfma_f32_16x16x32_bf16 v[62:65], v[178:181], v[222:225], v[30:33]
	v_mfma_f32_16x16x32_bf16 v[30:33], v[156:159], v[164:167], v[144:147]
	v_mfma_f32_16x16x32_bf16 v[22:25], v[174:177], v[136:139], v[22:25]
	v_mfma_f32_16x16x32_bf16 v[14:17], v[194:197], v[136:139], v[14:17]
	v_mfma_f32_16x16x32_bf16 v[54:57], v[178:181], v[226:229], v[30:33]
	v_mfma_f32_16x16x32_bf16 v[46:49], v[182:185], v[222:225], v[22:25]
	v_mfma_f32_16x16x32_bf16 v[22:25], v[174:177], v[164:167], v[152:155]
	v_mfma_f32_16x16x32_bf16 v[30:33], v[230:233], v[222:225], v[14:17]
	v_mfma_f32_16x16x32_bf16 v[14:17], v[194:197], v[164:167], v[170:173]
	v_mfma_f32_16x16x32_bf16 v[6:9], v[198:201], v[136:139], v[6:9]
	v_mfma_f32_16x16x32_bf16 v[38:41], v[182:185], v[226:229], v[22:25]
	v_mfma_f32_16x16x32_bf16 v[22:25], v[230:233], v[226:229], v[14:17]
	v_mfma_f32_16x16x32_bf16 v[14:17], v[148:151], v[222:225], v[6:9]
	v_mfma_f32_16x16x32_bf16 v[6:9], v[198:201], v[164:167], v[186:189]
	v_mfma_f32_16x16x32_bf16 v[6:9], v[148:151], v[226:229], v[6:9]
	s_setprio 0
	s_cmpk_gt_u32 s0, 0xff
	s_barrier
	s_cbranch_scc1 .LBB0_344
	s_barrier

.LBB0_348:
	s_lshl_b32 s16, s16, 5
	v_and_b32_e32 v19, 15, v17
	s_and_b32 s16, s16, 0x60
	v_lshlrev_b32_e32 v20, 7, v19
	v_or_b32_e32 v19, s16, v19
	s_add_i32 s16, s1, 0x18000
	s_mov_b64 s[20:21], 0x80
	v_lshl_or_b32 v20, s17, 13, v20
	v_lshl_add_u64 v[6:7], v[6:7], 0, s[20:21]
	s_mov_b32 m0, s16
	s_add_i32 s17, s1, 0x1a000
	s_waitcnt vmcnt(4)
	s_barrier
	global_load_lds_dwordx4 v[6:7], off
	v_lshl_add_u64 v[6:7], v[8:9], 0, s[20:21]
	s_mov_b32 m0, s17
	s_add_i32 s18, s1, 0x8000
	global_load_lds_dwordx4 v[6:7], off
	v_lshl_add_u64 v[6:7], v[12:13], 0, s[20:21]
	s_mov_b32 m0, s18
	s_add_i32 s19, s1, 0xa000
	global_load_lds_dwordx4 v[6:7], off
	v_lshl_add_u64 v[6:7], v[10:11], 0, s[20:21]
	s_mov_b32 m0, s19
	v_lshl_add_u64 v[4:5], v[4:5], 0, s[50:51]
	s_add_i32 s20, s1, 0x1c000
	global_load_lds_dwordx4 v[6:7], off
	v_lshl_add_u64 v[6:7], v[0:1], 1, v[4:5]
	s_mov_b32 m0, s20
	s_add_i32 s21, s1, 0x1e000
	global_load_lds_dwordx4 v[6:7], off
	v_lshl_add_u64 v[2:3], v[2:3], 1, v[4:5]
	s_mov_b32 m0, s21
	v_and_b32_e32 v21, 3, v18
	global_load_lds_dwordx4 v[2:3], off
	v_bfe_u32 v17, v17, 1, 3
	v_add_u32_e32 v0, v16, v14
	v_bitop3_b32 v18, v18, v17, 3 bitop3:0x6c
	v_bitop3_b32 v17, v21, v17, 4 bitop3:0x36
	s_waitcnt vmcnt(6)
	v_lshlrev_b64 v[2:3], 1, v[0:1]
	v_add_u32_e32 v0, v15, v14
	v_lshlrev_b32_e32 v18, 4, v18
	v_lshlrev_b32_e32 v17, 4, v17
	v_lshlrev_b32_e32 v19, 7, v19
	v_lshl_add_u64 v[140:141], s[4:5], 0, v[2:3]
	v_lshlrev_b64 v[4:5], 1, v[0:1]
	v_lshl_add_u64 v[144:145], v[2:3], 0, s[90:91]
	v_mov_b32_e32 v2, 0
	v_or_b32_e32 v148, v18, v20
	v_or_b32_e32 v150, v19, v18
	v_or_b32_e32 v149, v17, v20
	v_or_b32_e32 v151, v19, v17
	v_lshl_add_u64 v[142:143], s[4:5], 0, v[4:5]
	v_lshl_add_u64 v[146:147], v[4:5], 0, s[90:91]
	s_mov_b32 s4, -2
	v_mov_b32_e32 v3, v2
	v_mov_b32_e32 v4, v2
	v_mov_b32_e32 v5, v2
	v_mov_b32_e32 v6, v2
	v_mov_b32_e32 v7, v2
	v_mov_b32_e32 v8, v2
	v_mov_b32_e32 v9, v2
	v_mov_b32_e32 v10, v2
	v_mov_b32_e32 v11, v2
	v_mov_b32_e32 v12, v2
	v_mov_b32_e32 v13, v2
	v_mov_b32_e32 v14, v2
	v_mov_b32_e32 v15, v2
	v_mov_b32_e32 v16, v2
	v_mov_b32_e32 v17, v2
	v_mov_b32_e32 v18, v2
	v_mov_b32_e32 v19, v2
	v_mov_b32_e32 v20, v2
	v_mov_b32_e32 v21, v2
	v_mov_b32_e32 v22, v2
	v_mov_b32_e32 v23, v2
	v_mov_b32_e32 v24, v2
	v_mov_b32_e32 v25, v2
	v_mov_b32_e32 v26, v2
	v_mov_b32_e32 v27, v2
	v_mov_b32_e32 v28, v2
	v_mov_b32_e32 v29, v2
	v_mov_b32_e32 v30, v2
	v_mov_b32_e32 v31, v2
	v_mov_b32_e32 v32, v2
	v_mov_b32_e32 v33, v2
	v_mov_b32_e32 v34, v2
	v_mov_b32_e32 v35, v2
	v_mov_b32_e32 v36, v2
	v_mov_b32_e32 v37, v2
	v_mov_b32_e32 v38, v2
	v_mov_b32_e32 v39, v2
	v_mov_b32_e32 v40, v2
	v_mov_b32_e32 v41, v2
	v_mov_b32_e32 v42, v2
	v_mov_b32_e32 v43, v2
	v_mov_b32_e32 v44, v2
	v_mov_b32_e32 v45, v2
	v_mov_b32_e32 v46, v2
	v_mov_b32_e32 v47, v2
	v_mov_b32_e32 v48, v2
	v_mov_b32_e32 v49, v2
	v_mov_b32_e32 v50, v2
	v_mov_b32_e32 v51, v2
	v_mov_b32_e32 v52, v2
	v_mov_b32_e32 v53, v2
	v_mov_b32_e32 v54, v2
	v_mov_b32_e32 v55, v2
	v_mov_b32_e32 v56, v2
	v_mov_b32_e32 v57, v2
	v_mov_b32_e32 v58, v2
	v_mov_b32_e32 v59, v2
	v_mov_b32_e32 v60, v2
	v_mov_b32_e32 v61, v2
	v_mov_b32_e32 v62, v2
	v_mov_b32_e32 v63, v2
	v_mov_b32_e32 v64, v2
	v_mov_b32_e32 v65, v2
	v_mov_b32_e32 v66, v2
	v_mov_b32_e32 v67, v2
	v_mov_b32_e32 v68, v2
	v_mov_b32_e32 v69, v2
	v_mov_b32_e32 v70, v2
	v_mov_b32_e32 v71, v2
	v_mov_b32_e32 v72, v2
	v_mov_b32_e32 v73, v2
	v_mov_b32_e32 v74, v2
	v_mov_b32_e32 v75, v2
	v_mov_b32_e32 v76, v2
	v_mov_b32_e32 v77, v2
	v_mov_b32_e32 v78, v2
	v_mov_b32_e32 v79, v2
	v_mov_b32_e32 v80, v2
	v_mov_b32_e32 v81, v2
	v_mov_b32_e32 v82, v2
	v_mov_b32_e32 v83, v2
	v_mov_b32_e32 v84, v2
	v_mov_b32_e32 v85, v2
	v_mov_b32_e32 v86, v2
	v_mov_b32_e32 v87, v2
	v_mov_b32_e32 v88, v2
	v_mov_b32_e32 v89, v2
	v_mov_b32_e32 v90, v2
	v_mov_b32_e32 v91, v2
	v_mov_b32_e32 v92, v2
	v_mov_b32_e32 v93, v2
	v_mov_b32_e32 v94, v2
	v_mov_b32_e32 v95, v2
	v_mov_b32_e32 v96, v2
	v_mov_b32_e32 v97, v2
	v_mov_b32_e32 v98, v2
	v_mov_b32_e32 v99, v2
	v_mov_b32_e32 v100, v2
	v_mov_b32_e32 v101, v2
	v_mov_b32_e32 v102, v2
	v_mov_b32_e32 v103, v2
	v_mov_b32_e32 v104, v2
	v_mov_b32_e32 v105, v2
	v_mov_b32_e32 v106, v2
	v_mov_b32_e32 v107, v2
	v_mov_b32_e32 v108, v2
	v_mov_b32_e32 v109, v2
	v_mov_b32_e32 v110, v2
	v_mov_b32_e32 v111, v2
	v_mov_b32_e32 v112, v2
	v_mov_b32_e32 v113, v2
	v_mov_b32_e32 v114, v2
	v_mov_b32_e32 v115, v2
	v_mov_b32_e32 v116, v2
	v_mov_b32_e32 v117, v2
	v_mov_b32_e32 v118, v2
	v_mov_b32_e32 v119, v2
	v_mov_b32_e32 v120, v2
	v_mov_b32_e32 v121, v2
	v_mov_b32_e32 v122, v2
	v_mov_b32_e32 v123, v2
	v_mov_b32_e32 v124, v2
	v_mov_b32_e32 v125, v2
	v_mov_b32_e32 v126, v2
	v_mov_b32_e32 v127, v2
	v_mov_b32_e32 v128, v2
	v_mov_b32_e32 v129, v2
	s_mov_b64 s[24:25], 0x82d4900
	s_mov_b64 s[26:27], 0x8254980
	s_mov_b64 s[28:29], 0x82d4980
	s_waitcnt lgkmcnt(0)
	s_sub_u32 s100, s100, 0x40000000
	s_subb_u32 s101, s101, 0
	s_mov_b64 vcc, s[100:101]
	v_lshl_add_u64 v[206:207], v[132:133], 0, v[142:143]
	v_subrev_u32_e32 v206, vcc_lo, v206
	v_lshl_add_u64 v[208:209], v[132:133], 0, v[140:141]
	v_subrev_u32_e32 v208, vcc_lo, v208
	v_lshl_add_u64 v[210:211], v[132:133], 0, v[146:147]
	v_subrev_u32_e32 v210, vcc_lo, v210
	v_lshl_add_u64 v[214:215], v[132:133], 0, v[144:145]
	v_subrev_u32_e32 v214, vcc_lo, v214
	v_add_u32_e32 v207, 0x10000, v150
	v_add_u32_e32 v209, 0x10000, v151
	s_barrier
.LBB0_349:
	ds_read_b128 v[160:163], v207
	ds_read_b128 v[164:167], v209
	ds_read_b128 v[168:171], v207 offset:2048
	ds_read_b128 v[172:175], v209 offset:2048
	s_add_i32 s22, s1, 0xc000
	s_mov_b32 m0, s22
	s_add_i32 s5, s1, 0xe000
	ds_read_b128 v[176:179], v148
	ds_read_b128 v[180:183], v148 offset:2048
	ds_read_b128 v[184:187], v149
	ds_read_b128 v[188:191], v149 offset:2048
	ds_read_b128 v[192:195], v148 offset:4096
	ds_read_b128 v[196:199], v148 offset:6144
	ds_read_b128 v[200:203], v149 offset:4096
	ds_read_b128 v[218:221], v149 offset:6144
	s_add_u32 s100, vcc_lo, s50
	s_addc_u32 s101, vcc_hi, s51
	global_load_lds_dwordx4 v206, s[100:101]
	s_mov_b32 m0, s5
	s_add_u32 s100, vcc_lo, s50
	s_addc_u32 s101, vcc_hi, s51
	global_load_lds_dwordx4 v208, s[100:101]
	s_waitcnt lgkmcnt(8)
	s_waitcnt vmcnt(10)
	s_barrier
	s_waitcnt lgkmcnt(0)
	s_setprio 1
	s_waitcnt lgkmcnt(0)
	v_mfma_f32_16x16x32_bf16 v[126:129], v[160:163], v[176:179], v[126:129]
	v_mfma_f32_16x16x32_bf16 v[122:125], v[168:171], v[176:179], v[122:125]
	v_mfma_f32_16x16x32_bf16 v[118:121], v[160:163], v[180:183], v[118:121]
	v_mfma_f32_16x16x32_bf16 v[114:117], v[168:171], v[180:183], v[114:117]
	v_mfma_f32_16x16x32_bf16 v[110:113], v[160:163], v[192:195], v[110:113]
	v_mfma_f32_16x16x32_bf16 v[106:109], v[168:171], v[192:195], v[106:109]
	v_mfma_f32_16x16x32_bf16 v[102:105], v[160:163], v[196:199], v[102:105]
	v_mfma_f32_16x16x32_bf16 v[98:101], v[168:171], v[196:199], v[98:101]
	v_mfma_f32_16x16x32_bf16 v[126:129], v[164:167], v[184:187], v[126:129]
	v_mfma_f32_16x16x32_bf16 v[122:125], v[172:175], v[184:187], v[122:125]
	v_mfma_f32_16x16x32_bf16 v[118:121], v[164:167], v[188:191], v[118:121]
	v_mfma_f32_16x16x32_bf16 v[114:117], v[172:175], v[188:191], v[114:117]
	v_mfma_f32_16x16x32_bf16 v[110:113], v[164:167], v[200:203], v[110:113]
	v_mfma_f32_16x16x32_bf16 v[106:109], v[172:175], v[200:203], v[106:109]
	v_mfma_f32_16x16x32_bf16 v[102:105], v[164:167], v[218:221], v[102:105]
	v_mfma_f32_16x16x32_bf16 v[98:101], v[172:175], v[218:221], v[98:101]
	s_setprio 0
	s_barrier
	s_mov_b32 m0, s2
	ds_read_b128 v[222:225], v207 offset:16384
	ds_read_b128 v[226:229], v209 offset:16384
	ds_read_b128 v[230:233], v207 offset:18432
	ds_read_b128 v[234:237], v209 offset:18432
	s_add_u32 s100, vcc_lo, s70
	s_addc_u32 s101, vcc_hi, s71
	global_load_lds_dwordx4 v210, s[100:101]
	s_mov_b32 m0, s3
	s_add_u32 s100, vcc_lo, s70
	s_addc_u32 s101, vcc_hi, s71
	global_load_lds_dwordx4 v214, s[100:101]
	s_waitcnt vmcnt(10)
	s_waitcnt lgkmcnt(0)
	s_barrier
	s_waitcnt lgkmcnt(0)
	s_setprio 1
	s_waitcnt lgkmcnt(0)
	v_mfma_f32_16x16x32_bf16 v[94:97], v[222:225], v[176:179], v[94:97]
	v_mfma_f32_16x16x32_bf16 v[90:93], v[230:233], v[176:179], v[90:93]
	v_mfma_f32_16x16x32_bf16 v[86:89], v[222:225], v[180:183], v[86:89]
	v_mfma_f32_16x16x32_bf16 v[82:85], v[230:233], v[180:183], v[82:85]
	v_mfma_f32_16x16x32_bf16 v[78:81], v[222:225], v[192:195], v[78:81]
	v_mfma_f32_16x16x32_bf16 v[74:77], v[230:233], v[192:195], v[74:77]
	v_mfma_f32_16x16x32_bf16 v[70:73], v[222:225], v[196:199], v[70:73]
	v_mfma_f32_16x16x32_bf16 v[66:69], v[230:233], v[196:199], v[66:69]
	v_mfma_f32_16x16x32_bf16 v[94:97], v[226:229], v[184:187], v[94:97]
	v_mfma_f32_16x16x32_bf16 v[90:93], v[234:237], v[184:187], v[90:93]
	v_mfma_f32_16x16x32_bf16 v[86:89], v[226:229], v[188:191], v[86:89]
	v_mfma_f32_16x16x32_bf16 v[82:85], v[234:237], v[188:191], v[82:85]
	v_mfma_f32_16x16x32_bf16 v[78:81], v[226:229], v[200:203], v[78:81]
	v_mfma_f32_16x16x32_bf16 v[74:77], v[234:237], v[200:203], v[74:77]
	v_mfma_f32_16x16x32_bf16 v[70:73], v[226:229], v[218:221], v[70:73]
	v_mfma_f32_16x16x32_bf16 v[66:69], v[234:237], v[218:221], v[66:69]
	s_setprio 0
	s_mov_b32 m0, s1
	s_barrier
	ds_read_b128 v[176:179], v148 offset:16384
	ds_read_b128 v[180:183], v148 offset:18432
	ds_read_b128 v[184:187], v149 offset:16384
	ds_read_b128 v[188:191], v149 offset:18432
	ds_read_b128 v[192:195], v148 offset:20480
	ds_read_b128 v[196:199], v148 offset:22528
	ds_read_b128 v[200:203], v149 offset:20480
	ds_read_b128 v[218:221], v149 offset:22528
	s_add_u32 s100, vcc_lo, s54
	s_addc_u32 s101, vcc_hi, s55
	global_load_lds_dwordx4 v206, s[100:101]
	s_mov_b32 m0, s9
	s_add_u32 s100, vcc_lo, s54
	s_addc_u32 s101, vcc_hi, s55
	global_load_lds_dwordx4 v208, s[100:101]
	s_mov_b32 m0, s11
	s_add_u32 s100, vcc_lo, s24
	s_addc_u32 s101, vcc_hi, s25
	global_load_lds_dwordx4 v210, s[100:101]
	s_mov_b32 m0, s12
	s_add_u32 s100, vcc_lo, s24
	s_addc_u32 s101, vcc_hi, s25
	global_load_lds_dwordx4 v214, s[100:101]
	s_waitcnt vmcnt(10)
	s_waitcnt lgkmcnt(0)
	s_barrier
	s_waitcnt lgkmcnt(0)
	s_setprio 1
	s_waitcnt lgkmcnt(0)
	v_mfma_f32_16x16x32_bf16 v[62:65], v[160:163], v[176:179], v[62:65]
	v_mfma_f32_16x16x32_bf16 v[58:61], v[168:171], v[176:179], v[58:61]
	v_mfma_f32_16x16x32_bf16 v[54:57], v[160:163], v[180:183], v[54:57]
	v_mfma_f32_16x16x32_bf16 v[50:53], v[168:171], v[180:183], v[50:53]
	v_mfma_f32_16x16x32_bf16 v[46:49], v[160:163], v[192:195], v[46:49]
	v_mfma_f32_16x16x32_bf16 v[42:45], v[168:171], v[192:195], v[42:45]
	v_mfma_f32_16x16x32_bf16 v[38:41], v[160:163], v[196:199], v[38:41]
	v_mfma_f32_16x16x32_bf16 v[34:37], v[168:171], v[196:199], v[34:37]
	v_mfma_f32_16x16x32_bf16 v[62:65], v[164:167], v[184:187], v[62:65]
	v_mfma_f32_16x16x32_bf16 v[58:61], v[172:175], v[184:187], v[58:61]
	v_mfma_f32_16x16x32_bf16 v[54:57], v[164:167], v[188:191], v[54:57]
	v_mfma_f32_16x16x32_bf16 v[50:53], v[172:175], v[188:191], v[50:53]
	v_mfma_f32_16x16x32_bf16 v[46:49], v[164:167], v[200:203], v[46:49]
	v_mfma_f32_16x16x32_bf16 v[42:45], v[172:175], v[200:203], v[42:45]
	v_mfma_f32_16x16x32_bf16 v[38:41], v[164:167], v[218:221], v[38:41]
	v_mfma_f32_16x16x32_bf16 v[34:37], v[172:175], v[218:221], v[34:37]
	v_mfma_f32_16x16x32_bf16 v[30:33], v[222:225], v[176:179], v[30:33]
	v_mfma_f32_16x16x32_bf16 v[26:29], v[230:233], v[176:179], v[26:29]
	v_mfma_f32_16x16x32_bf16 v[22:25], v[222:225], v[180:183], v[22:25]
	v_mfma_f32_16x16x32_bf16 v[18:21], v[230:233], v[180:183], v[18:21]
	v_mfma_f32_16x16x32_bf16 v[14:17], v[222:225], v[192:195], v[14:17]
	v_mfma_f32_16x16x32_bf16 v[10:13], v[230:233], v[192:195], v[10:13]
	v_mfma_f32_16x16x32_bf16 v[6:9], v[222:225], v[196:199], v[6:9]
	v_mfma_f32_16x16x32_bf16 v[2:5], v[230:233], v[196:199], v[2:5]
	v_mfma_f32_16x16x32_bf16 v[30:33], v[226:229], v[184:187], v[30:33]
	v_mfma_f32_16x16x32_bf16 v[26:29], v[234:237], v[184:187], v[26:29]
	v_mfma_f32_16x16x32_bf16 v[22:25], v[226:229], v[188:191], v[22:25]
	v_mfma_f32_16x16x32_bf16 v[18:21], v[234:237], v[188:191], v[18:21]
	v_mfma_f32_16x16x32_bf16 v[14:17], v[226:229], v[200:203], v[14:17]
	v_mfma_f32_16x16x32_bf16 v[10:13], v[234:237], v[200:203], v[10:13]
	v_mfma_f32_16x16x32_bf16 v[6:9], v[226:229], v[218:221], v[6:9]
	v_mfma_f32_16x16x32_bf16 v[2:5], v[234:237], v[218:221], v[2:5]
	s_setprio 0
	s_barrier
	ds_read_b128 v[168:171], v207 offset:32768
	ds_read_b128 v[172:175], v209 offset:32768
	ds_read_b128 v[176:179], v207 offset:34816
	ds_read_b128 v[180:183], v209 offset:34816
	s_mov_b32 m0, s13
	ds_read_b128 v[184:187], v148 offset:32768
	ds_read_b128 v[188:191], v148 offset:34816
	ds_read_b128 v[192:195], v149 offset:32768
	ds_read_b128 v[196:199], v149 offset:34816
	ds_read_b128 v[200:203], v148 offset:36864
	ds_read_b128 v[218:221], v148 offset:38912
	ds_read_b128 v[222:225], v149 offset:36864
	ds_read_b128 v[226:229], v149 offset:38912
	s_add_u32 s100, vcc_lo, s58
	s_addc_u32 s101, vcc_hi, s59
	global_load_lds_dwordx4 v206, s[100:101]
	s_mov_b32 m0, s15
	s_add_u32 s100, vcc_lo, s58
	s_addc_u32 s101, vcc_hi, s59
	global_load_lds_dwordx4 v208, s[100:101]
	s_waitcnt lgkmcnt(8)
	s_waitcnt vmcnt(10)
	s_barrier
	s_waitcnt lgkmcnt(0)
	s_setprio 1
	s_waitcnt lgkmcnt(0)
	v_mfma_f32_16x16x32_bf16 v[126:129], v[168:171], v[184:187], v[126:129]
	v_mfma_f32_16x16x32_bf16 v[122:125], v[176:179], v[184:187], v[122:125]
	v_mfma_f32_16x16x32_bf16 v[118:121], v[168:171], v[188:191], v[118:121]
	v_mfma_f32_16x16x32_bf16 v[114:117], v[176:179], v[188:191], v[114:117]
	v_mfma_f32_16x16x32_bf16 v[110:113], v[168:171], v[200:203], v[110:113]
	v_mfma_f32_16x16x32_bf16 v[106:109], v[176:179], v[200:203], v[106:109]
	v_mfma_f32_16x16x32_bf16 v[102:105], v[168:171], v[218:221], v[102:105]
	v_mfma_f32_16x16x32_bf16 v[98:101], v[176:179], v[218:221], v[98:101]
	v_mfma_f32_16x16x32_bf16 v[126:129], v[172:175], v[192:195], v[126:129]
	v_mfma_f32_16x16x32_bf16 v[122:125], v[180:183], v[192:195], v[122:125]
	v_mfma_f32_16x16x32_bf16 v[118:121], v[172:175], v[196:199], v[118:121]
	v_mfma_f32_16x16x32_bf16 v[114:117], v[180:183], v[196:199], v[114:117]
	v_mfma_f32_16x16x32_bf16 v[110:113], v[172:175], v[222:225], v[110:113]
	v_mfma_f32_16x16x32_bf16 v[106:109], v[180:183], v[222:225], v[106:109]
	v_mfma_f32_16x16x32_bf16 v[102:105], v[172:175], v[226:229], v[102:105]
	v_mfma_f32_16x16x32_bf16 v[98:101], v[180:183], v[226:229], v[98:101]
	s_setprio 0
	s_barrier
	s_mov_b32 m0, s16
	ds_read_b128 v[230:233], v207 offset:49152
	ds_read_b128 v[234:237], v209 offset:49152
	ds_read_b128 v[238:241], v207 offset:51200
	ds_read_b128 v[242:245], v209 offset:51200
	s_add_u32 s100, vcc_lo, s26
	s_addc_u32 s101, vcc_hi, s27
	global_load_lds_dwordx4 v210, s[100:101]
	s_mov_b32 m0, s17
	s_add_u32 s100, vcc_lo, s26
	s_addc_u32 s101, vcc_hi, s27
	global_load_lds_dwordx4 v214, s[100:101]
	s_waitcnt vmcnt(10)
	s_waitcnt lgkmcnt(0)
	s_barrier
	s_waitcnt lgkmcnt(0)
	s_setprio 1
	s_waitcnt lgkmcnt(0)
	v_mfma_f32_16x16x32_bf16 v[94:97], v[230:233], v[184:187], v[94:97]
	v_mfma_f32_16x16x32_bf16 v[90:93], v[238:241], v[184:187], v[90:93]
	v_mfma_f32_16x16x32_bf16 v[86:89], v[230:233], v[188:191], v[86:89]
	v_mfma_f32_16x16x32_bf16 v[82:85], v[238:241], v[188:191], v[82:85]
	v_mfma_f32_16x16x32_bf16 v[78:81], v[230:233], v[200:203], v[78:81]
	v_mfma_f32_16x16x32_bf16 v[74:77], v[238:241], v[200:203], v[74:77]
	v_mfma_f32_16x16x32_bf16 v[70:73], v[230:233], v[218:221], v[70:73]
	v_mfma_f32_16x16x32_bf16 v[66:69], v[238:241], v[218:221], v[66:69]
	v_mfma_f32_16x16x32_bf16 v[94:97], v[234:237], v[192:195], v[94:97]
	v_mfma_f32_16x16x32_bf16 v[90:93], v[242:245], v[192:195], v[90:93]
	v_mfma_f32_16x16x32_bf16 v[86:89], v[234:237], v[196:199], v[86:89]
	v_mfma_f32_16x16x32_bf16 v[82:85], v[242:245], v[196:199], v[82:85]
	v_mfma_f32_16x16x32_bf16 v[78:81], v[234:237], v[222:225], v[78:81]
	v_mfma_f32_16x16x32_bf16 v[74:77], v[242:245], v[222:225], v[74:77]
	v_mfma_f32_16x16x32_bf16 v[70:73], v[234:237], v[226:229], v[70:73]
	v_mfma_f32_16x16x32_bf16 v[66:69], v[242:245], v[226:229], v[66:69]
	s_setprio 0
	s_mov_b32 m0, s18
	s_barrier
	ds_read_b128 v[184:187], v148 offset:49152
	ds_read_b128 v[188:191], v148 offset:51200
	ds_read_b128 v[192:195], v149 offset:49152
	ds_read_b128 v[196:199], v149 offset:51200
	ds_read_b128 v[200:203], v148 offset:53248
	ds_read_b128 v[218:221], v148 offset:55296
	ds_read_b128 v[222:225], v149 offset:53248
	ds_read_b128 v[226:229], v149 offset:55296
	s_add_u32 s100, vcc_lo, s62
	s_addc_u32 s101, vcc_hi, s63
	global_load_lds_dwordx4 v206, s[100:101]
	s_mov_b32 m0, s19
	s_add_u32 s100, vcc_lo, s62
	s_addc_u32 s101, vcc_hi, s63
	global_load_lds_dwordx4 v208, s[100:101]
	s_mov_b32 m0, s20
	s_add_u32 s100, vcc_lo, s28
	s_addc_u32 s101, vcc_hi, s29
	global_load_lds_dwordx4 v210, s[100:101]
	s_mov_b32 m0, s21
	s_add_u32 s100, vcc_lo, s28
	s_addc_u32 s101, vcc_hi, s29
	global_load_lds_dwordx4 v214, s[100:101]
	s_waitcnt vmcnt(10)
	s_waitcnt lgkmcnt(0)
	s_barrier
	s_waitcnt lgkmcnt(0)
	s_setprio 1
	s_waitcnt lgkmcnt(0)
	v_mfma_f32_16x16x32_bf16 v[62:65], v[168:171], v[184:187], v[62:65]
	v_mfma_f32_16x16x32_bf16 v[58:61], v[176:179], v[184:187], v[58:61]
	v_mfma_f32_16x16x32_bf16 v[54:57], v[168:171], v[188:191], v[54:57]
	v_mfma_f32_16x16x32_bf16 v[50:53], v[176:179], v[188:191], v[50:53]
	v_mfma_f32_16x16x32_bf16 v[46:49], v[168:171], v[200:203], v[46:49]
	v_mfma_f32_16x16x32_bf16 v[42:45], v[176:179], v[200:203], v[42:45]
	v_mfma_f32_16x16x32_bf16 v[38:41], v[168:171], v[218:221], v[38:41]
	v_mfma_f32_16x16x32_bf16 v[34:37], v[176:179], v[218:221], v[34:37]
	v_mfma_f32_16x16x32_bf16 v[62:65], v[172:175], v[192:195], v[62:65]
	v_mfma_f32_16x16x32_bf16 v[58:61], v[180:183], v[192:195], v[58:61]
	v_mfma_f32_16x16x32_bf16 v[54:57], v[172:175], v[196:199], v[54:57]
	v_mfma_f32_16x16x32_bf16 v[50:53], v[180:183], v[196:199], v[50:53]
	v_mfma_f32_16x16x32_bf16 v[46:49], v[172:175], v[222:225], v[46:49]
	v_mfma_f32_16x16x32_bf16 v[42:45], v[180:183], v[222:225], v[42:45]
	v_mfma_f32_16x16x32_bf16 v[38:41], v[172:175], v[226:229], v[38:41]
	v_mfma_f32_16x16x32_bf16 v[34:37], v[180:183], v[226:229], v[34:37]
	v_mfma_f32_16x16x32_bf16 v[30:33], v[230:233], v[184:187], v[30:33]
	v_mfma_f32_16x16x32_bf16 v[26:29], v[238:241], v[184:187], v[26:29]
	v_mfma_f32_16x16x32_bf16 v[22:25], v[230:233], v[188:191], v[22:25]
	v_mfma_f32_16x16x32_bf16 v[18:21], v[238:241], v[188:191], v[18:21]
	v_mfma_f32_16x16x32_bf16 v[14:17], v[230:233], v[200:203], v[14:17]
	v_mfma_f32_16x16x32_bf16 v[10:13], v[238:241], v[200:203], v[10:13]
	v_mfma_f32_16x16x32_bf16 v[6:9], v[230:233], v[218:221], v[6:9]
	v_mfma_f32_16x16x32_bf16 v[2:5], v[238:241], v[218:221], v[2:5]
	v_mfma_f32_16x16x32_bf16 v[30:33], v[234:237], v[192:195], v[30:33]
	v_mfma_f32_16x16x32_bf16 v[26:29], v[242:245], v[192:195], v[26:29]
	v_mfma_f32_16x16x32_bf16 v[22:25], v[234:237], v[196:199], v[22:25]
	v_mfma_f32_16x16x32_bf16 v[18:21], v[242:245], v[196:199], v[18:21]
	v_mfma_f32_16x16x32_bf16 v[14:17], v[234:237], v[222:225], v[14:17]
	v_mfma_f32_16x16x32_bf16 v[10:13], v[242:245], v[222:225], v[10:13]
	v_mfma_f32_16x16x32_bf16 v[6:9], v[234:237], v[226:229], v[6:9]
	v_mfma_f32_16x16x32_bf16 v[2:5], v[242:245], v[226:229], v[2:5]
	s_setprio 0
	s_add_u32 vcc_lo, vcc_lo, s54
	s_addc_u32 vcc_hi, vcc_hi, s55
	s_add_i32 s4, s4, 2
	s_cmp_lt_u32 s4, 28
	v_lshl_add_u64 v[132:133], v[132:133], 0, s[54:55]
	s_barrier
	s_cbranch_scc1 .LBB0_349
	s_waitcnt vmcnt(6)
	v_or_b32_e32 v0, 0x10000, v150
	v_add_u32_e32 v153, 0x10800, v150
	v_or_b32_e32 v152, 0x10000, v151
	v_add_u32_e32 v154, 0x10800, v151
	v_or_b32_e32 v155, 0x14000, v150
	v_add_u32_e32 v157, 0x14800, v150
	v_or_b32_e32 v156, 0x14000, v151
	v_add_u32_e32 v158, 0x14800, v151
	v_or_b32_e32 v159, 0x18000, v150
	v_add_u32_e32 v161, 0x18800, v150
	v_or_b32_e32 v160, 0x18000, v151
	v_add_u32_e32 v162, 0x18800, v151
	v_or_b32_e32 v163, 0x1c000, v150
	v_add_u32_e32 v165, 0x1c800, v150
	v_or_b32_e32 v164, 0x1c000, v151
	v_add_u32_e32 v166, 0x1c800, v151
	s_mov_b64 s[2:3], 0xf80
	s_mov_b32 m0, s22
	v_lshl_add_u64 v[132:133], v[138:139], 0, s[2:3]
	ds_read_b128 v[140:143], v0
	ds_read_b128 v[144:147], v152
	ds_read_b128 v[150:153], v153
	ds_read_b128 v[168:171], v154
	ds_read_b128 v[172:175], v148
	ds_read_b128 v[176:179], v148 offset:2048
	ds_read_b128 v[180:183], v149
	ds_read_b128 v[184:187], v149 offset:2048
	ds_read_b128 v[188:191], v148 offset:4096
	ds_read_b128 v[192:195], v148 offset:6144
	ds_read_b128 v[196:199], v149 offset:4096
	ds_read_b128 v[200:203], v149 offset:6144
	global_load_lds_dwordx4 v[132:133], off
	v_lshl_add_u64 v[132:133], v[136:137], 0, s[2:3]
	s_mov_b32 m0, s5
	s_nop 0
	global_load_lds_dwordx4 v[132:133], off
	s_barrier
	s_waitcnt lgkmcnt(0)
	s_setprio 1
	s_waitcnt lgkmcnt(0)
	v_mfma_f32_16x16x32_bf16 v[126:129], v[140:143], v[172:175], v[126:129]
	v_mfma_f32_16x16x32_bf16 v[122:125], v[150:153], v[172:175], v[122:125]
	v_mfma_f32_16x16x32_bf16 v[118:121], v[140:143], v[176:179], v[118:121]
	v_mfma_f32_16x16x32_bf16 v[110:113], v[140:143], v[188:191], v[110:113]
	v_mfma_f32_16x16x32_bf16 v[106:109], v[150:153], v[188:191], v[106:109]
	v_mfma_f32_16x16x32_bf16 v[126:129], v[144:147], v[180:183], v[126:129]
	v_mfma_f32_16x16x32_bf16 v[122:125], v[168:171], v[180:183], v[122:125]
	v_mfma_f32_16x16x32_bf16 v[118:121], v[144:147], v[184:187], v[118:121]
	v_mfma_f32_16x16x32_bf16 v[114:117], v[150:153], v[176:179], v[114:117]
	v_mfma_f32_16x16x32_bf16 v[110:113], v[144:147], v[196:199], v[110:113]
	v_mfma_f32_16x16x32_bf16 v[106:109], v[168:171], v[196:199], v[106:109]
	v_mfma_f32_16x16x32_bf16 v[102:105], v[140:143], v[192:195], v[102:105]
	v_mfma_f32_16x16x32_bf16 v[98:101], v[150:153], v[192:195], v[98:101]
	v_mfma_f32_16x16x32_bf16 v[136:139], v[168:171], v[184:187], v[114:117]
	v_mfma_f32_16x16x32_bf16 v[218:221], v[144:147], v[200:203], v[102:105]
	v_mfma_f32_16x16x32_bf16 v[222:225], v[168:171], v[200:203], v[98:101]
	s_setprio 0
	s_barrier
	s_nop 2
	ds_read_b128 v[98:101], v155
	ds_read_b128 v[102:105], v156
	ds_read_b128 v[114:117], v157
	ds_read_b128 v[154:157], v158
	s_barrier
	s_waitcnt lgkmcnt(0)
	s_setprio 1
	s_waitcnt lgkmcnt(0)
	v_mfma_f32_16x16x32_bf16 v[94:97], v[98:101], v[172:175], v[94:97]
	v_mfma_f32_16x16x32_bf16 v[90:93], v[114:117], v[172:175], v[90:93]
	v_mfma_f32_16x16x32_bf16 v[78:81], v[98:101], v[188:191], v[78:81]
	v_mfma_f32_16x16x32_bf16 v[74:77], v[114:117], v[188:191], v[74:77]
	v_mfma_f32_16x16x32_bf16 v[94:97], v[102:105], v[180:183], v[94:97]
	v_mfma_f32_16x16x32_bf16 v[90:93], v[154:157], v[180:183], v[90:93]
	v_mfma_f32_16x16x32_bf16 v[86:89], v[98:101], v[176:179], v[86:89]
	v_mfma_f32_16x16x32_bf16 v[82:85], v[114:117], v[176:179], v[82:85]
	v_mfma_f32_16x16x32_bf16 v[78:81], v[102:105], v[196:199], v[78:81]
	v_mfma_f32_16x16x32_bf16 v[74:77], v[154:157], v[196:199], v[74:77]
	v_mfma_f32_16x16x32_bf16 v[70:73], v[98:101], v[192:195], v[70:73]
	v_mfma_f32_16x16x32_bf16 v[66:69], v[114:117], v[192:195], v[66:69]
	v_mfma_f32_16x16x32_bf16 v[172:175], v[102:105], v[184:187], v[86:89]
	v_mfma_f32_16x16x32_bf16 v[176:179], v[154:157], v[184:187], v[82:85]
	v_mfma_f32_16x16x32_bf16 v[180:183], v[102:105], v[200:203], v[70:73]
	v_mfma_f32_16x16x32_bf16 v[184:187], v[154:157], v[200:203], v[66:69]
	s_setprio 0
	s_barrier
	s_nop 1
	ds_read_b128 v[66:69], v148 offset:16384
	ds_read_b128 v[70:73], v148 offset:18432
	ds_read_b128 v[82:85], v149 offset:16384
	ds_read_b128 v[86:89], v149 offset:18432
	ds_read_b128 v[188:191], v148 offset:20480
	ds_read_b128 v[192:195], v148 offset:22528
	ds_read_b128 v[196:199], v149 offset:20480
	ds_read_b128 v[200:203], v149 offset:22528
	s_waitcnt vmcnt(4)
	s_barrier
	s_waitcnt lgkmcnt(0)
	s_setprio 1
	s_waitcnt lgkmcnt(0)
	v_mfma_f32_16x16x32_bf16 v[62:65], v[140:143], v[66:69], v[62:65]
	v_mfma_f32_16x16x32_bf16 v[58:61], v[150:153], v[66:69], v[58:61]
	v_mfma_f32_16x16x32_bf16 v[46:49], v[140:143], v[188:191], v[46:49]
	v_mfma_f32_16x16x32_bf16 v[42:45], v[150:153], v[188:191], v[42:45]
	v_mfma_f32_16x16x32_bf16 v[62:65], v[144:147], v[82:85], v[62:65]
	v_mfma_f32_16x16x32_bf16 v[58:61], v[168:171], v[82:85], v[58:61]
	v_mfma_f32_16x16x32_bf16 v[54:57], v[140:143], v[70:73], v[54:57]
	v_mfma_f32_16x16x32_bf16 v[50:53], v[150:153], v[70:73], v[50:53]
	v_mfma_f32_16x16x32_bf16 v[46:49], v[144:147], v[196:199], v[46:49]
	v_mfma_f32_16x16x32_bf16 v[42:45], v[168:171], v[196:199], v[42:45]
	v_mfma_f32_16x16x32_bf16 v[38:41], v[140:143], v[192:195], v[38:41]
	v_mfma_f32_16x16x32_bf16 v[34:37], v[150:153], v[192:195], v[34:37]
	v_mfma_f32_16x16x32_bf16 v[226:229], v[144:147], v[86:89], v[54:57]
	v_mfma_f32_16x16x32_bf16 v[230:233], v[168:171], v[86:89], v[50:53]
	v_mfma_f32_16x16x32_bf16 v[140:143], v[144:147], v[200:203], v[38:41]
	v_mfma_f32_16x16x32_bf16 v[144:147], v[168:171], v[200:203], v[34:37]
	s_setprio 0
	s_setprio 1
	v_mfma_f32_16x16x32_bf16 v[30:33], v[98:101], v[66:69], v[30:33]
	v_mfma_f32_16x16x32_bf16 v[26:29], v[114:117], v[66:69], v[26:29]
	v_mfma_f32_16x16x32_bf16 v[14:17], v[98:101], v[188:191], v[14:17]
	v_mfma_f32_16x16x32_bf16 v[10:13], v[114:117], v[188:191], v[10:13]
	v_mfma_f32_16x16x32_bf16 v[30:33], v[102:105], v[82:85], v[30:33]
	v_mfma_f32_16x16x32_bf16 v[26:29], v[154:157], v[82:85], v[26:29]
	v_mfma_f32_16x16x32_bf16 v[22:25], v[98:101], v[70:73], v[22:25]
	v_mfma_f32_16x16x32_bf16 v[18:21], v[114:117], v[70:73], v[18:21]
	v_mfma_f32_16x16x32_bf16 v[14:17], v[102:105], v[196:199], v[14:17]
	v_mfma_f32_16x16x32_bf16 v[10:13], v[154:157], v[196:199], v[10:13]
	v_mfma_f32_16x16x32_bf16 v[6:9], v[98:101], v[192:195], v[6:9]
	v_mfma_f32_16x16x32_bf16 v[2:5], v[114:117], v[192:195], v[2:5]
	v_mfma_f32_16x16x32_bf16 v[150:153], v[102:105], v[86:89], v[22:25]
	v_mfma_f32_16x16x32_bf16 v[168:171], v[154:157], v[86:89], v[18:21]
	v_mfma_f32_16x16x32_bf16 v[188:191], v[102:105], v[200:203], v[6:9]
	v_mfma_f32_16x16x32_bf16 v[154:157], v[154:157], v[200:203], v[2:5]
	s_setprio 0
	s_barrier
	s_nop 1
	ds_read_b128 v[2:5], v159
	ds_read_b128 v[6:9], v160
	ds_read_b128 v[158:161], v161
	ds_read_b128 v[192:195], v162
	ds_read_b128 v[18:21], v148 offset:32768
	ds_read_b128 v[22:25], v148 offset:34816
	ds_read_b128 v[34:37], v149 offset:32768
	ds_read_b128 v[38:41], v149 offset:34816
	ds_read_b128 v[50:53], v148 offset:36864
	ds_read_b128 v[54:57], v148 offset:38912
	ds_read_b128 v[196:199], v149 offset:36864
	ds_read_b128 v[200:203], v149 offset:38912
	s_waitcnt vmcnt(2)
	s_barrier
	s_waitcnt lgkmcnt(0)
	s_setprio 1
	s_waitcnt lgkmcnt(0)
	v_mfma_f32_16x16x32_bf16 v[66:69], v[2:5], v[18:21], v[126:129]
	v_mfma_f32_16x16x32_bf16 v[126:129], v[6:9], v[34:37], v[66:69]
	v_mfma_f32_16x16x32_bf16 v[66:69], v[158:161], v[18:21], v[122:125]
	v_mfma_f32_16x16x32_bf16 v[114:117], v[192:195], v[34:37], v[66:69]
	v_mfma_f32_16x16x32_bf16 v[66:69], v[2:5], v[22:25], v[118:121]
	v_mfma_f32_16x16x32_bf16 v[102:105], v[6:9], v[38:41], v[66:69]
	v_mfma_f32_16x16x32_bf16 v[66:69], v[158:161], v[22:25], v[136:139]
	v_mfma_f32_16x16x32_bf16 v[98:101], v[192:195], v[38:41], v[66:69]
	v_mfma_f32_16x16x32_bf16 v[66:69], v[2:5], v[50:53], v[110:113]
	v_mfma_f32_16x16x32_bf16 v[86:89], v[6:9], v[196:199], v[66:69]
	v_mfma_f32_16x16x32_bf16 v[66:69], v[158:161], v[50:53], v[106:109]
	v_mfma_f32_16x16x32_bf16 v[82:85], v[192:195], v[196:199], v[66:69]
	v_mfma_f32_16x16x32_bf16 v[66:69], v[2:5], v[54:57], v[218:221]
	v_mfma_f32_16x16x32_bf16 v[70:73], v[6:9], v[200:203], v[66:69]
	v_mfma_f32_16x16x32_bf16 v[66:69], v[158:161], v[54:57], v[222:225]
	v_mfma_f32_16x16x32_bf16 v[66:69], v[192:195], v[200:203], v[66:69]
	s_setprio 0
	s_barrier
	ds_read_b128 v[136:139], v163
	ds_read_b128 v[218:221], v164
	ds_read_b128 v[162:165], v165
	ds_read_b128 v[222:225], v166
	s_waitcnt vmcnt(0)
	s_barrier
	s_waitcnt lgkmcnt(0)
	s_setprio 1
	s_waitcnt lgkmcnt(0)
	v_mfma_f32_16x16x32_bf16 v[94:97], v[136:139], v[18:21], v[94:97]
	v_mfma_f32_16x16x32_bf16 v[18:21], v[162:165], v[18:21], v[90:93]
	v_mfma_f32_16x16x32_bf16 v[118:121], v[222:225], v[34:37], v[18:21]
	v_mfma_f32_16x16x32_bf16 v[18:21], v[136:139], v[22:25], v[172:175]
	v_mfma_f32_16x16x32_bf16 v[110:113], v[218:221], v[38:41], v[18:21]
	v_mfma_f32_16x16x32_bf16 v[18:21], v[162:165], v[22:25], v[176:179]
	v_mfma_f32_16x16x32_bf16 v[106:109], v[222:225], v[38:41], v[18:21]
	v_mfma_f32_16x16x32_bf16 v[18:21], v[136:139], v[50:53], v[78:81]
	v_mfma_f32_16x16x32_bf16 v[122:125], v[218:221], v[34:37], v[94:97]
	v_mfma_f32_16x16x32_bf16 v[94:97], v[218:221], v[196:199], v[18:21]
	v_mfma_f32_16x16x32_bf16 v[18:21], v[162:165], v[50:53], v[74:77]
	v_mfma_f32_16x16x32_bf16 v[90:93], v[222:225], v[196:199], v[18:21]
	v_mfma_f32_16x16x32_bf16 v[18:21], v[136:139], v[54:57], v[180:183]
	v_mfma_f32_16x16x32_bf16 v[78:81], v[218:221], v[200:203], v[18:21]
	v_mfma_f32_16x16x32_bf16 v[18:21], v[162:165], v[54:57], v[184:187]
	v_mfma_f32_16x16x32_bf16 v[74:77], v[222:225], v[200:203], v[18:21]
	s_setprio 0
	s_barrier
	ds_read_b128 v[172:175], v148 offset:49152
	ds_read_b128 v[176:179], v148 offset:51200
	ds_read_b128 v[180:183], v149 offset:49152
	ds_read_b128 v[184:187], v149 offset:51200
	ds_read_b128 v[196:199], v148 offset:53248
	ds_read_b128 v[200:203], v148 offset:55296
	ds_read_b128 v[234:237], v149 offset:53248
	ds_read_b128 v[238:241], v149 offset:55296
	s_barrier
	s_waitcnt lgkmcnt(0)
	s_setprio 1
	s_waitcnt lgkmcnt(0)
	v_mfma_f32_16x16x32_bf16 v[18:21], v[2:5], v[172:175], v[62:65]
	v_mfma_f32_16x16x32_bf16 v[54:57], v[6:9], v[180:183], v[18:21]
	v_mfma_f32_16x16x32_bf16 v[18:21], v[158:161], v[172:175], v[58:61]
	v_mfma_f32_16x16x32_bf16 v[50:53], v[192:195], v[180:183], v[18:21]
	v_mfma_f32_16x16x32_bf16 v[18:21], v[2:5], v[176:179], v[226:229]
	v_mfma_f32_16x16x32_bf16 v[38:41], v[6:9], v[184:187], v[18:21]
	v_mfma_f32_16x16x32_bf16 v[18:21], v[158:161], v[176:179], v[230:233]
	v_mfma_f32_16x16x32_bf16 v[34:37], v[192:195], v[184:187], v[18:21]
	v_mfma_f32_16x16x32_bf16 v[18:21], v[2:5], v[196:199], v[46:49]
	v_mfma_f32_16x16x32_bf16 v[2:5], v[2:5], v[200:203], v[140:143]
	v_mfma_f32_16x16x32_bf16 v[22:25], v[6:9], v[234:237], v[18:21]
	v_mfma_f32_16x16x32_bf16 v[18:21], v[158:161], v[196:199], v[42:45]
	v_mfma_f32_16x16x32_bf16 v[6:9], v[6:9], v[238:241], v[2:5]
	v_mfma_f32_16x16x32_bf16 v[2:5], v[158:161], v[200:203], v[144:147]
	v_mfma_f32_16x16x32_bf16 v[18:21], v[192:195], v[234:237], v[18:21]
	v_mfma_f32_16x16x32_bf16 v[2:5], v[192:195], v[238:241], v[2:5]
	s_setprio 0
	s_setprio 1
	v_mfma_f32_16x16x32_bf16 v[26:29], v[162:165], v[172:175], v[26:29]
	v_mfma_f32_16x16x32_bf16 v[58:61], v[222:225], v[180:183], v[26:29]
	v_mfma_f32_16x16x32_bf16 v[26:29], v[136:139], v[176:179], v[150:153]
	v_mfma_f32_16x16x32_bf16 v[46:49], v[218:221], v[184:187], v[26:29]
	v_mfma_f32_16x16x32_bf16 v[26:29], v[162:165], v[176:179], v[168:171]
	v_mfma_f32_16x16x32_bf16 v[10:13], v[162:165], v[196:199], v[10:13]
	v_mfma_f32_16x16x32_bf16 v[30:33], v[136:139], v[172:175], v[30:33]
	v_mfma_f32_16x16x32_bf16 v[42:45], v[222:225], v[184:187], v[26:29]
	v_mfma_f32_16x16x32_bf16 v[14:17], v[136:139], v[196:199], v[14:17]
	v_mfma_f32_16x16x32_bf16 v[26:29], v[222:225], v[234:237], v[10:13]
	v_mfma_f32_16x16x32_bf16 v[10:13], v[136:139], v[200:203], v[188:191]
	v_mfma_f32_16x16x32_bf16 v[62:65], v[218:221], v[180:183], v[30:33]
	v_mfma_f32_16x16x32_bf16 v[30:33], v[218:221], v[234:237], v[14:17]
	v_mfma_f32_16x16x32_bf16 v[14:17], v[218:221], v[238:241], v[10:13]
	v_mfma_f32_16x16x32_bf16 v[10:13], v[162:165], v[200:203], v[154:157]
	v_mfma_f32_16x16x32_bf16 v[10:13], v[222:225], v[238:241], v[10:13]
	s_setprio 0
	s_cmpk_gt_u32 s0, 0xff
	s_barrier
	s_cbranch_scc1 .LBB0_352
	s_barrier

.LBB0_354:
	v_mov_b64_e32 v[2:3], s[6:7]
	flat_load_dwordx2 v[134:135], v[2:3] offset:160
	s_load_dwordx2 s[100:101], s[78:79], 0xa0
	v_mov_b32_e32 v19, v204
	s_ashr_i32 s9, s8, 31
	v_lshrrev_b32_e32 v20, 4, v19
	v_xor_b32_e32 v0, v19, v20
	v_lshlrev_b32_e32 v0, 3, v0
	v_readfirstlane_b32 s0, v19
	v_and_b32_e32 v16, 56, v0
	v_lshlrev_b32_e32 v0, 8, v19
	s_ashr_i32 s19, s0, 6
	v_and_b32_e32 v17, 0xfffff800, v0
	v_or_b32_e32 v0, v16, v17
	v_add_u32_e32 v18, 0x20000, v17
	s_lshl_b64 s[4:5], s[8:9], 12
	s_lshl_b32 s1, s19, 10
	v_or_b32_e32 v4, v16, v18
	s_add_i32 s2, s1, 0x10000
	v_lshlrev_b64 v[14:15], 1, v[0:1]
	v_mov_b32_e32 v5, v1
	s_ashr_i32 s11, s10, 31
	s_mov_b32 m0, s2
	v_lshlrev_b64 v[22:23], 1, v[4:5]
	s_add_i32 s3, s1, 0x12000
	s_lshl_b64 s[12:13], s[10:11], 12
	s_or_b32 s16, s8, 0x80
	s_ashr_i32 s17, s16, 31
	s_add_i32 s11, s1, 0x2000
	s_lshl_b64 s[16:17], s[16:17], 12
	s_or_b32 s22, s10, 0x80
	s_add_i32 s15, s1, 0x14000
	s_ashr_i32 s23, s22, 31
	s_lshl_b64 s[22:23], s[22:23], 12
	s_add_i32 s18, s1, 0x6000
	s_ashr_i32 s20, s0, 8
	s_waitcnt vmcnt(0) lgkmcnt(0)
	v_lshl_add_u64 v[10:11], v[134:135], 0, s[94:95]
	v_lshl_add_u64 v[6:7], v[10:11], 0, s[4:5]
	v_lshl_add_u64 v[2:3], v[6:7], 0, v[14:15]
	global_load_lds_dwordx4 v[2:3], off
	v_lshl_add_u64 v[4:5], v[6:7], 0, v[22:23]
	s_mov_b32 m0, s3
	v_lshl_add_u64 v[132:133], v[134:135], 0, s[12:13]
	global_load_lds_dwordx4 v[4:5], off
	v_lshl_add_u64 v[8:9], v[132:133], 0, v[14:15]
	s_mov_b32 m0, s1
	v_lshl_add_u64 v[6:7], v[132:133], 0, v[22:23]
	global_load_lds_dwordx4 v[8:9], off
	s_mov_b32 m0, s11
	v_lshl_add_u64 v[10:11], v[10:11], 0, s[16:17]
	global_load_lds_dwordx4 v[6:7], off
	v_lshl_add_u64 v[12:13], v[10:11], 0, v[14:15]
	s_mov_b32 m0, s15
	s_add_i32 s16, s1, 0x16000
	global_load_lds_dwordx4 v[12:13], off
	v_lshl_add_u64 v[10:11], v[10:11], 0, v[22:23]
	s_mov_b32 m0, s16
	v_lshl_add_u64 v[24:25], v[134:135], 0, s[22:23]
	s_add_i32 s17, s1, 0x4000
	global_load_lds_dwordx4 v[10:11], off
	v_lshl_add_u64 v[138:139], v[24:25], 0, v[14:15]
	s_mov_b32 m0, s17
	v_lshl_add_u64 v[136:137], v[24:25], 0, v[22:23]
	global_load_lds_dwordx4 v[138:139], off
	s_mov_b32 m0, s18
	s_cmp_lg_u32 s20, 1
	global_load_lds_dwordx4 v[136:137], off
	s_cbranch_scc1 .LBB0_356
	s_barrier
.LBB0_356:
	s_lshl_b32 s19, s19, 5
	v_and_b32_e32 v0, 15, v19
	s_and_b32 s19, s19, 0x60
	v_lshlrev_b32_e32 v14, 7, v0
	v_or_b32_e32 v0, s19, v0
	s_add_i32 s19, s1, 0x18000
	s_mov_b64 s[24:25], 0x80
	v_lshl_or_b32 v14, s20, 13, v14
	v_lshl_add_u64 v[2:3], v[2:3], 0, s[24:25]
	s_mov_b32 m0, s19
	s_add_i32 s20, s1, 0x1a000
	s_waitcnt vmcnt(4)
	s_barrier
	global_load_lds_dwordx4 v[2:3], off
	v_lshl_add_u64 v[2:3], v[4:5], 0, s[24:25]
	s_mov_b32 m0, s20
	s_add_i32 s21, s1, 0x8000
	global_load_lds_dwordx4 v[2:3], off
	v_lshl_add_u64 v[2:3], v[8:9], 0, s[24:25]
	s_mov_b32 m0, s21
	s_add_i32 s22, s1, 0xa000
	global_load_lds_dwordx4 v[2:3], off
	v_lshl_add_u64 v[2:3], v[6:7], 0, s[24:25]
	s_mov_b32 m0, s22
	s_add_i32 s23, s1, 0x1c000
	global_load_lds_dwordx4 v[2:3], off
	v_lshl_add_u64 v[2:3], v[12:13], 0, s[24:25]
	s_mov_b32 m0, s23
	v_and_b32_e32 v15, 3, v20
	global_load_lds_dwordx4 v[2:3], off
	v_lshl_add_u64 v[2:3], v[10:11], 0, s[24:25]
	s_add_i32 s24, s1, 0x1e000
	s_mov_b32 m0, s24
	v_bfe_u32 v19, v19, 1, 3
	global_load_lds_dwordx4 v[2:3], off
	v_bitop3_b32 v20, v20, v19, 3 bitop3:0x6c
	v_bitop3_b32 v15, v15, v19, 4 bitop3:0x36
	v_lshlrev_b32_e32 v20, 4, v20
	v_lshlrev_b32_e32 v15, 4, v15
	v_lshlrev_b32_e32 v0, 7, v0
	v_or_b32_e32 v150, v0, v20
	v_or_b32_e32 v151, v0, v15
	v_add_u32_e32 v0, v18, v16
	s_waitcnt vmcnt(6)
	v_lshlrev_b64 v[2:3], 1, v[0:1]
	v_add_u32_e32 v0, v17, v16
	v_lshl_add_u64 v[140:141], s[12:13], 0, v[2:3]
	v_lshlrev_b64 v[4:5], 1, v[0:1]
	v_lshl_add_u64 v[144:145], s[4:5], 0, v[2:3]
	v_mov_b32_e32 v2, 0
	v_or_b32_e32 v148, v20, v14
	v_or_b32_e32 v149, v15, v14
	v_lshl_add_u64 v[142:143], s[12:13], 0, v[4:5]
	v_lshl_add_u64 v[146:147], s[4:5], 0, v[4:5]
	s_mov_b32 s4, -2
	v_mov_b32_e32 v3, v2
	v_mov_b32_e32 v4, v2
	v_mov_b32_e32 v5, v2
	v_mov_b32_e32 v6, v2
	v_mov_b32_e32 v7, v2
	v_mov_b32_e32 v8, v2
	v_mov_b32_e32 v9, v2
	v_mov_b32_e32 v10, v2
	v_mov_b32_e32 v11, v2
	v_mov_b32_e32 v12, v2
	v_mov_b32_e32 v13, v2
	v_mov_b32_e32 v14, v2
	v_mov_b32_e32 v15, v2
	v_mov_b32_e32 v16, v2
	v_mov_b32_e32 v17, v2
	v_mov_b32_e32 v18, v2
	v_mov_b32_e32 v19, v2
	v_mov_b32_e32 v20, v2
	v_mov_b32_e32 v21, v2
	v_mov_b32_e32 v22, v2
	v_mov_b32_e32 v23, v2
	v_mov_b32_e32 v24, v2
	v_mov_b32_e32 v25, v2
	v_mov_b32_e32 v26, v2
	v_mov_b32_e32 v27, v2
	v_mov_b32_e32 v28, v2
	v_mov_b32_e32 v29, v2
	v_mov_b32_e32 v30, v2
	v_mov_b32_e32 v31, v2
	v_mov_b32_e32 v32, v2
	v_mov_b32_e32 v33, v2
	v_mov_b32_e32 v34, v2
	v_mov_b32_e32 v35, v2
	v_mov_b32_e32 v36, v2
	v_mov_b32_e32 v37, v2
	v_mov_b32_e32 v38, v2
	v_mov_b32_e32 v39, v2
	v_mov_b32_e32 v40, v2
	v_mov_b32_e32 v41, v2
	v_mov_b32_e32 v42, v2
	v_mov_b32_e32 v43, v2
	v_mov_b32_e32 v44, v2
	v_mov_b32_e32 v45, v2
	v_mov_b32_e32 v46, v2
	v_mov_b32_e32 v47, v2
	v_mov_b32_e32 v48, v2
	v_mov_b32_e32 v49, v2
	v_mov_b32_e32 v50, v2
	v_mov_b32_e32 v51, v2
	v_mov_b32_e32 v52, v2
	v_mov_b32_e32 v53, v2
	v_mov_b32_e32 v54, v2
	v_mov_b32_e32 v55, v2
	v_mov_b32_e32 v56, v2
	v_mov_b32_e32 v57, v2
	v_mov_b32_e32 v58, v2
	v_mov_b32_e32 v59, v2
	v_mov_b32_e32 v60, v2
	v_mov_b32_e32 v61, v2
	v_mov_b32_e32 v62, v2
	v_mov_b32_e32 v63, v2
	v_mov_b32_e32 v64, v2
	v_mov_b32_e32 v65, v2
	v_mov_b32_e32 v66, v2
	v_mov_b32_e32 v67, v2
	v_mov_b32_e32 v68, v2
	v_mov_b32_e32 v69, v2
	v_mov_b32_e32 v70, v2
	v_mov_b32_e32 v71, v2
	v_mov_b32_e32 v72, v2
	v_mov_b32_e32 v73, v2
	v_mov_b32_e32 v74, v2
	v_mov_b32_e32 v75, v2
	v_mov_b32_e32 v76, v2
	v_mov_b32_e32 v77, v2
	v_mov_b32_e32 v78, v2
	v_mov_b32_e32 v79, v2
	v_mov_b32_e32 v80, v2
	v_mov_b32_e32 v81, v2
	v_mov_b32_e32 v82, v2
	v_mov_b32_e32 v83, v2
	v_mov_b32_e32 v84, v2
	v_mov_b32_e32 v85, v2
	v_mov_b32_e32 v86, v2
	v_mov_b32_e32 v87, v2
	v_mov_b32_e32 v88, v2
	v_mov_b32_e32 v89, v2
	v_mov_b32_e32 v90, v2
	v_mov_b32_e32 v91, v2
	v_mov_b32_e32 v92, v2
	v_mov_b32_e32 v93, v2
	v_mov_b32_e32 v94, v2
	v_mov_b32_e32 v95, v2
	v_mov_b32_e32 v96, v2
	v_mov_b32_e32 v97, v2
	v_mov_b32_e32 v98, v2
	v_mov_b32_e32 v99, v2
	v_mov_b32_e32 v100, v2
	v_mov_b32_e32 v101, v2
	v_mov_b32_e32 v102, v2
	v_mov_b32_e32 v103, v2
	v_mov_b32_e32 v104, v2
	v_mov_b32_e32 v105, v2
	v_mov_b32_e32 v106, v2
	v_mov_b32_e32 v107, v2
	v_mov_b32_e32 v108, v2
	v_mov_b32_e32 v109, v2
	v_mov_b32_e32 v110, v2
	v_mov_b32_e32 v111, v2
	v_mov_b32_e32 v112, v2
	v_mov_b32_e32 v113, v2
	v_mov_b32_e32 v114, v2
	v_mov_b32_e32 v115, v2
	v_mov_b32_e32 v116, v2
	v_mov_b32_e32 v117, v2
	v_mov_b32_e32 v118, v2
	v_mov_b32_e32 v119, v2
	v_mov_b32_e32 v120, v2
	v_mov_b32_e32 v121, v2
	v_mov_b32_e32 v122, v2
	v_mov_b32_e32 v123, v2
	v_mov_b32_e32 v124, v2
	v_mov_b32_e32 v125, v2
	v_mov_b32_e32 v126, v2
	v_mov_b32_e32 v127, v2
	v_mov_b32_e32 v128, v2
	v_mov_b32_e32 v129, v2
	s_mov_b64 s[26:27], 0x82d4900
	s_mov_b64 s[28:29], 0x8254980
	s_mov_b64 s[30:31], 0x82d4980
	s_waitcnt lgkmcnt(0)
	s_sub_u32 s100, s100, 0x40000000
	s_subb_u32 s101, s101, 0
	s_mov_b64 vcc, s[100:101]
	v_lshl_add_u64 v[206:207], v[134:135], 0, v[142:143]
	v_subrev_u32_e32 v206, vcc_lo, v206
	v_lshl_add_u64 v[208:209], v[134:135], 0, v[140:141]
	v_subrev_u32_e32 v208, vcc_lo, v208
	v_lshl_add_u64 v[210:211], v[134:135], 0, v[146:147]
	v_subrev_u32_e32 v210, vcc_lo, v210
	v_lshl_add_u64 v[214:215], v[134:135], 0, v[144:145]
	v_subrev_u32_e32 v214, vcc_lo, v214
	v_add_u32_e32 v207, 0x10000, v150
	v_add_u32_e32 v209, 0x10000, v151
	s_barrier
.LBB0_357:
	ds_read_b128 v[160:163], v207
	ds_read_b128 v[164:167], v209
	ds_read_b128 v[168:171], v207 offset:2048
	ds_read_b128 v[172:175], v209 offset:2048
	s_add_i32 s12, s1, 0xc000
	s_mov_b32 m0, s12
	s_add_i32 s5, s1, 0xe000
	ds_read_b128 v[176:179], v148
	ds_read_b128 v[180:183], v148 offset:2048
	ds_read_b128 v[184:187], v149
	ds_read_b128 v[188:191], v149 offset:2048
	ds_read_b128 v[192:195], v148 offset:4096
	ds_read_b128 v[196:199], v148 offset:6144
	ds_read_b128 v[200:203], v149 offset:4096
	ds_read_b128 v[218:221], v149 offset:6144
	s_add_u32 s100, vcc_lo, s50
	s_addc_u32 s101, vcc_hi, s51
	global_load_lds_dwordx4 v206, s[100:101]
	s_mov_b32 m0, s5
	s_add_u32 s100, vcc_lo, s50
	s_addc_u32 s101, vcc_hi, s51
	global_load_lds_dwordx4 v208, s[100:101]
	s_waitcnt lgkmcnt(8)
	s_waitcnt vmcnt(10)
	s_barrier
	s_waitcnt lgkmcnt(0)
	s_setprio 1
	s_waitcnt lgkmcnt(0)
	v_mfma_f32_16x16x32_bf16 v[126:129], v[160:163], v[176:179], v[126:129]
	v_mfma_f32_16x16x32_bf16 v[122:125], v[168:171], v[176:179], v[122:125]
	v_mfma_f32_16x16x32_bf16 v[118:121], v[160:163], v[180:183], v[118:121]
	v_mfma_f32_16x16x32_bf16 v[114:117], v[168:171], v[180:183], v[114:117]
	v_mfma_f32_16x16x32_bf16 v[110:113], v[160:163], v[192:195], v[110:113]
	v_mfma_f32_16x16x32_bf16 v[106:109], v[168:171], v[192:195], v[106:109]
	v_mfma_f32_16x16x32_bf16 v[102:105], v[160:163], v[196:199], v[102:105]
	v_mfma_f32_16x16x32_bf16 v[98:101], v[168:171], v[196:199], v[98:101]
	v_mfma_f32_16x16x32_bf16 v[126:129], v[164:167], v[184:187], v[126:129]
	v_mfma_f32_16x16x32_bf16 v[122:125], v[172:175], v[184:187], v[122:125]
	v_mfma_f32_16x16x32_bf16 v[118:121], v[164:167], v[188:191], v[118:121]
	v_mfma_f32_16x16x32_bf16 v[114:117], v[172:175], v[188:191], v[114:117]
	v_mfma_f32_16x16x32_bf16 v[110:113], v[164:167], v[200:203], v[110:113]
	v_mfma_f32_16x16x32_bf16 v[106:109], v[172:175], v[200:203], v[106:109]
	v_mfma_f32_16x16x32_bf16 v[102:105], v[164:167], v[218:221], v[102:105]
	v_mfma_f32_16x16x32_bf16 v[98:101], v[172:175], v[218:221], v[98:101]
	s_setprio 0
	s_barrier
	s_mov_b32 m0, s2
	ds_read_b128 v[222:225], v207 offset:16384
	ds_read_b128 v[226:229], v209 offset:16384
	ds_read_b128 v[230:233], v207 offset:18432
	ds_read_b128 v[234:237], v209 offset:18432
	s_add_u32 s100, vcc_lo, s70
	s_addc_u32 s101, vcc_hi, s71
	global_load_lds_dwordx4 v210, s[100:101]
	s_mov_b32 m0, s3
	s_add_u32 s100, vcc_lo, s70
	s_addc_u32 s101, vcc_hi, s71
	global_load_lds_dwordx4 v214, s[100:101]
	s_waitcnt vmcnt(10)
	s_waitcnt lgkmcnt(0)
	s_barrier
	s_waitcnt lgkmcnt(0)
	s_setprio 1
	s_waitcnt lgkmcnt(0)
	v_mfma_f32_16x16x32_bf16 v[94:97], v[222:225], v[176:179], v[94:97]
	v_mfma_f32_16x16x32_bf16 v[90:93], v[230:233], v[176:179], v[90:93]
	v_mfma_f32_16x16x32_bf16 v[86:89], v[222:225], v[180:183], v[86:89]
	v_mfma_f32_16x16x32_bf16 v[82:85], v[230:233], v[180:183], v[82:85]
	v_mfma_f32_16x16x32_bf16 v[78:81], v[222:225], v[192:195], v[78:81]
	v_mfma_f32_16x16x32_bf16 v[74:77], v[230:233], v[192:195], v[74:77]
	v_mfma_f32_16x16x32_bf16 v[70:73], v[222:225], v[196:199], v[70:73]
	v_mfma_f32_16x16x32_bf16 v[66:69], v[230:233], v[196:199], v[66:69]
	v_mfma_f32_16x16x32_bf16 v[94:97], v[226:229], v[184:187], v[94:97]
	v_mfma_f32_16x16x32_bf16 v[90:93], v[234:237], v[184:187], v[90:93]
	v_mfma_f32_16x16x32_bf16 v[86:89], v[226:229], v[188:191], v[86:89]
	v_mfma_f32_16x16x32_bf16 v[82:85], v[234:237], v[188:191], v[82:85]
	v_mfma_f32_16x16x32_bf16 v[78:81], v[226:229], v[200:203], v[78:81]
	v_mfma_f32_16x16x32_bf16 v[74:77], v[234:237], v[200:203], v[74:77]
	v_mfma_f32_16x16x32_bf16 v[70:73], v[226:229], v[218:221], v[70:73]
	v_mfma_f32_16x16x32_bf16 v[66:69], v[234:237], v[218:221], v[66:69]
	s_setprio 0
	s_mov_b32 m0, s1
	s_barrier
	ds_read_b128 v[176:179], v148 offset:16384
	ds_read_b128 v[180:183], v148 offset:18432
	ds_read_b128 v[184:187], v149 offset:16384
	ds_read_b128 v[188:191], v149 offset:18432
	ds_read_b128 v[192:195], v148 offset:20480
	ds_read_b128 v[196:199], v148 offset:22528
	ds_read_b128 v[200:203], v149 offset:20480
	ds_read_b128 v[218:221], v149 offset:22528
	s_add_u32 s100, vcc_lo, s54
	s_addc_u32 s101, vcc_hi, s55
	global_load_lds_dwordx4 v206, s[100:101]
	s_mov_b32 m0, s11
	s_add_u32 s100, vcc_lo, s54
	s_addc_u32 s101, vcc_hi, s55
	global_load_lds_dwordx4 v208, s[100:101]
	s_mov_b32 m0, s15
	s_add_u32 s100, vcc_lo, s26
	s_addc_u32 s101, vcc_hi, s27
	global_load_lds_dwordx4 v210, s[100:101]
	s_mov_b32 m0, s16
	s_add_u32 s100, vcc_lo, s26
	s_addc_u32 s101, vcc_hi, s27
	global_load_lds_dwordx4 v214, s[100:101]
	s_waitcnt vmcnt(10)
	s_waitcnt lgkmcnt(0)
	s_barrier
	s_waitcnt lgkmcnt(0)
	s_setprio 1
	s_waitcnt lgkmcnt(0)
	v_mfma_f32_16x16x32_bf16 v[62:65], v[160:163], v[176:179], v[62:65]
	v_mfma_f32_16x16x32_bf16 v[58:61], v[168:171], v[176:179], v[58:61]
	v_mfma_f32_16x16x32_bf16 v[54:57], v[160:163], v[180:183], v[54:57]
	v_mfma_f32_16x16x32_bf16 v[50:53], v[168:171], v[180:183], v[50:53]
	v_mfma_f32_16x16x32_bf16 v[46:49], v[160:163], v[192:195], v[46:49]
	v_mfma_f32_16x16x32_bf16 v[42:45], v[168:171], v[192:195], v[42:45]
	v_mfma_f32_16x16x32_bf16 v[38:41], v[160:163], v[196:199], v[38:41]
	v_mfma_f32_16x16x32_bf16 v[34:37], v[168:171], v[196:199], v[34:37]
	v_mfma_f32_16x16x32_bf16 v[62:65], v[164:167], v[184:187], v[62:65]
	v_mfma_f32_16x16x32_bf16 v[58:61], v[172:175], v[184:187], v[58:61]
	v_mfma_f32_16x16x32_bf16 v[54:57], v[164:167], v[188:191], v[54:57]
	v_mfma_f32_16x16x32_bf16 v[50:53], v[172:175], v[188:191], v[50:53]
	v_mfma_f32_16x16x32_bf16 v[46:49], v[164:167], v[200:203], v[46:49]
	v_mfma_f32_16x16x32_bf16 v[42:45], v[172:175], v[200:203], v[42:45]
	v_mfma_f32_16x16x32_bf16 v[38:41], v[164:167], v[218:221], v[38:41]
	v_mfma_f32_16x16x32_bf16 v[34:37], v[172:175], v[218:221], v[34:37]
	v_mfma_f32_16x16x32_bf16 v[30:33], v[222:225], v[176:179], v[30:33]
	v_mfma_f32_16x16x32_bf16 v[26:29], v[230:233], v[176:179], v[26:29]
	v_mfma_f32_16x16x32_bf16 v[22:25], v[222:225], v[180:183], v[22:25]
	v_mfma_f32_16x16x32_bf16 v[18:21], v[230:233], v[180:183], v[18:21]
	v_mfma_f32_16x16x32_bf16 v[14:17], v[222:225], v[192:195], v[14:17]
	v_mfma_f32_16x16x32_bf16 v[10:13], v[230:233], v[192:195], v[10:13]
	v_mfma_f32_16x16x32_bf16 v[6:9], v[222:225], v[196:199], v[6:9]
	v_mfma_f32_16x16x32_bf16 v[2:5], v[230:233], v[196:199], v[2:5]
	v_mfma_f32_16x16x32_bf16 v[30:33], v[226:229], v[184:187], v[30:33]
	v_mfma_f32_16x16x32_bf16 v[26:29], v[234:237], v[184:187], v[26:29]
	v_mfma_f32_16x16x32_bf16 v[22:25], v[226:229], v[188:191], v[22:25]
	v_mfma_f32_16x16x32_bf16 v[18:21], v[234:237], v[188:191], v[18:21]
	v_mfma_f32_16x16x32_bf16 v[14:17], v[226:229], v[200:203], v[14:17]
	v_mfma_f32_16x16x32_bf16 v[10:13], v[234:237], v[200:203], v[10:13]
	v_mfma_f32_16x16x32_bf16 v[6:9], v[226:229], v[218:221], v[6:9]
	v_mfma_f32_16x16x32_bf16 v[2:5], v[234:237], v[218:221], v[2:5]
	s_setprio 0
	s_barrier
	ds_read_b128 v[168:171], v207 offset:32768
	ds_read_b128 v[172:175], v209 offset:32768
	ds_read_b128 v[176:179], v207 offset:34816
	ds_read_b128 v[180:183], v209 offset:34816
	s_mov_b32 m0, s17
	ds_read_b128 v[184:187], v148 offset:32768
	ds_read_b128 v[188:191], v148 offset:34816
	ds_read_b128 v[192:195], v149 offset:32768
	ds_read_b128 v[196:199], v149 offset:34816
	ds_read_b128 v[200:203], v148 offset:36864
	ds_read_b128 v[218:221], v148 offset:38912
	ds_read_b128 v[222:225], v149 offset:36864
	ds_read_b128 v[226:229], v149 offset:38912
	s_add_u32 s100, vcc_lo, s58
	s_addc_u32 s101, vcc_hi, s59
	global_load_lds_dwordx4 v206, s[100:101]
	s_mov_b32 m0, s18
	s_add_u32 s100, vcc_lo, s58
	s_addc_u32 s101, vcc_hi, s59
	global_load_lds_dwordx4 v208, s[100:101]
	s_waitcnt lgkmcnt(8)
	s_waitcnt vmcnt(10)
	s_barrier
	s_waitcnt lgkmcnt(0)
	s_setprio 1
	s_waitcnt lgkmcnt(0)
	v_mfma_f32_16x16x32_bf16 v[126:129], v[168:171], v[184:187], v[126:129]
	v_mfma_f32_16x16x32_bf16 v[122:125], v[176:179], v[184:187], v[122:125]
	v_mfma_f32_16x16x32_bf16 v[118:121], v[168:171], v[188:191], v[118:121]
	v_mfma_f32_16x16x32_bf16 v[114:117], v[176:179], v[188:191], v[114:117]
	v_mfma_f32_16x16x32_bf16 v[110:113], v[168:171], v[200:203], v[110:113]
	v_mfma_f32_16x16x32_bf16 v[106:109], v[176:179], v[200:203], v[106:109]
	v_mfma_f32_16x16x32_bf16 v[102:105], v[168:171], v[218:221], v[102:105]
	v_mfma_f32_16x16x32_bf16 v[98:101], v[176:179], v[218:221], v[98:101]
	v_mfma_f32_16x16x32_bf16 v[126:129], v[172:175], v[192:195], v[126:129]
	v_mfma_f32_16x16x32_bf16 v[122:125], v[180:183], v[192:195], v[122:125]
	v_mfma_f32_16x16x32_bf16 v[118:121], v[172:175], v[196:199], v[118:121]
	v_mfma_f32_16x16x32_bf16 v[114:117], v[180:183], v[196:199], v[114:117]
	v_mfma_f32_16x16x32_bf16 v[110:113], v[172:175], v[222:225], v[110:113]
	v_mfma_f32_16x16x32_bf16 v[106:109], v[180:183], v[222:225], v[106:109]
	v_mfma_f32_16x16x32_bf16 v[102:105], v[172:175], v[226:229], v[102:105]
	v_mfma_f32_16x16x32_bf16 v[98:101], v[180:183], v[226:229], v[98:101]
	s_setprio 0
	s_barrier
	s_mov_b32 m0, s19
	ds_read_b128 v[230:233], v207 offset:49152
	ds_read_b128 v[234:237], v209 offset:49152
	ds_read_b128 v[238:241], v207 offset:51200
	ds_read_b128 v[242:245], v209 offset:51200
	s_add_u32 s100, vcc_lo, s28
	s_addc_u32 s101, vcc_hi, s29
	global_load_lds_dwordx4 v210, s[100:101]
	s_mov_b32 m0, s20
	s_add_u32 s100, vcc_lo, s28
	s_addc_u32 s101, vcc_hi, s29
	global_load_lds_dwordx4 v214, s[100:101]
	s_waitcnt vmcnt(10)
	s_waitcnt lgkmcnt(0)
	s_barrier
	s_waitcnt lgkmcnt(0)
	s_setprio 1
	s_waitcnt lgkmcnt(0)
	v_mfma_f32_16x16x32_bf16 v[94:97], v[230:233], v[184:187], v[94:97]
	v_mfma_f32_16x16x32_bf16 v[90:93], v[238:241], v[184:187], v[90:93]
	v_mfma_f32_16x16x32_bf16 v[86:89], v[230:233], v[188:191], v[86:89]
	v_mfma_f32_16x16x32_bf16 v[82:85], v[238:241], v[188:191], v[82:85]
	v_mfma_f32_16x16x32_bf16 v[78:81], v[230:233], v[200:203], v[78:81]
	v_mfma_f32_16x16x32_bf16 v[74:77], v[238:241], v[200:203], v[74:77]
	v_mfma_f32_16x16x32_bf16 v[70:73], v[230:233], v[218:221], v[70:73]
	v_mfma_f32_16x16x32_bf16 v[66:69], v[238:241], v[218:221], v[66:69]
	v_mfma_f32_16x16x32_bf16 v[94:97], v[234:237], v[192:195], v[94:97]
	v_mfma_f32_16x16x32_bf16 v[90:93], v[242:245], v[192:195], v[90:93]
	v_mfma_f32_16x16x32_bf16 v[86:89], v[234:237], v[196:199], v[86:89]
	v_mfma_f32_16x16x32_bf16 v[82:85], v[242:245], v[196:199], v[82:85]
	v_mfma_f32_16x16x32_bf16 v[78:81], v[234:237], v[222:225], v[78:81]
	v_mfma_f32_16x16x32_bf16 v[74:77], v[242:245], v[222:225], v[74:77]
	v_mfma_f32_16x16x32_bf16 v[70:73], v[234:237], v[226:229], v[70:73]
	v_mfma_f32_16x16x32_bf16 v[66:69], v[242:245], v[226:229], v[66:69]
	s_setprio 0
	s_mov_b32 m0, s21
	s_barrier
	ds_read_b128 v[184:187], v148 offset:49152
	ds_read_b128 v[188:191], v148 offset:51200
	ds_read_b128 v[192:195], v149 offset:49152
	ds_read_b128 v[196:199], v149 offset:51200
	ds_read_b128 v[200:203], v148 offset:53248
	ds_read_b128 v[218:221], v148 offset:55296
	ds_read_b128 v[222:225], v149 offset:53248
	ds_read_b128 v[226:229], v149 offset:55296
	s_add_u32 s100, vcc_lo, s62
	s_addc_u32 s101, vcc_hi, s63
	global_load_lds_dwordx4 v206, s[100:101]
	s_mov_b32 m0, s22
	s_add_u32 s100, vcc_lo, s62
	s_addc_u32 s101, vcc_hi, s63
	global_load_lds_dwordx4 v208, s[100:101]
	s_mov_b32 m0, s23
	s_add_u32 s100, vcc_lo, s30
	s_addc_u32 s101, vcc_hi, s31
	global_load_lds_dwordx4 v210, s[100:101]
	s_mov_b32 m0, s24
	s_add_u32 s100, vcc_lo, s30
	s_addc_u32 s101, vcc_hi, s31
	global_load_lds_dwordx4 v214, s[100:101]
	s_waitcnt vmcnt(10)
	s_waitcnt lgkmcnt(0)
	s_barrier
	s_waitcnt lgkmcnt(0)
	s_setprio 1
	s_waitcnt lgkmcnt(0)
	v_mfma_f32_16x16x32_bf16 v[62:65], v[168:171], v[184:187], v[62:65]
	v_mfma_f32_16x16x32_bf16 v[58:61], v[176:179], v[184:187], v[58:61]
	v_mfma_f32_16x16x32_bf16 v[54:57], v[168:171], v[188:191], v[54:57]
	v_mfma_f32_16x16x32_bf16 v[50:53], v[176:179], v[188:191], v[50:53]
	v_mfma_f32_16x16x32_bf16 v[46:49], v[168:171], v[200:203], v[46:49]
	v_mfma_f32_16x16x32_bf16 v[42:45], v[176:179], v[200:203], v[42:45]
	v_mfma_f32_16x16x32_bf16 v[38:41], v[168:171], v[218:221], v[38:41]
	v_mfma_f32_16x16x32_bf16 v[34:37], v[176:179], v[218:221], v[34:37]
	v_mfma_f32_16x16x32_bf16 v[62:65], v[172:175], v[192:195], v[62:65]
	v_mfma_f32_16x16x32_bf16 v[58:61], v[180:183], v[192:195], v[58:61]
	v_mfma_f32_16x16x32_bf16 v[54:57], v[172:175], v[196:199], v[54:57]
	v_mfma_f32_16x16x32_bf16 v[50:53], v[180:183], v[196:199], v[50:53]
	v_mfma_f32_16x16x32_bf16 v[46:49], v[172:175], v[222:225], v[46:49]
	v_mfma_f32_16x16x32_bf16 v[42:45], v[180:183], v[222:225], v[42:45]
	v_mfma_f32_16x16x32_bf16 v[38:41], v[172:175], v[226:229], v[38:41]
	v_mfma_f32_16x16x32_bf16 v[34:37], v[180:183], v[226:229], v[34:37]
	v_mfma_f32_16x16x32_bf16 v[30:33], v[230:233], v[184:187], v[30:33]
	v_mfma_f32_16x16x32_bf16 v[26:29], v[238:241], v[184:187], v[26:29]
	v_mfma_f32_16x16x32_bf16 v[22:25], v[230:233], v[188:191], v[22:25]
	v_mfma_f32_16x16x32_bf16 v[18:21], v[238:241], v[188:191], v[18:21]
	v_mfma_f32_16x16x32_bf16 v[14:17], v[230:233], v[200:203], v[14:17]
	v_mfma_f32_16x16x32_bf16 v[10:13], v[238:241], v[200:203], v[10:13]
	v_mfma_f32_16x16x32_bf16 v[6:9], v[230:233], v[218:221], v[6:9]
	v_mfma_f32_16x16x32_bf16 v[2:5], v[238:241], v[218:221], v[2:5]
	v_mfma_f32_16x16x32_bf16 v[30:33], v[234:237], v[192:195], v[30:33]
	v_mfma_f32_16x16x32_bf16 v[26:29], v[242:245], v[192:195], v[26:29]
	v_mfma_f32_16x16x32_bf16 v[22:25], v[234:237], v[196:199], v[22:25]
	v_mfma_f32_16x16x32_bf16 v[18:21], v[242:245], v[196:199], v[18:21]
	v_mfma_f32_16x16x32_bf16 v[14:17], v[234:237], v[222:225], v[14:17]
	v_mfma_f32_16x16x32_bf16 v[10:13], v[242:245], v[222:225], v[10:13]
	v_mfma_f32_16x16x32_bf16 v[6:9], v[234:237], v[226:229], v[6:9]
	v_mfma_f32_16x16x32_bf16 v[2:5], v[242:245], v[226:229], v[2:5]
	s_setprio 0
	s_add_u32 vcc_lo, vcc_lo, s54
	s_addc_u32 vcc_hi, vcc_hi, s55
	s_add_i32 s4, s4, 2
	s_cmp_lt_u32 s4, 28
	v_lshl_add_u64 v[134:135], v[134:135], 0, s[54:55]
	s_barrier
	s_cbranch_scc1 .LBB0_357
	s_waitcnt vmcnt(6)
	v_or_b32_e32 v0, 0x10000, v150
	v_add_u32_e32 v153, 0x10800, v150
	v_or_b32_e32 v152, 0x10000, v151
	v_add_u32_e32 v154, 0x10800, v151
	v_or_b32_e32 v155, 0x14000, v150
	v_add_u32_e32 v157, 0x14800, v150
	v_or_b32_e32 v156, 0x14000, v151
	v_add_u32_e32 v158, 0x14800, v151
	v_or_b32_e32 v159, 0x18000, v150
	v_add_u32_e32 v161, 0x18800, v150
	v_or_b32_e32 v160, 0x18000, v151
	v_add_u32_e32 v162, 0x18800, v151
	v_or_b32_e32 v163, 0x1c000, v150
	v_add_u32_e32 v165, 0x1c800, v150
	v_or_b32_e32 v164, 0x1c000, v151
	v_add_u32_e32 v166, 0x1c800, v151
	s_mov_b64 s[2:3], 0xf80
	s_mov_b32 m0, s12
	v_lshl_add_u64 v[134:135], v[138:139], 0, s[2:3]
	ds_read_b128 v[140:143], v0
	ds_read_b128 v[144:147], v152
	ds_read_b128 v[150:153], v153
	ds_read_b128 v[168:171], v154
	ds_read_b128 v[172:175], v148
	ds_read_b128 v[176:179], v148 offset:2048
	ds_read_b128 v[180:183], v149
	ds_read_b128 v[184:187], v149 offset:2048
	ds_read_b128 v[188:191], v148 offset:4096
	ds_read_b128 v[192:195], v148 offset:6144
	ds_read_b128 v[196:199], v149 offset:4096
	ds_read_b128 v[200:203], v149 offset:6144
	global_load_lds_dwordx4 v[134:135], off
	v_lshl_add_u64 v[134:135], v[136:137], 0, s[2:3]
	s_mov_b32 m0, s5
	s_nop 0
	global_load_lds_dwordx4 v[134:135], off
	s_barrier
	s_waitcnt lgkmcnt(0)
	s_setprio 1
	s_waitcnt lgkmcnt(0)
	v_mfma_f32_16x16x32_bf16 v[126:129], v[140:143], v[172:175], v[126:129]
	v_mfma_f32_16x16x32_bf16 v[122:125], v[150:153], v[172:175], v[122:125]
	v_mfma_f32_16x16x32_bf16 v[118:121], v[140:143], v[176:179], v[118:121]
	v_mfma_f32_16x16x32_bf16 v[110:113], v[140:143], v[188:191], v[110:113]
	v_mfma_f32_16x16x32_bf16 v[106:109], v[150:153], v[188:191], v[106:109]
	v_mfma_f32_16x16x32_bf16 v[126:129], v[144:147], v[180:183], v[126:129]
	v_mfma_f32_16x16x32_bf16 v[122:125], v[168:171], v[180:183], v[122:125]
	v_mfma_f32_16x16x32_bf16 v[118:121], v[144:147], v[184:187], v[118:121]
	v_mfma_f32_16x16x32_bf16 v[114:117], v[150:153], v[176:179], v[114:117]
	v_mfma_f32_16x16x32_bf16 v[110:113], v[144:147], v[196:199], v[110:113]
	v_mfma_f32_16x16x32_bf16 v[106:109], v[168:171], v[196:199], v[106:109]
	v_mfma_f32_16x16x32_bf16 v[102:105], v[140:143], v[192:195], v[102:105]
	v_mfma_f32_16x16x32_bf16 v[98:101], v[150:153], v[192:195], v[98:101]
	v_mfma_f32_16x16x32_bf16 v[134:137], v[168:171], v[184:187], v[114:117]
	v_mfma_f32_16x16x32_bf16 v[218:221], v[144:147], v[200:203], v[102:105]
	v_mfma_f32_16x16x32_bf16 v[222:225], v[168:171], v[200:203], v[98:101]
	s_setprio 0
	s_barrier
	s_nop 2
	ds_read_b128 v[98:101], v155
	ds_read_b128 v[102:105], v156
	ds_read_b128 v[114:117], v157
	ds_read_b128 v[154:157], v158
	s_barrier
	s_waitcnt lgkmcnt(0)
	s_setprio 1
	s_waitcnt lgkmcnt(0)
	v_mfma_f32_16x16x32_bf16 v[94:97], v[98:101], v[172:175], v[94:97]
	v_mfma_f32_16x16x32_bf16 v[90:93], v[114:117], v[172:175], v[90:93]
	v_mfma_f32_16x16x32_bf16 v[78:81], v[98:101], v[188:191], v[78:81]
	v_mfma_f32_16x16x32_bf16 v[74:77], v[114:117], v[188:191], v[74:77]
	v_mfma_f32_16x16x32_bf16 v[94:97], v[102:105], v[180:183], v[94:97]
	v_mfma_f32_16x16x32_bf16 v[90:93], v[154:157], v[180:183], v[90:93]
	v_mfma_f32_16x16x32_bf16 v[86:89], v[98:101], v[176:179], v[86:89]
	v_mfma_f32_16x16x32_bf16 v[82:85], v[114:117], v[176:179], v[82:85]
	v_mfma_f32_16x16x32_bf16 v[78:81], v[102:105], v[196:199], v[78:81]
	v_mfma_f32_16x16x32_bf16 v[74:77], v[154:157], v[196:199], v[74:77]
	v_mfma_f32_16x16x32_bf16 v[70:73], v[98:101], v[192:195], v[70:73]
	v_mfma_f32_16x16x32_bf16 v[66:69], v[114:117], v[192:195], v[66:69]
	v_mfma_f32_16x16x32_bf16 v[172:175], v[102:105], v[184:187], v[86:89]
	v_mfma_f32_16x16x32_bf16 v[176:179], v[154:157], v[184:187], v[82:85]
	v_mfma_f32_16x16x32_bf16 v[180:183], v[102:105], v[200:203], v[70:73]
	v_mfma_f32_16x16x32_bf16 v[184:187], v[154:157], v[200:203], v[66:69]
	s_setprio 0
	s_barrier
	s_nop 1
	ds_read_b128 v[66:69], v148 offset:16384
	ds_read_b128 v[70:73], v148 offset:18432
	ds_read_b128 v[82:85], v149 offset:16384
	ds_read_b128 v[86:89], v149 offset:18432
	ds_read_b128 v[188:191], v148 offset:20480
	ds_read_b128 v[192:195], v148 offset:22528
	ds_read_b128 v[196:199], v149 offset:20480
	ds_read_b128 v[200:203], v149 offset:22528
	s_waitcnt vmcnt(4)
	s_barrier
	s_waitcnt lgkmcnt(0)
	s_setprio 1
	s_waitcnt lgkmcnt(0)
	v_mfma_f32_16x16x32_bf16 v[62:65], v[140:143], v[66:69], v[62:65]
	v_mfma_f32_16x16x32_bf16 v[58:61], v[150:153], v[66:69], v[58:61]
	v_mfma_f32_16x16x32_bf16 v[46:49], v[140:143], v[188:191], v[46:49]
	v_mfma_f32_16x16x32_bf16 v[42:45], v[150:153], v[188:191], v[42:45]
	v_mfma_f32_16x16x32_bf16 v[62:65], v[144:147], v[82:85], v[62:65]
	v_mfma_f32_16x16x32_bf16 v[58:61], v[168:171], v[82:85], v[58:61]
	v_mfma_f32_16x16x32_bf16 v[54:57], v[140:143], v[70:73], v[54:57]
	v_mfma_f32_16x16x32_bf16 v[50:53], v[150:153], v[70:73], v[50:53]
	v_mfma_f32_16x16x32_bf16 v[46:49], v[144:147], v[196:199], v[46:49]
	v_mfma_f32_16x16x32_bf16 v[42:45], v[168:171], v[196:199], v[42:45]
	v_mfma_f32_16x16x32_bf16 v[38:41], v[140:143], v[192:195], v[38:41]
	v_mfma_f32_16x16x32_bf16 v[34:37], v[150:153], v[192:195], v[34:37]
	v_mfma_f32_16x16x32_bf16 v[226:229], v[144:147], v[86:89], v[54:57]
	v_mfma_f32_16x16x32_bf16 v[230:233], v[168:171], v[86:89], v[50:53]
	v_mfma_f32_16x16x32_bf16 v[138:141], v[144:147], v[200:203], v[38:41]
	v_mfma_f32_16x16x32_bf16 v[142:145], v[168:171], v[200:203], v[34:37]
	s_setprio 0
	s_setprio 1
	v_mfma_f32_16x16x32_bf16 v[30:33], v[98:101], v[66:69], v[30:33]
	v_mfma_f32_16x16x32_bf16 v[26:29], v[114:117], v[66:69], v[26:29]
	v_mfma_f32_16x16x32_bf16 v[14:17], v[98:101], v[188:191], v[14:17]
	v_mfma_f32_16x16x32_bf16 v[10:13], v[114:117], v[188:191], v[10:13]
	v_mfma_f32_16x16x32_bf16 v[30:33], v[102:105], v[82:85], v[30:33]
	v_mfma_f32_16x16x32_bf16 v[26:29], v[154:157], v[82:85], v[26:29]
	v_mfma_f32_16x16x32_bf16 v[22:25], v[98:101], v[70:73], v[22:25]
	v_mfma_f32_16x16x32_bf16 v[18:21], v[114:117], v[70:73], v[18:21]
	v_mfma_f32_16x16x32_bf16 v[14:17], v[102:105], v[196:199], v[14:17]
	v_mfma_f32_16x16x32_bf16 v[10:13], v[154:157], v[196:199], v[10:13]
	v_mfma_f32_16x16x32_bf16 v[6:9], v[98:101], v[192:195], v[6:9]
	v_mfma_f32_16x16x32_bf16 v[2:5], v[114:117], v[192:195], v[2:5]
	v_mfma_f32_16x16x32_bf16 v[150:153], v[102:105], v[86:89], v[22:25]
	v_mfma_f32_16x16x32_bf16 v[168:171], v[154:157], v[86:89], v[18:21]
	v_mfma_f32_16x16x32_bf16 v[188:191], v[102:105], v[200:203], v[6:9]
	v_mfma_f32_16x16x32_bf16 v[154:157], v[154:157], v[200:203], v[2:5]
	s_setprio 0
	s_barrier
	s_nop 1
	ds_read_b128 v[2:5], v159
	ds_read_b128 v[6:9], v160
	ds_read_b128 v[158:161], v161
	ds_read_b128 v[192:195], v162
	ds_read_b128 v[18:21], v148 offset:32768
	ds_read_b128 v[22:25], v148 offset:34816
	ds_read_b128 v[34:37], v149 offset:32768
	ds_read_b128 v[38:41], v149 offset:34816
	ds_read_b128 v[50:53], v148 offset:36864
	ds_read_b128 v[54:57], v148 offset:38912
	ds_read_b128 v[196:199], v149 offset:36864
	ds_read_b128 v[200:203], v149 offset:38912
	s_waitcnt vmcnt(2)
	s_barrier
	s_waitcnt lgkmcnt(0)
	s_setprio 1
	s_waitcnt lgkmcnt(0)
	v_mfma_f32_16x16x32_bf16 v[66:69], v[2:5], v[18:21], v[126:129]
	v_mfma_f32_16x16x32_bf16 v[126:129], v[6:9], v[34:37], v[66:69]
	v_mfma_f32_16x16x32_bf16 v[66:69], v[158:161], v[18:21], v[122:125]
	v_mfma_f32_16x16x32_bf16 v[114:117], v[192:195], v[34:37], v[66:69]
	v_mfma_f32_16x16x32_bf16 v[66:69], v[2:5], v[22:25], v[118:121]
	v_mfma_f32_16x16x32_bf16 v[102:105], v[6:9], v[38:41], v[66:69]
	v_mfma_f32_16x16x32_bf16 v[66:69], v[158:161], v[22:25], v[134:137]
	v_mfma_f32_16x16x32_bf16 v[98:101], v[192:195], v[38:41], v[66:69]
	v_mfma_f32_16x16x32_bf16 v[66:69], v[2:5], v[50:53], v[110:113]
	v_mfma_f32_16x16x32_bf16 v[86:89], v[6:9], v[196:199], v[66:69]
	v_mfma_f32_16x16x32_bf16 v[66:69], v[158:161], v[50:53], v[106:109]
	v_mfma_f32_16x16x32_bf16 v[82:85], v[192:195], v[196:199], v[66:69]
	v_mfma_f32_16x16x32_bf16 v[66:69], v[2:5], v[54:57], v[218:221]
	v_mfma_f32_16x16x32_bf16 v[70:73], v[6:9], v[200:203], v[66:69]
	v_mfma_f32_16x16x32_bf16 v[66:69], v[158:161], v[54:57], v[222:225]
	v_mfma_f32_16x16x32_bf16 v[66:69], v[192:195], v[200:203], v[66:69]
	s_setprio 0
	s_barrier
	ds_read_b128 v[134:137], v163
	ds_read_b128 v[218:221], v164
	ds_read_b128 v[162:165], v165
	ds_read_b128 v[222:225], v166
	s_waitcnt vmcnt(0)
	s_barrier
	s_waitcnt lgkmcnt(0)
	s_setprio 1
	s_waitcnt lgkmcnt(0)
	v_mfma_f32_16x16x32_bf16 v[94:97], v[134:137], v[18:21], v[94:97]
	v_mfma_f32_16x16x32_bf16 v[18:21], v[162:165], v[18:21], v[90:93]
	v_mfma_f32_16x16x32_bf16 v[118:121], v[222:225], v[34:37], v[18:21]
	v_mfma_f32_16x16x32_bf16 v[18:21], v[134:137], v[22:25], v[172:175]
	v_mfma_f32_16x16x32_bf16 v[110:113], v[218:221], v[38:41], v[18:21]
	v_mfma_f32_16x16x32_bf16 v[18:21], v[162:165], v[22:25], v[176:179]
	v_mfma_f32_16x16x32_bf16 v[106:109], v[222:225], v[38:41], v[18:21]
	v_mfma_f32_16x16x32_bf16 v[18:21], v[134:137], v[50:53], v[78:81]
	v_mfma_f32_16x16x32_bf16 v[122:125], v[218:221], v[34:37], v[94:97]
	v_mfma_f32_16x16x32_bf16 v[94:97], v[218:221], v[196:199], v[18:21]
	v_mfma_f32_16x16x32_bf16 v[18:21], v[162:165], v[50:53], v[74:77]
	v_mfma_f32_16x16x32_bf16 v[90:93], v[222:225], v[196:199], v[18:21]
	v_mfma_f32_16x16x32_bf16 v[18:21], v[134:137], v[54:57], v[180:183]
	v_mfma_f32_16x16x32_bf16 v[78:81], v[218:221], v[200:203], v[18:21]
	v_mfma_f32_16x16x32_bf16 v[18:21], v[162:165], v[54:57], v[184:187]
	v_mfma_f32_16x16x32_bf16 v[74:77], v[222:225], v[200:203], v[18:21]
	s_setprio 0
	s_barrier
	ds_read_b128 v[172:175], v148 offset:49152
	ds_read_b128 v[176:179], v148 offset:51200
	ds_read_b128 v[180:183], v149 offset:49152
	ds_read_b128 v[184:187], v149 offset:51200
	ds_read_b128 v[196:199], v148 offset:53248
	ds_read_b128 v[200:203], v148 offset:55296
	ds_read_b128 v[234:237], v149 offset:53248
	ds_read_b128 v[146:149], v149 offset:55296
	s_barrier
	s_waitcnt lgkmcnt(0)
	s_setprio 1
	s_waitcnt lgkmcnt(0)
	v_mfma_f32_16x16x32_bf16 v[18:21], v[2:5], v[172:175], v[62:65]
	v_mfma_f32_16x16x32_bf16 v[54:57], v[6:9], v[180:183], v[18:21]
	v_mfma_f32_16x16x32_bf16 v[18:21], v[158:161], v[172:175], v[58:61]
	v_mfma_f32_16x16x32_bf16 v[50:53], v[192:195], v[180:183], v[18:21]
	v_mfma_f32_16x16x32_bf16 v[18:21], v[2:5], v[176:179], v[226:229]
	v_mfma_f32_16x16x32_bf16 v[38:41], v[6:9], v[184:187], v[18:21]
	v_mfma_f32_16x16x32_bf16 v[18:21], v[158:161], v[176:179], v[230:233]
	v_mfma_f32_16x16x32_bf16 v[34:37], v[192:195], v[184:187], v[18:21]
	v_mfma_f32_16x16x32_bf16 v[18:21], v[2:5], v[196:199], v[46:49]
	v_mfma_f32_16x16x32_bf16 v[2:5], v[2:5], v[200:203], v[138:141]
	v_mfma_f32_16x16x32_bf16 v[22:25], v[6:9], v[234:237], v[18:21]
	v_mfma_f32_16x16x32_bf16 v[18:21], v[158:161], v[196:199], v[42:45]
	v_mfma_f32_16x16x32_bf16 v[6:9], v[6:9], v[146:149], v[2:5]
	v_mfma_f32_16x16x32_bf16 v[2:5], v[158:161], v[200:203], v[142:145]
	v_mfma_f32_16x16x32_bf16 v[18:21], v[192:195], v[234:237], v[18:21]
	v_mfma_f32_16x16x32_bf16 v[2:5], v[192:195], v[146:149], v[2:5]
	s_setprio 0
	s_setprio 1
	v_mfma_f32_16x16x32_bf16 v[26:29], v[162:165], v[172:175], v[26:29]
	v_mfma_f32_16x16x32_bf16 v[58:61], v[222:225], v[180:183], v[26:29]
	v_mfma_f32_16x16x32_bf16 v[26:29], v[134:137], v[176:179], v[150:153]
	v_mfma_f32_16x16x32_bf16 v[46:49], v[218:221], v[184:187], v[26:29]
	v_mfma_f32_16x16x32_bf16 v[26:29], v[162:165], v[176:179], v[168:171]
	v_mfma_f32_16x16x32_bf16 v[10:13], v[162:165], v[196:199], v[10:13]
	v_mfma_f32_16x16x32_bf16 v[30:33], v[134:137], v[172:175], v[30:33]
	v_mfma_f32_16x16x32_bf16 v[42:45], v[222:225], v[184:187], v[26:29]
	v_mfma_f32_16x16x32_bf16 v[14:17], v[134:137], v[196:199], v[14:17]
	v_mfma_f32_16x16x32_bf16 v[26:29], v[222:225], v[234:237], v[10:13]
	v_mfma_f32_16x16x32_bf16 v[10:13], v[134:137], v[200:203], v[188:191]
	v_mfma_f32_16x16x32_bf16 v[62:65], v[218:221], v[180:183], v[30:33]
	v_mfma_f32_16x16x32_bf16 v[30:33], v[218:221], v[234:237], v[14:17]
	v_mfma_f32_16x16x32_bf16 v[14:17], v[218:221], v[146:149], v[10:13]
	v_mfma_f32_16x16x32_bf16 v[10:13], v[162:165], v[200:203], v[154:157]
	v_mfma_f32_16x16x32_bf16 v[10:13], v[222:225], v[146:149], v[10:13]
	s_setprio 0
	s_cmpk_gt_u32 s0, 0xff
	s_barrier
	s_cbranch_scc1 .LBB0_329
	s_barrier
	s_branch .LBB0_329

.LBB0_596:
	s_lshl_b32 s19, s19, 5
	v_and_b32_e32 v0, 15, v17
	s_and_b32 s19, s19, 0x60
	v_lshlrev_b32_e32 v19, 7, v0
	v_or_b32_e32 v0, s19, v0
	s_add_i32 s19, s1, 0x18000
	s_mov_b64 s[24:25], 0x80
	v_lshl_or_b32 v19, s20, 13, v19
	v_lshl_add_u64 v[2:3], v[2:3], 0, s[24:25]
	s_mov_b32 m0, s19
	s_add_i32 s20, s1, 0x1a000
	s_waitcnt vmcnt(4)
	s_barrier
	global_load_lds_dwordx4 v[2:3], off
	v_lshl_add_u64 v[2:3], v[4:5], 0, s[24:25]
	s_mov_b32 m0, s20
	s_add_i32 s21, s1, 0x8000
	global_load_lds_dwordx4 v[2:3], off
	v_lshl_add_u64 v[2:3], v[8:9], 0, s[24:25]
	s_mov_b32 m0, s21
	s_add_i32 s22, s1, 0xa000
	global_load_lds_dwordx4 v[2:3], off nt
	v_lshl_add_u64 v[2:3], v[6:7], 0, s[24:25]
	s_mov_b32 m0, s22
	s_add_i32 s23, s1, 0x1c000
	global_load_lds_dwordx4 v[2:3], off nt
	v_lshl_add_u64 v[2:3], v[12:13], 0, s[24:25]
	s_mov_b32 m0, s23
	v_and_b32_e32 v20, 3, v18
	global_load_lds_dwordx4 v[2:3], off
	v_lshl_add_u64 v[2:3], v[10:11], 0, s[24:25]
	s_add_i32 s24, s1, 0x1e000
	s_mov_b32 m0, s24
	v_bfe_u32 v17, v17, 1, 3
	global_load_lds_dwordx4 v[2:3], off
	v_bitop3_b32 v18, v18, v17, 3 bitop3:0x6c
	v_bitop3_b32 v17, v20, v17, 4 bitop3:0x36
	v_lshlrev_b32_e32 v18, 4, v18
	v_lshlrev_b32_e32 v17, 4, v17
	v_lshlrev_b32_e32 v0, 7, v0
	v_or_b32_e32 v154, v0, v18
	v_or_b32_e32 v155, v0, v17
	v_add_u32_e32 v0, v16, v14
	s_waitcnt vmcnt(6)
	v_lshlrev_b64 v[2:3], 1, v[0:1]
	v_add_u32_e32 v0, v15, v14
	v_lshl_add_u64 v[142:143], s[8:9], 0, v[2:3]
	v_lshlrev_b64 v[4:5], 1, v[0:1]
	v_lshl_add_u64 v[146:147], s[10:11], 0, v[2:3]
	v_mov_b32_e32 v2, 0
	v_or_b32_e32 v152, v18, v19
	v_or_b32_e32 v153, v17, v19
	v_lshl_add_u64 v[144:145], s[8:9], 0, v[4:5]
	v_lshl_add_u64 v[148:149], s[10:11], 0, v[4:5]
	s_mov_b32 s10, -2
	v_mov_b64_e32 v[150:151], v[130:131]
	v_mov_b32_e32 v3, v2
	v_mov_b32_e32 v4, v2
	v_mov_b32_e32 v5, v2
	v_mov_b32_e32 v6, v2
	v_mov_b32_e32 v7, v2
	v_mov_b32_e32 v8, v2
	v_mov_b32_e32 v9, v2
	v_mov_b32_e32 v10, v2
	v_mov_b32_e32 v11, v2
	v_mov_b32_e32 v12, v2
	v_mov_b32_e32 v13, v2
	v_mov_b32_e32 v14, v2
	v_mov_b32_e32 v15, v2
	v_mov_b32_e32 v16, v2
	v_mov_b32_e32 v17, v2
	v_mov_b32_e32 v18, v2
	v_mov_b32_e32 v19, v2
	v_mov_b32_e32 v20, v2
	v_mov_b32_e32 v21, v2
	v_mov_b32_e32 v22, v2
	v_mov_b32_e32 v23, v2
	v_mov_b32_e32 v24, v2
	v_mov_b32_e32 v25, v2
	v_mov_b32_e32 v26, v2
	v_mov_b32_e32 v27, v2
	v_mov_b32_e32 v28, v2
	v_mov_b32_e32 v29, v2
	v_mov_b32_e32 v30, v2
	v_mov_b32_e32 v31, v2
	v_mov_b32_e32 v32, v2
	v_mov_b32_e32 v33, v2
	v_mov_b32_e32 v34, v2
	v_mov_b32_e32 v35, v2
	v_mov_b32_e32 v36, v2
	v_mov_b32_e32 v37, v2
	v_mov_b32_e32 v38, v2
	v_mov_b32_e32 v39, v2
	v_mov_b32_e32 v40, v2
	v_mov_b32_e32 v41, v2
	v_mov_b32_e32 v42, v2
	v_mov_b32_e32 v43, v2
	v_mov_b32_e32 v44, v2
	v_mov_b32_e32 v45, v2
	v_mov_b32_e32 v46, v2
	v_mov_b32_e32 v47, v2
	v_mov_b32_e32 v48, v2
	v_mov_b32_e32 v49, v2
	v_mov_b32_e32 v50, v2
	v_mov_b32_e32 v51, v2
	v_mov_b32_e32 v52, v2
	v_mov_b32_e32 v53, v2
	v_mov_b32_e32 v54, v2
	v_mov_b32_e32 v55, v2
	v_mov_b32_e32 v56, v2
	v_mov_b32_e32 v57, v2
	v_mov_b32_e32 v58, v2
	v_mov_b32_e32 v59, v2
	v_mov_b32_e32 v60, v2
	v_mov_b32_e32 v61, v2
	v_mov_b32_e32 v62, v2
	v_mov_b32_e32 v63, v2
	v_mov_b32_e32 v64, v2
	v_mov_b32_e32 v65, v2
	v_mov_b32_e32 v66, v2
	v_mov_b32_e32 v67, v2
	v_mov_b32_e32 v68, v2
	v_mov_b32_e32 v69, v2
	v_mov_b32_e32 v70, v2
	v_mov_b32_e32 v71, v2
	v_mov_b32_e32 v72, v2
	v_mov_b32_e32 v73, v2
	v_mov_b32_e32 v74, v2
	v_mov_b32_e32 v75, v2
	v_mov_b32_e32 v76, v2
	v_mov_b32_e32 v77, v2
	v_mov_b32_e32 v78, v2
	v_mov_b32_e32 v79, v2
	v_mov_b32_e32 v80, v2
	v_mov_b32_e32 v81, v2
	v_mov_b32_e32 v82, v2
	v_mov_b32_e32 v83, v2
	v_mov_b32_e32 v84, v2
	v_mov_b32_e32 v85, v2
	v_mov_b32_e32 v86, v2
	v_mov_b32_e32 v87, v2
	v_mov_b32_e32 v88, v2
	v_mov_b32_e32 v89, v2
	v_mov_b32_e32 v90, v2
	v_mov_b32_e32 v91, v2
	v_mov_b32_e32 v92, v2
	v_mov_b32_e32 v93, v2
	v_mov_b32_e32 v94, v2
	v_mov_b32_e32 v95, v2
	v_mov_b32_e32 v96, v2
	v_mov_b32_e32 v97, v2
	v_mov_b32_e32 v98, v2
	v_mov_b32_e32 v99, v2
	v_mov_b32_e32 v100, v2
	v_mov_b32_e32 v101, v2
	v_mov_b32_e32 v102, v2
	v_mov_b32_e32 v103, v2
	v_mov_b32_e32 v104, v2
	v_mov_b32_e32 v105, v2
	v_mov_b32_e32 v106, v2
	v_mov_b32_e32 v107, v2
	v_mov_b32_e32 v108, v2
	v_mov_b32_e32 v109, v2
	v_mov_b32_e32 v110, v2
	v_mov_b32_e32 v111, v2
	v_mov_b32_e32 v112, v2
	v_mov_b32_e32 v113, v2
	v_mov_b32_e32 v114, v2
	v_mov_b32_e32 v115, v2
	v_mov_b32_e32 v116, v2
	v_mov_b32_e32 v117, v2
	v_mov_b32_e32 v118, v2
	v_mov_b32_e32 v119, v2
	v_mov_b32_e32 v120, v2
	v_mov_b32_e32 v121, v2
	v_mov_b32_e32 v122, v2
	v_mov_b32_e32 v123, v2
	v_mov_b32_e32 v124, v2
	v_mov_b32_e32 v125, v2
	v_mov_b32_e32 v126, v2
	v_mov_b32_e32 v127, v2
	v_mov_b32_e32 v128, v2
	v_mov_b32_e32 v129, v2
	s_mov_b64 s[26:27], 0x263f4880
	s_mov_b64 s[30:31], 0x9a54900
	s_mov_b64 s[34:35], 0x26374900
	s_mov_b64 s[36:37], 0x9ad4900
	s_mov_b64 s[38:39], 0x263f4900
	s_mov_b64 s[40:41], 0x9a54980
	s_mov_b64 s[44:45], 0x26374980
	s_mov_b64 s[48:49], 0x9ad4980
	v_readfirstlane_b32 s100, v130
	v_readfirstlane_b32 s101, v131
	s_sub_u32 s100, s100, 0x40000000
	s_subb_u32 s101, s101, 0
	s_mov_b64 vcc, s[100:101]
	v_lshl_add_u64 v[210:211], v[150:151], 0, v[144:145]
	v_subrev_u32_e32 v210, vcc_lo, v210
	v_lshl_add_u64 v[214:215], v[150:151], 0, v[142:143]
	v_subrev_u32_e32 v214, vcc_lo, v214
	v_lshl_add_u64 v[246:247], v[150:151], 0, v[148:149]
	v_subrev_u32_e32 v246, vcc_lo, v246
	v_lshl_add_u64 v[248:249], v[150:151], 0, v[146:147]
	v_subrev_u32_e32 v248, vcc_lo, v248
	v_add_u32_e32 v211, 0x10000, v154
	v_add_u32_e32 v215, 0x10000, v155
	s_barrier
.LBB0_597:
	ds_read_b128 v[164:167], v211
	ds_read_b128 v[168:171], v215
	ds_read_b128 v[172:175], v211 offset:2048
	ds_read_b128 v[176:179], v215 offset:2048
	s_add_i32 s25, s1, 0xc000
	s_mov_b32 m0, s25
	s_add_i32 s11, s1, 0xe000
	ds_read_b128 v[180:183], v152
	ds_read_b128 v[184:187], v152 offset:2048
	ds_read_b128 v[188:191], v153
	ds_read_b128 v[192:195], v153 offset:2048
	ds_read_b128 v[196:199], v152 offset:4096
	ds_read_b128 v[200:203], v152 offset:6144
	ds_read_b128 v[206:209], v153 offset:4096
	ds_read_b128 v[218:221], v153 offset:6144
	s_add_u32 s100, vcc_lo, s26
	s_addc_u32 s101, vcc_hi, s27
	global_load_lds_dwordx4 v210, s[100:101] nt
	s_mov_b32 m0, s11
	s_add_u32 s100, vcc_lo, s26
	s_addc_u32 s101, vcc_hi, s27
	global_load_lds_dwordx4 v214, s[100:101] nt
	s_waitcnt lgkmcnt(8)
	s_waitcnt vmcnt(10)
	s_barrier
	s_waitcnt lgkmcnt(0)
	s_setprio 1
	s_waitcnt lgkmcnt(0)
	v_mfma_f32_16x16x32_bf16 v[126:129], v[164:167], v[180:183], v[126:129]
	v_mfma_f32_16x16x32_bf16 v[122:125], v[172:175], v[180:183], v[122:125]
	v_mfma_f32_16x16x32_bf16 v[118:121], v[164:167], v[184:187], v[118:121]
	v_mfma_f32_16x16x32_bf16 v[114:117], v[172:175], v[184:187], v[114:117]
	v_mfma_f32_16x16x32_bf16 v[110:113], v[164:167], v[196:199], v[110:113]
	v_mfma_f32_16x16x32_bf16 v[106:109], v[172:175], v[196:199], v[106:109]
	v_mfma_f32_16x16x32_bf16 v[102:105], v[164:167], v[200:203], v[102:105]
	v_mfma_f32_16x16x32_bf16 v[98:101], v[172:175], v[200:203], v[98:101]
	v_mfma_f32_16x16x32_bf16 v[126:129], v[168:171], v[188:191], v[126:129]
	v_mfma_f32_16x16x32_bf16 v[122:125], v[176:179], v[188:191], v[122:125]
	v_mfma_f32_16x16x32_bf16 v[118:121], v[168:171], v[192:195], v[118:121]
	v_mfma_f32_16x16x32_bf16 v[114:117], v[176:179], v[192:195], v[114:117]
	v_mfma_f32_16x16x32_bf16 v[110:113], v[168:171], v[206:209], v[110:113]
	v_mfma_f32_16x16x32_bf16 v[106:109], v[176:179], v[206:209], v[106:109]
	v_mfma_f32_16x16x32_bf16 v[102:105], v[168:171], v[218:221], v[102:105]
	v_mfma_f32_16x16x32_bf16 v[98:101], v[176:179], v[218:221], v[98:101]
	s_setprio 0
	s_barrier
	s_mov_b32 m0, s2
	ds_read_b128 v[222:225], v211 offset:16384
	ds_read_b128 v[226:229], v215 offset:16384
	ds_read_b128 v[230:233], v211 offset:18432
	ds_read_b128 v[234:237], v215 offset:18432
	s_add_u32 s100, vcc_lo, s30
	s_addc_u32 s101, vcc_hi, s31
	global_load_lds_dwordx4 v246, s[100:101]
	s_mov_b32 m0, s3
	s_add_u32 s100, vcc_lo, s30
	s_addc_u32 s101, vcc_hi, s31
	global_load_lds_dwordx4 v248, s[100:101]
	s_waitcnt vmcnt(10)
	s_waitcnt lgkmcnt(0)
	s_barrier
	s_waitcnt lgkmcnt(0)
	s_setprio 1
	s_waitcnt lgkmcnt(0)
	v_mfma_f32_16x16x32_bf16 v[94:97], v[222:225], v[180:183], v[94:97]
	v_mfma_f32_16x16x32_bf16 v[90:93], v[230:233], v[180:183], v[90:93]
	v_mfma_f32_16x16x32_bf16 v[86:89], v[222:225], v[184:187], v[86:89]
	v_mfma_f32_16x16x32_bf16 v[82:85], v[230:233], v[184:187], v[82:85]
	v_mfma_f32_16x16x32_bf16 v[78:81], v[222:225], v[196:199], v[78:81]
	v_mfma_f32_16x16x32_bf16 v[74:77], v[230:233], v[196:199], v[74:77]
	v_mfma_f32_16x16x32_bf16 v[70:73], v[222:225], v[200:203], v[70:73]
	v_mfma_f32_16x16x32_bf16 v[66:69], v[230:233], v[200:203], v[66:69]
	v_mfma_f32_16x16x32_bf16 v[94:97], v[226:229], v[188:191], v[94:97]
	v_mfma_f32_16x16x32_bf16 v[90:93], v[234:237], v[188:191], v[90:93]
	v_mfma_f32_16x16x32_bf16 v[86:89], v[226:229], v[192:195], v[86:89]
	v_mfma_f32_16x16x32_bf16 v[82:85], v[234:237], v[192:195], v[82:85]
	v_mfma_f32_16x16x32_bf16 v[78:81], v[226:229], v[206:209], v[78:81]
	v_mfma_f32_16x16x32_bf16 v[74:77], v[234:237], v[206:209], v[74:77]
	v_mfma_f32_16x16x32_bf16 v[70:73], v[226:229], v[218:221], v[70:73]
	v_mfma_f32_16x16x32_bf16 v[66:69], v[234:237], v[218:221], v[66:69]
	s_setprio 0
	s_mov_b32 m0, s1
	s_barrier
	ds_read_b128 v[180:183], v152 offset:16384
	ds_read_b128 v[184:187], v152 offset:18432
	ds_read_b128 v[188:191], v153 offset:16384
	ds_read_b128 v[192:195], v153 offset:18432
	ds_read_b128 v[196:199], v152 offset:20480
	ds_read_b128 v[200:203], v152 offset:22528
	ds_read_b128 v[206:209], v153 offset:20480
	ds_read_b128 v[218:221], v153 offset:22528
	s_add_u32 s100, vcc_lo, s34
	s_addc_u32 s101, vcc_hi, s35
	global_load_lds_dwordx4 v210, s[100:101] nt
	s_mov_b32 m0, s13
	s_add_u32 s100, vcc_lo, s34
	s_addc_u32 s101, vcc_hi, s35
	global_load_lds_dwordx4 v214, s[100:101] nt
	s_mov_b32 m0, s15
	s_add_u32 s100, vcc_lo, s36
	s_addc_u32 s101, vcc_hi, s37
	global_load_lds_dwordx4 v246, s[100:101]
	s_mov_b32 m0, s16
	s_add_u32 s100, vcc_lo, s36
	s_addc_u32 s101, vcc_hi, s37
	global_load_lds_dwordx4 v248, s[100:101]
	s_waitcnt vmcnt(10)
	s_waitcnt lgkmcnt(0)
	s_barrier
	s_waitcnt lgkmcnt(0)
	s_setprio 1
	s_waitcnt lgkmcnt(0)
	v_mfma_f32_16x16x32_bf16 v[62:65], v[164:167], v[180:183], v[62:65]
	v_mfma_f32_16x16x32_bf16 v[58:61], v[172:175], v[180:183], v[58:61]
	v_mfma_f32_16x16x32_bf16 v[54:57], v[164:167], v[184:187], v[54:57]
	v_mfma_f32_16x16x32_bf16 v[50:53], v[172:175], v[184:187], v[50:53]
	v_mfma_f32_16x16x32_bf16 v[46:49], v[164:167], v[196:199], v[46:49]
	v_mfma_f32_16x16x32_bf16 v[42:45], v[172:175], v[196:199], v[42:45]
	v_mfma_f32_16x16x32_bf16 v[38:41], v[164:167], v[200:203], v[38:41]
	v_mfma_f32_16x16x32_bf16 v[34:37], v[172:175], v[200:203], v[34:37]
	v_mfma_f32_16x16x32_bf16 v[62:65], v[168:171], v[188:191], v[62:65]
	v_mfma_f32_16x16x32_bf16 v[58:61], v[176:179], v[188:191], v[58:61]
	v_mfma_f32_16x16x32_bf16 v[54:57], v[168:171], v[192:195], v[54:57]
	v_mfma_f32_16x16x32_bf16 v[50:53], v[176:179], v[192:195], v[50:53]
	v_mfma_f32_16x16x32_bf16 v[46:49], v[168:171], v[206:209], v[46:49]
	v_mfma_f32_16x16x32_bf16 v[42:45], v[176:179], v[206:209], v[42:45]
	v_mfma_f32_16x16x32_bf16 v[38:41], v[168:171], v[218:221], v[38:41]
	v_mfma_f32_16x16x32_bf16 v[34:37], v[176:179], v[218:221], v[34:37]
	v_mfma_f32_16x16x32_bf16 v[30:33], v[222:225], v[180:183], v[30:33]
	v_mfma_f32_16x16x32_bf16 v[26:29], v[230:233], v[180:183], v[26:29]
	v_mfma_f32_16x16x32_bf16 v[22:25], v[222:225], v[184:187], v[22:25]
	v_mfma_f32_16x16x32_bf16 v[18:21], v[230:233], v[184:187], v[18:21]
	v_mfma_f32_16x16x32_bf16 v[14:17], v[222:225], v[196:199], v[14:17]
	v_mfma_f32_16x16x32_bf16 v[10:13], v[230:233], v[196:199], v[10:13]
	v_mfma_f32_16x16x32_bf16 v[6:9], v[222:225], v[200:203], v[6:9]
	v_mfma_f32_16x16x32_bf16 v[2:5], v[230:233], v[200:203], v[2:5]
	v_mfma_f32_16x16x32_bf16 v[30:33], v[226:229], v[188:191], v[30:33]
	v_mfma_f32_16x16x32_bf16 v[26:29], v[234:237], v[188:191], v[26:29]
	v_mfma_f32_16x16x32_bf16 v[22:25], v[226:229], v[192:195], v[22:25]
	v_mfma_f32_16x16x32_bf16 v[18:21], v[234:237], v[192:195], v[18:21]
	v_mfma_f32_16x16x32_bf16 v[14:17], v[226:229], v[206:209], v[14:17]
	v_mfma_f32_16x16x32_bf16 v[10:13], v[234:237], v[206:209], v[10:13]
	v_mfma_f32_16x16x32_bf16 v[6:9], v[226:229], v[218:221], v[6:9]
	v_mfma_f32_16x16x32_bf16 v[2:5], v[234:237], v[218:221], v[2:5]
	s_setprio 0
	s_barrier
	ds_read_b128 v[172:175], v211 offset:32768
	ds_read_b128 v[176:179], v215 offset:32768
	ds_read_b128 v[180:183], v211 offset:34816
	ds_read_b128 v[184:187], v215 offset:34816
	s_mov_b32 m0, s17
	ds_read_b128 v[188:191], v152 offset:32768
	ds_read_b128 v[192:195], v152 offset:34816
	ds_read_b128 v[196:199], v153 offset:32768
	ds_read_b128 v[200:203], v153 offset:34816
	ds_read_b128 v[206:209], v152 offset:36864
	ds_read_b128 v[218:221], v152 offset:38912
	ds_read_b128 v[222:225], v153 offset:36864
	ds_read_b128 v[226:229], v153 offset:38912
	s_add_u32 s100, vcc_lo, s38
	s_addc_u32 s101, vcc_hi, s39
	global_load_lds_dwordx4 v210, s[100:101] nt
	s_mov_b32 m0, s18
	s_add_u32 s100, vcc_lo, s38
	s_addc_u32 s101, vcc_hi, s39
	global_load_lds_dwordx4 v214, s[100:101] nt
	s_waitcnt lgkmcnt(8)
	s_waitcnt vmcnt(10)
	s_barrier
	s_waitcnt lgkmcnt(0)
	s_setprio 1
	s_waitcnt lgkmcnt(0)
	v_mfma_f32_16x16x32_bf16 v[126:129], v[172:175], v[188:191], v[126:129]
	v_mfma_f32_16x16x32_bf16 v[122:125], v[180:183], v[188:191], v[122:125]
	v_mfma_f32_16x16x32_bf16 v[118:121], v[172:175], v[192:195], v[118:121]
	v_mfma_f32_16x16x32_bf16 v[114:117], v[180:183], v[192:195], v[114:117]
	v_mfma_f32_16x16x32_bf16 v[110:113], v[172:175], v[206:209], v[110:113]
	v_mfma_f32_16x16x32_bf16 v[106:109], v[180:183], v[206:209], v[106:109]
	v_mfma_f32_16x16x32_bf16 v[102:105], v[172:175], v[218:221], v[102:105]
	v_mfma_f32_16x16x32_bf16 v[98:101], v[180:183], v[218:221], v[98:101]
	v_mfma_f32_16x16x32_bf16 v[126:129], v[176:179], v[196:199], v[126:129]
	v_mfma_f32_16x16x32_bf16 v[122:125], v[184:187], v[196:199], v[122:125]
	v_mfma_f32_16x16x32_bf16 v[118:121], v[176:179], v[200:203], v[118:121]
	v_mfma_f32_16x16x32_bf16 v[114:117], v[184:187], v[200:203], v[114:117]
	v_mfma_f32_16x16x32_bf16 v[110:113], v[176:179], v[222:225], v[110:113]
	v_mfma_f32_16x16x32_bf16 v[106:109], v[184:187], v[222:225], v[106:109]
	v_mfma_f32_16x16x32_bf16 v[102:105], v[176:179], v[226:229], v[102:105]
	v_mfma_f32_16x16x32_bf16 v[98:101], v[184:187], v[226:229], v[98:101]
	s_setprio 0
	s_barrier
	s_mov_b32 m0, s19
	ds_read_b128 v[230:233], v211 offset:49152
	ds_read_b128 v[234:237], v215 offset:49152
	ds_read_b128 v[238:241], v211 offset:51200
	ds_read_b128 v[242:245], v215 offset:51200
	s_add_u32 s100, vcc_lo, s40
	s_addc_u32 s101, vcc_hi, s41
	global_load_lds_dwordx4 v246, s[100:101]
	s_mov_b32 m0, s20
	s_add_u32 s100, vcc_lo, s40
	s_addc_u32 s101, vcc_hi, s41
	global_load_lds_dwordx4 v248, s[100:101]
	s_waitcnt vmcnt(10)
	s_waitcnt lgkmcnt(0)
	s_barrier
	s_waitcnt lgkmcnt(0)
	s_setprio 1
	s_waitcnt lgkmcnt(0)
	v_mfma_f32_16x16x32_bf16 v[94:97], v[230:233], v[188:191], v[94:97]
	v_mfma_f32_16x16x32_bf16 v[90:93], v[238:241], v[188:191], v[90:93]
	v_mfma_f32_16x16x32_bf16 v[86:89], v[230:233], v[192:195], v[86:89]
	v_mfma_f32_16x16x32_bf16 v[82:85], v[238:241], v[192:195], v[82:85]
	v_mfma_f32_16x16x32_bf16 v[78:81], v[230:233], v[206:209], v[78:81]
	v_mfma_f32_16x16x32_bf16 v[74:77], v[238:241], v[206:209], v[74:77]
	v_mfma_f32_16x16x32_bf16 v[70:73], v[230:233], v[218:221], v[70:73]
	v_mfma_f32_16x16x32_bf16 v[66:69], v[238:241], v[218:221], v[66:69]
	v_mfma_f32_16x16x32_bf16 v[94:97], v[234:237], v[196:199], v[94:97]
	v_mfma_f32_16x16x32_bf16 v[90:93], v[242:245], v[196:199], v[90:93]
	v_mfma_f32_16x16x32_bf16 v[86:89], v[234:237], v[200:203], v[86:89]
	v_mfma_f32_16x16x32_bf16 v[82:85], v[242:245], v[200:203], v[82:85]
	v_mfma_f32_16x16x32_bf16 v[78:81], v[234:237], v[222:225], v[78:81]
	v_mfma_f32_16x16x32_bf16 v[74:77], v[242:245], v[222:225], v[74:77]
	v_mfma_f32_16x16x32_bf16 v[70:73], v[234:237], v[226:229], v[70:73]
	v_mfma_f32_16x16x32_bf16 v[66:69], v[242:245], v[226:229], v[66:69]
	s_setprio 0
	s_mov_b32 m0, s21
	s_barrier
	ds_read_b128 v[188:191], v152 offset:49152
	ds_read_b128 v[192:195], v152 offset:51200
	ds_read_b128 v[196:199], v153 offset:49152
	ds_read_b128 v[200:203], v153 offset:51200
	ds_read_b128 v[206:209], v152 offset:53248
	ds_read_b128 v[218:221], v152 offset:55296
	ds_read_b128 v[222:225], v153 offset:53248
	ds_read_b128 v[226:229], v153 offset:55296
	s_add_u32 s100, vcc_lo, s44
	s_addc_u32 s101, vcc_hi, s45
	global_load_lds_dwordx4 v210, s[100:101] nt
	s_mov_b32 m0, s22
	s_add_u32 s100, vcc_lo, s44
	s_addc_u32 s101, vcc_hi, s45
	global_load_lds_dwordx4 v214, s[100:101] nt
	s_mov_b32 m0, s23
	s_add_u32 s100, vcc_lo, s48
	s_addc_u32 s101, vcc_hi, s49
	global_load_lds_dwordx4 v246, s[100:101]
	s_mov_b32 m0, s24
	s_add_u32 s100, vcc_lo, s48
	s_addc_u32 s101, vcc_hi, s49
	global_load_lds_dwordx4 v248, s[100:101]
	s_waitcnt vmcnt(10)
	s_waitcnt lgkmcnt(0)
	s_barrier
	s_waitcnt lgkmcnt(0)
	s_setprio 1
	s_waitcnt lgkmcnt(0)
	v_mfma_f32_16x16x32_bf16 v[62:65], v[172:175], v[188:191], v[62:65]
	v_mfma_f32_16x16x32_bf16 v[58:61], v[180:183], v[188:191], v[58:61]
	v_mfma_f32_16x16x32_bf16 v[54:57], v[172:175], v[192:195], v[54:57]
	v_mfma_f32_16x16x32_bf16 v[50:53], v[180:183], v[192:195], v[50:53]
	v_mfma_f32_16x16x32_bf16 v[46:49], v[172:175], v[206:209], v[46:49]
	v_mfma_f32_16x16x32_bf16 v[42:45], v[180:183], v[206:209], v[42:45]
	v_mfma_f32_16x16x32_bf16 v[38:41], v[172:175], v[218:221], v[38:41]
	v_mfma_f32_16x16x32_bf16 v[34:37], v[180:183], v[218:221], v[34:37]
	v_mfma_f32_16x16x32_bf16 v[62:65], v[176:179], v[196:199], v[62:65]
	v_mfma_f32_16x16x32_bf16 v[58:61], v[184:187], v[196:199], v[58:61]
	v_mfma_f32_16x16x32_bf16 v[54:57], v[176:179], v[200:203], v[54:57]
	v_mfma_f32_16x16x32_bf16 v[50:53], v[184:187], v[200:203], v[50:53]
	v_mfma_f32_16x16x32_bf16 v[46:49], v[176:179], v[222:225], v[46:49]
	v_mfma_f32_16x16x32_bf16 v[42:45], v[184:187], v[222:225], v[42:45]
	v_mfma_f32_16x16x32_bf16 v[38:41], v[176:179], v[226:229], v[38:41]
	v_mfma_f32_16x16x32_bf16 v[34:37], v[184:187], v[226:229], v[34:37]
	v_mfma_f32_16x16x32_bf16 v[30:33], v[230:233], v[188:191], v[30:33]
	v_mfma_f32_16x16x32_bf16 v[26:29], v[238:241], v[188:191], v[26:29]
	v_mfma_f32_16x16x32_bf16 v[22:25], v[230:233], v[192:195], v[22:25]
	v_mfma_f32_16x16x32_bf16 v[18:21], v[238:241], v[192:195], v[18:21]
	v_mfma_f32_16x16x32_bf16 v[14:17], v[230:233], v[206:209], v[14:17]
	v_mfma_f32_16x16x32_bf16 v[10:13], v[238:241], v[206:209], v[10:13]
	v_mfma_f32_16x16x32_bf16 v[6:9], v[230:233], v[218:221], v[6:9]
	v_mfma_f32_16x16x32_bf16 v[2:5], v[238:241], v[218:221], v[2:5]
	v_mfma_f32_16x16x32_bf16 v[30:33], v[234:237], v[196:199], v[30:33]
	v_mfma_f32_16x16x32_bf16 v[26:29], v[242:245], v[196:199], v[26:29]
	v_mfma_f32_16x16x32_bf16 v[22:25], v[234:237], v[200:203], v[22:25]
	v_mfma_f32_16x16x32_bf16 v[18:21], v[242:245], v[200:203], v[18:21]
	v_mfma_f32_16x16x32_bf16 v[14:17], v[234:237], v[222:225], v[14:17]
	v_mfma_f32_16x16x32_bf16 v[10:13], v[242:245], v[222:225], v[10:13]
	v_mfma_f32_16x16x32_bf16 v[6:9], v[234:237], v[226:229], v[6:9]
	v_mfma_f32_16x16x32_bf16 v[2:5], v[242:245], v[226:229], v[2:5]
	s_setprio 0
	s_add_u32 vcc_lo, vcc_lo, s54
	s_addc_u32 vcc_hi, vcc_hi, s55
	s_add_i32 s10, s10, 2
	s_cmp_lt_u32 s10, 28
	v_lshl_add_u64 v[150:151], v[150:151], 0, s[54:55]
	s_barrier
	s_cbranch_scc1 .LBB0_597
	s_waitcnt vmcnt(6)
	v_or_b32_e32 v0, 0x10000, v154
	v_add_u32_e32 v157, 0x10800, v154
	v_or_b32_e32 v156, 0x10000, v155
	v_add_u32_e32 v158, 0x10800, v155
	v_or_b32_e32 v159, 0x14000, v154
	v_add_u32_e32 v161, 0x14800, v154
	v_or_b32_e32 v160, 0x14000, v155
	v_add_u32_e32 v162, 0x14800, v155
	v_or_b32_e32 v163, 0x18000, v154
	v_add_u32_e32 v165, 0x18800, v154
	v_or_b32_e32 v164, 0x18000, v155
	v_add_u32_e32 v166, 0x18800, v155
	v_or_b32_e32 v167, 0x1c000, v154
	v_add_u32_e32 v169, 0x1c800, v154
	v_or_b32_e32 v168, 0x1c000, v155
	v_add_u32_e32 v170, 0x1c800, v155
	s_mov_b64 s[2:3], 0xf80
	s_mov_b32 m0, s25
	v_lshl_add_u64 v[140:141], v[140:141], 0, s[2:3]
	ds_read_b128 v[142:145], v0
	ds_read_b128 v[146:149], v156
	ds_read_b128 v[154:157], v157
	ds_read_b128 v[172:175], v158
	ds_read_b128 v[176:179], v152
	ds_read_b128 v[180:183], v152 offset:2048
	ds_read_b128 v[184:187], v153
	ds_read_b128 v[188:191], v153 offset:2048
	ds_read_b128 v[192:195], v152 offset:4096
	ds_read_b128 v[196:199], v152 offset:6144
	ds_read_b128 v[200:203], v153 offset:4096
	ds_read_b128 v[206:209], v153 offset:6144
	global_load_lds_dwordx4 v[140:141], off nt
	v_lshl_add_u64 v[138:139], v[138:139], 0, s[2:3]
	s_mov_b32 m0, s11
	s_nop 0
	global_load_lds_dwordx4 v[138:139], off nt
	s_barrier
	s_waitcnt lgkmcnt(0)
	s_setprio 1
	s_waitcnt lgkmcnt(0)
	v_mfma_f32_16x16x32_bf16 v[126:129], v[142:145], v[176:179], v[126:129]
	v_mfma_f32_16x16x32_bf16 v[122:125], v[154:157], v[176:179], v[122:125]
	v_mfma_f32_16x16x32_bf16 v[118:121], v[142:145], v[180:183], v[118:121]
	v_mfma_f32_16x16x32_bf16 v[114:117], v[154:157], v[180:183], v[114:117]
	v_mfma_f32_16x16x32_bf16 v[102:105], v[142:145], v[196:199], v[102:105]
	v_mfma_f32_16x16x32_bf16 v[98:101], v[154:157], v[196:199], v[98:101]
	v_mfma_f32_16x16x32_bf16 v[126:129], v[146:149], v[184:187], v[126:129]
	v_mfma_f32_16x16x32_bf16 v[122:125], v[172:175], v[184:187], v[122:125]
	v_mfma_f32_16x16x32_bf16 v[118:121], v[146:149], v[188:191], v[118:121]
	v_mfma_f32_16x16x32_bf16 v[114:117], v[172:175], v[188:191], v[114:117]
	v_mfma_f32_16x16x32_bf16 v[110:113], v[142:145], v[192:195], v[110:113]
	v_mfma_f32_16x16x32_bf16 v[106:109], v[154:157], v[192:195], v[106:109]
	v_mfma_f32_16x16x32_bf16 v[102:105], v[146:149], v[206:209], v[102:105]
	v_mfma_f32_16x16x32_bf16 v[98:101], v[172:175], v[206:209], v[98:101]
	v_mfma_f32_16x16x32_bf16 v[138:141], v[146:149], v[200:203], v[110:113]
	v_mfma_f32_16x16x32_bf16 v[218:221], v[172:175], v[200:203], v[106:109]
	s_setprio 0
	s_barrier
	s_nop 1
	ds_read_b128 v[106:109], v159
	ds_read_b128 v[110:113], v160
	ds_read_b128 v[158:161], v161
	ds_read_b128 v[222:225], v162
	s_barrier
	s_waitcnt lgkmcnt(0)
	s_setprio 1
	s_waitcnt lgkmcnt(0)
	v_mfma_f32_16x16x32_bf16 v[86:89], v[106:109], v[180:183], v[86:89]
	v_mfma_f32_16x16x32_bf16 v[82:85], v[158:161], v[180:183], v[82:85]
	v_mfma_f32_16x16x32_bf16 v[70:73], v[106:109], v[196:199], v[70:73]
	v_mfma_f32_16x16x32_bf16 v[66:69], v[158:161], v[196:199], v[66:69]
	v_mfma_f32_16x16x32_bf16 v[94:97], v[106:109], v[176:179], v[94:97]
	v_mfma_f32_16x16x32_bf16 v[90:93], v[158:161], v[176:179], v[90:93]
	v_mfma_f32_16x16x32_bf16 v[86:89], v[110:113], v[188:191], v[86:89]
	v_mfma_f32_16x16x32_bf16 v[82:85], v[222:225], v[188:191], v[82:85]
	v_mfma_f32_16x16x32_bf16 v[78:81], v[106:109], v[192:195], v[78:81]
	v_mfma_f32_16x16x32_bf16 v[74:77], v[158:161], v[192:195], v[74:77]
	v_mfma_f32_16x16x32_bf16 v[70:73], v[110:113], v[206:209], v[70:73]
	v_mfma_f32_16x16x32_bf16 v[66:69], v[222:225], v[206:209], v[66:69]
	v_mfma_f32_16x16x32_bf16 v[226:229], v[110:113], v[184:187], v[94:97]
	v_mfma_f32_16x16x32_bf16 v[176:179], v[222:225], v[184:187], v[90:93]
	v_mfma_f32_16x16x32_bf16 v[180:183], v[110:113], v[200:203], v[78:81]
	v_mfma_f32_16x16x32_bf16 v[184:187], v[222:225], v[200:203], v[74:77]
	s_setprio 0
	s_barrier
	s_nop 0
	ds_read_b128 v[74:77], v152 offset:16384
	ds_read_b128 v[78:81], v152 offset:18432
	ds_read_b128 v[90:93], v153 offset:16384
	ds_read_b128 v[94:97], v153 offset:18432
	ds_read_b128 v[188:191], v152 offset:20480
	ds_read_b128 v[192:195], v152 offset:22528
	ds_read_b128 v[196:199], v153 offset:20480
	ds_read_b128 v[200:203], v153 offset:22528
	s_waitcnt vmcnt(4)
	s_barrier
	s_waitcnt lgkmcnt(0)
	s_setprio 1
	s_waitcnt lgkmcnt(0)
	v_mfma_f32_16x16x32_bf16 v[62:65], v[142:145], v[74:77], v[62:65]
	v_mfma_f32_16x16x32_bf16 v[58:61], v[154:157], v[74:77], v[58:61]
	v_mfma_f32_16x16x32_bf16 v[54:57], v[142:145], v[78:81], v[54:57]
	v_mfma_f32_16x16x32_bf16 v[50:53], v[154:157], v[78:81], v[50:53]
	v_mfma_f32_16x16x32_bf16 v[38:41], v[142:145], v[192:195], v[38:41]
	v_mfma_f32_16x16x32_bf16 v[34:37], v[154:157], v[192:195], v[34:37]
	v_mfma_f32_16x16x32_bf16 v[62:65], v[146:149], v[90:93], v[62:65]
	v_mfma_f32_16x16x32_bf16 v[58:61], v[172:175], v[90:93], v[58:61]
	v_mfma_f32_16x16x32_bf16 v[54:57], v[146:149], v[94:97], v[54:57]
	v_mfma_f32_16x16x32_bf16 v[50:53], v[172:175], v[94:97], v[50:53]
	v_mfma_f32_16x16x32_bf16 v[46:49], v[142:145], v[188:191], v[46:49]
	v_mfma_f32_16x16x32_bf16 v[42:45], v[154:157], v[188:191], v[42:45]
	v_mfma_f32_16x16x32_bf16 v[38:41], v[146:149], v[200:203], v[38:41]
	v_mfma_f32_16x16x32_bf16 v[34:37], v[172:175], v[200:203], v[34:37]
	v_mfma_f32_16x16x32_bf16 v[206:209], v[146:149], v[196:199], v[46:49]
	v_mfma_f32_16x16x32_bf16 v[230:233], v[172:175], v[196:199], v[42:45]
	s_setprio 0
	s_setprio 1
	v_mfma_f32_16x16x32_bf16 v[22:25], v[106:109], v[78:81], v[22:25]
	v_mfma_f32_16x16x32_bf16 v[18:21], v[158:161], v[78:81], v[18:21]
	v_mfma_f32_16x16x32_bf16 v[6:9], v[106:109], v[192:195], v[6:9]
	v_mfma_f32_16x16x32_bf16 v[2:5], v[158:161], v[192:195], v[2:5]
	v_mfma_f32_16x16x32_bf16 v[30:33], v[106:109], v[74:77], v[30:33]
	v_mfma_f32_16x16x32_bf16 v[26:29], v[158:161], v[74:77], v[26:29]
	v_mfma_f32_16x16x32_bf16 v[22:25], v[110:113], v[94:97], v[22:25]
	v_mfma_f32_16x16x32_bf16 v[18:21], v[222:225], v[94:97], v[18:21]
	v_mfma_f32_16x16x32_bf16 v[14:17], v[106:109], v[188:191], v[14:17]
	v_mfma_f32_16x16x32_bf16 v[10:13], v[158:161], v[188:191], v[10:13]
	v_mfma_f32_16x16x32_bf16 v[6:9], v[110:113], v[200:203], v[6:9]
	v_mfma_f32_16x16x32_bf16 v[2:5], v[222:225], v[200:203], v[2:5]
	v_mfma_f32_16x16x32_bf16 v[142:145], v[110:113], v[90:93], v[30:33]
	v_mfma_f32_16x16x32_bf16 v[146:149], v[222:225], v[90:93], v[26:29]
	v_mfma_f32_16x16x32_bf16 v[154:157], v[110:113], v[196:199], v[14:17]
	v_mfma_f32_16x16x32_bf16 v[172:175], v[222:225], v[196:199], v[10:13]
	s_setprio 0
	s_barrier
	s_nop 0
	ds_read_b128 v[10:13], v163
	ds_read_b128 v[14:17], v164
	ds_read_b128 v[158:161], v165
	ds_read_b128 v[162:165], v166
	ds_read_b128 v[26:29], v152 offset:32768
	ds_read_b128 v[30:33], v152 offset:34816
	ds_read_b128 v[42:45], v153 offset:32768
	ds_read_b128 v[46:49], v153 offset:34816
	ds_read_b128 v[188:191], v152 offset:36864
	ds_read_b128 v[192:195], v152 offset:38912
	ds_read_b128 v[196:199], v153 offset:36864
	ds_read_b128 v[200:203], v153 offset:38912
	s_waitcnt vmcnt(2)
	s_barrier
	s_waitcnt lgkmcnt(0)
	s_setprio 1
	s_waitcnt lgkmcnt(0)
	v_mfma_f32_16x16x32_bf16 v[74:77], v[10:13], v[26:29], v[126:129]
	v_mfma_f32_16x16x32_bf16 v[126:129], v[14:17], v[42:45], v[74:77]
	v_mfma_f32_16x16x32_bf16 v[74:77], v[158:161], v[26:29], v[122:125]
	v_mfma_f32_16x16x32_bf16 v[122:125], v[162:165], v[42:45], v[74:77]
	v_mfma_f32_16x16x32_bf16 v[74:77], v[10:13], v[30:33], v[118:121]
	v_mfma_f32_16x16x32_bf16 v[110:113], v[14:17], v[46:49], v[74:77]
	v_mfma_f32_16x16x32_bf16 v[74:77], v[158:161], v[30:33], v[114:117]
	v_mfma_f32_16x16x32_bf16 v[106:109], v[162:165], v[46:49], v[74:77]
	v_mfma_f32_16x16x32_bf16 v[74:77], v[10:13], v[188:191], v[138:141]
	v_mfma_f32_16x16x32_bf16 v[94:97], v[14:17], v[196:199], v[74:77]
	v_mfma_f32_16x16x32_bf16 v[74:77], v[158:161], v[188:191], v[218:221]
	v_mfma_f32_16x16x32_bf16 v[90:93], v[162:165], v[196:199], v[74:77]
	v_mfma_f32_16x16x32_bf16 v[74:77], v[10:13], v[192:195], v[102:105]
	v_mfma_f32_16x16x32_bf16 v[78:81], v[14:17], v[200:203], v[74:77]
	v_mfma_f32_16x16x32_bf16 v[74:77], v[158:161], v[192:195], v[98:101]
	v_mfma_f32_16x16x32_bf16 v[74:77], v[162:165], v[200:203], v[74:77]
	s_setprio 0
	s_barrier
	ds_read_b128 v[138:141], v167
	ds_read_b128 v[218:221], v168
	ds_read_b128 v[166:169], v169
	ds_read_b128 v[222:225], v170
	s_waitcnt vmcnt(0)
	s_barrier
	s_waitcnt lgkmcnt(0)
	s_setprio 1
	s_waitcnt lgkmcnt(0)
	v_mfma_f32_16x16x32_bf16 v[98:101], v[138:141], v[26:29], v[226:229]
	v_mfma_f32_16x16x32_bf16 v[26:29], v[166:169], v[26:29], v[176:179]
	v_mfma_f32_16x16x32_bf16 v[114:117], v[222:225], v[42:45], v[26:29]
	v_mfma_f32_16x16x32_bf16 v[26:29], v[138:141], v[30:33], v[86:89]
	v_mfma_f32_16x16x32_bf16 v[102:105], v[218:221], v[46:49], v[26:29]
	v_mfma_f32_16x16x32_bf16 v[26:29], v[166:169], v[30:33], v[82:85]
	v_mfma_f32_16x16x32_bf16 v[118:121], v[218:221], v[42:45], v[98:101]
	v_mfma_f32_16x16x32_bf16 v[98:101], v[222:225], v[46:49], v[26:29]
	v_mfma_f32_16x16x32_bf16 v[26:29], v[138:141], v[188:191], v[180:183]
	v_mfma_f32_16x16x32_bf16 v[86:89], v[218:221], v[196:199], v[26:29]
	v_mfma_f32_16x16x32_bf16 v[26:29], v[166:169], v[188:191], v[184:187]
	v_mfma_f32_16x16x32_bf16 v[82:85], v[222:225], v[196:199], v[26:29]
	v_mfma_f32_16x16x32_bf16 v[26:29], v[138:141], v[192:195], v[70:73]
	v_mfma_f32_16x16x32_bf16 v[70:73], v[218:221], v[200:203], v[26:29]
	v_mfma_f32_16x16x32_bf16 v[26:29], v[166:169], v[192:195], v[66:69]
	v_mfma_f32_16x16x32_bf16 v[66:69], v[222:225], v[200:203], v[26:29]
	s_setprio 0
	s_barrier
	ds_read_b128 v[176:179], v152 offset:49152
	ds_read_b128 v[180:183], v152 offset:51200
	ds_read_b128 v[184:187], v153 offset:49152
	ds_read_b128 v[188:191], v153 offset:51200
	ds_read_b128 v[192:195], v152 offset:53248
	ds_read_b128 v[196:199], v152 offset:55296
	ds_read_b128 v[200:203], v153 offset:53248
	ds_read_b128 v[150:153], v153 offset:55296
	s_barrier
	s_waitcnt lgkmcnt(0)
	s_setprio 1
	s_waitcnt lgkmcnt(0)
	v_mfma_f32_16x16x32_bf16 v[26:29], v[10:13], v[176:179], v[62:65]
	v_mfma_f32_16x16x32_bf16 v[62:65], v[14:17], v[184:187], v[26:29]
	v_mfma_f32_16x16x32_bf16 v[26:29], v[158:161], v[176:179], v[58:61]
	v_mfma_f32_16x16x32_bf16 v[58:61], v[162:165], v[184:187], v[26:29]
	v_mfma_f32_16x16x32_bf16 v[26:29], v[10:13], v[180:183], v[54:57]
	v_mfma_f32_16x16x32_bf16 v[46:49], v[14:17], v[188:191], v[26:29]
	v_mfma_f32_16x16x32_bf16 v[26:29], v[158:161], v[180:183], v[50:53]
	v_mfma_f32_16x16x32_bf16 v[42:45], v[162:165], v[188:191], v[26:29]
	v_mfma_f32_16x16x32_bf16 v[26:29], v[10:13], v[192:195], v[206:209]
	v_mfma_f32_16x16x32_bf16 v[10:13], v[10:13], v[196:199], v[38:41]
	v_mfma_f32_16x16x32_bf16 v[30:33], v[14:17], v[200:203], v[26:29]
	v_mfma_f32_16x16x32_bf16 v[26:29], v[158:161], v[192:195], v[230:233]
	v_mfma_f32_16x16x32_bf16 v[14:17], v[14:17], v[150:153], v[10:13]
	v_mfma_f32_16x16x32_bf16 v[10:13], v[158:161], v[196:199], v[34:37]
	v_mfma_f32_16x16x32_bf16 v[26:29], v[162:165], v[200:203], v[26:29]
	v_mfma_f32_16x16x32_bf16 v[10:13], v[162:165], v[150:153], v[10:13]
	s_setprio 0
	s_setprio 1
	v_mfma_f32_16x16x32_bf16 v[34:37], v[138:141], v[176:179], v[142:145]
	v_mfma_f32_16x16x32_bf16 v[54:57], v[218:221], v[184:187], v[34:37]
	v_mfma_f32_16x16x32_bf16 v[34:37], v[166:169], v[176:179], v[146:149]
	v_mfma_f32_16x16x32_bf16 v[18:21], v[166:169], v[180:183], v[18:21]
	v_mfma_f32_16x16x32_bf16 v[50:53], v[222:225], v[184:187], v[34:37]
	v_mfma_f32_16x16x32_bf16 v[22:25], v[138:141], v[180:183], v[22:25]
	v_mfma_f32_16x16x32_bf16 v[34:37], v[222:225], v[188:191], v[18:21]
	v_mfma_f32_16x16x32_bf16 v[18:21], v[138:141], v[192:195], v[154:157]
	v_mfma_f32_16x16x32_bf16 v[38:41], v[218:221], v[188:191], v[22:25]
	v_mfma_f32_16x16x32_bf16 v[22:25], v[218:221], v[200:203], v[18:21]
	v_mfma_f32_16x16x32_bf16 v[18:21], v[166:169], v[192:195], v[172:175]
	v_mfma_f32_16x16x32_bf16 v[6:9], v[138:141], v[196:199], v[6:9]
	v_mfma_f32_16x16x32_bf16 v[2:5], v[166:169], v[196:199], v[2:5]
	v_mfma_f32_16x16x32_bf16 v[18:21], v[222:225], v[200:203], v[18:21]
	v_mfma_f32_16x16x32_bf16 v[6:9], v[218:221], v[150:153], v[6:9]
	v_mfma_f32_16x16x32_bf16 v[2:5], v[222:225], v[150:153], v[2:5]
	s_setprio 0
	s_cmpk_gt_u32 s0, 0xff
	s_barrier
	s_cbranch_scc1 .LBB0_600
	s_barrier
